# in-proj: 256x128 pair tiles (two M tiles share the B tile; BK=64, A ring of 3 LDS buffers + B double buffer, half-step barriers, counted vmcnt), 5 pair rounds + 1 single round; bf16 MFMA fp32 acc unch
# speedup vs baseline: 1.2950x; 1.0497x over previous
.LBB0_193:
.LBB0_194:
	v_readlane_b32 s0, v254, 8
	v_readlane_b32 s1, v254, 9
	s_andn2_b64 vcc, exec, s[0:1]
	s_cbranch_vccnz .LBB0_292
	v_mov_b32_e32 v0, v151
	s_mul_i32 s11, s80, 0x700000
	v_readlane_b32 s0, v253, 30
	s_mul_hi_i32 s10, s80, 0x700000
	s_add_u32 s12, s0, s11
	v_readlane_b32 s0, v253, 31
	s_addc_u32 s13, s0, s10
	v_readlane_b32 s0, v254, 7
	s_movk_i32 s100, 0x100
	s_branch .Lip_j0
.LBB0_196:
	s_bfe_u32 s0, s100, 0x20008
	s_cmp_eq_u32 s0, 1
	s_cbranch_scc0 .Lip_next
	s_add_i32 s42, s42, 7
	s_and_b32 s100, s100, 0xff
	s_or_b32 s100, s100, 0x200
	s_branch .LBB0_197
.Lip_next:
	s_and_b32 s100, s100, 0xff
	s_add_i32 s100, s100, 1
	v_readlane_b32 s1, v254, 7
	s_cmp_lt_u32 s100, 5
	s_cbranch_scc0 .Lip_last
	s_lshl_b32 s0, s100, 6
	s_add_i32 s0, s0, s1
	s_or_b32 s100, s100, 0x100
	s_branch .Lip_j0
.Lip_last:
	s_cmp_eq_u32 s100, 5
	s_cbranch_scc0 .LBB0_292
	s_cmp_lt_u32 s1, 32
	s_cbranch_scc0 .LBB0_292
	s_lshr_b32 s0, s1, 1
	s_addk_i32 s0, 0x140
.Lip_j0:
	s_mul_hi_u32 s4, s0, 0x924924a
	s_mul_i32 s5, s4, 28
	s_sub_u32 s5, s0, s5
	s_mul_hi_u32 s6, s5, 0x24924925
	s_mul_i32 s7, s6, 7
	s_sub_u32 s7, s5, s7
	s_mul_i32 s4, s4, 56
	s_mul_i32 s6, s6, 14
	s_add_i32 s42, s4, s6
	s_add_i32 s42, s42, s7
	s_cmp_eq_u32 s100, 5
	s_cbranch_scc0 .LBB0_197
	s_and_b32 s1, s1, 1
	s_mul_i32 s1, s1, 7
	s_add_i32 s42, s42, s1

.LBB0_203:
	s_lshl_b32 s0, s4, 7
	s_cmpk_lt_i32 s5, 0x700
	s_cselect_b64 s[44:45], -1, 0
	s_ashr_i32 s1, s0, 31
	s_lshl_b64 s[46:47], s[0:1], 11
	s_add_u32 s28, s94, s46
	s_addc_u32 s29, s95, s47
	s_ashr_i32 s41, s40, 31
	s_lshl_b64 s[38:39], s[40:41], 18
	s_add_u32 s48, s12, s38
	s_addc_u32 s49, s13, s39
	s_and_b32 s4, s4, -2
	s_add_i32 s4, s4, s80
	s_ashr_i32 s5, s4, 31
	s_and_b32 s6, s0, 0x80
	s_lshl_b64 s[14:15], s[4:5], 8
	s_andn2_b64 vcc, exec, s[86:87]
	s_or_b32 s14, s14, s6
	s_cbranch_vccz .LBB0_255
	s_bfe_u32 s4, s100, 0x20008
	s_cmp_eq_u32 s4, 0
	s_cbranch_scc1 .Lpk_sw_orig
	s_cmp_eq_u32 s4, 2
	s_cbranch_scc1 .Lpk_sw_unpark
	v_lshrrev_b32_e32 v0, 6, v151
	v_and_b32_e32 v218, 63, v151
	s_nop 0
	v_readfirstlane_b32 s5, v0
	v_lshrrev_b32_e32 v219, 4, v218
	v_and_b32_e32 v220, 7, v218
	v_xor_b32_e32 v220, v220, v219
	v_lshlrev_b32_e32 v220, 4, v220
	v_lshrrev_b32_e32 v219, 3, v218
	v_lshl_or_b32 v98, v219, 11, v220
	s_lshl_b32 s4, s5, 16
	v_add_u32_e32 v98, s4, v98
	v_xor_b32_e32 v99, 64, v98
	v_add_u32_e32 v99, 0x4000, v99
	v_add_u32_e32 v100, 0x8000, v98
	v_add_u32_e32 v101, 0x8000, v99
	v_and_b32_e32 v219, 15, v218
	v_lshrrev_b32_e32 v220, 4, v218
	v_bfe_u32 v218, v219, 1, 3
	v_xor_b32_e32 v220, v220, v218
	v_lshlrev_b32_e32 v220, 4, v220
	v_lshl_or_b32 v220, v219, 7, v220
	s_lshr_b32 s4, s5, 1
	s_lshl_b32 s4, s4, 13
	v_add_u32_e32 v102, s4, v220
	v_xor_b32_e32 v103, 64, v102
	s_and_b32 s4, s5, 1
	s_lshl_b32 s4, s4, 13
	v_add_u32_e32 v104, s4, v220
	v_xor_b32_e32 v105, 64, v104
	v_add_u32_e32 v250, 0x4000, v104
	v_add_u32_e32 v251, 0x4000, v105
	s_lshl_b32 s4, s5, 12
	s_add_u32 s6, s28, 0x40000
	s_addc_u32 s7, s29, 0
	v_mov_b32_e32 v0, 0x13ff0
	ds_read_b64 v[218:219], v0
	s_waitcnt lgkmcnt(0)
	v_readfirstlane_b32 s5, v218
	v_readfirstlane_b32 s101, v219
	s_barrier
	s_add_u32 m0, s4, 0x0
	s_nop 0
	global_load_lds_dwordx4 v98, s[28:29]
	s_add_u32 m0, s4, 0x400
	s_nop 0
	global_load_lds_dwordx4 v99, s[28:29]
	s_add_u32 m0, s4, 0x800
	s_nop 0
	global_load_lds_dwordx4 v100, s[28:29]
	s_add_u32 m0, s4, 0xc00
	s_nop 0
	global_load_lds_dwordx4 v101, s[28:29]
	s_add_u32 m0, s4, 0xc000
	s_nop 0
	global_load_lds_dwordx4 v98, s[48:49]
	s_add_u32 m0, s4, 0xc400
	s_nop 0
	global_load_lds_dwordx4 v99, s[48:49]
	s_add_u32 m0, s4, 0xc800
	s_nop 0
	global_load_lds_dwordx4 v100, s[48:49]
	s_add_u32 m0, s4, 0xcc00
	s_nop 0
	global_load_lds_dwordx4 v101, s[48:49]
	s_add_u32 m0, s4, 0x4000
	s_nop 0
	global_load_lds_dwordx4 v98, s[6:7]
	s_add_u32 m0, s4, 0x4400
	s_nop 0
	global_load_lds_dwordx4 v99, s[6:7]
	s_add_u32 m0, s4, 0x4800
	s_nop 0
	global_load_lds_dwordx4 v100, s[6:7]
	s_add_u32 m0, s4, 0x4c00
	s_nop 0
	global_load_lds_dwordx4 v101, s[6:7]
	v_add_u32_e32 v98, 0x80, v98
	v_add_u32_e32 v99, 0x80, v99
	v_add_u32_e32 v100, 0x80, v100
	v_add_u32_e32 v101, 0x80, v101
	v_mov_b32_e32 v62, 0
	v_mov_b32_e32 v106, 0
	v_mov_b32_e32 v63, 0
	v_mov_b32_e32 v107, 0
	v_mov_b32_e32 v64, 0
	v_mov_b32_e32 v108, 0
	v_mov_b32_e32 v65, 0
	v_mov_b32_e32 v109, 0
	v_mov_b32_e32 v58, 0
	v_mov_b32_e32 v110, 0
	v_mov_b32_e32 v59, 0
	v_mov_b32_e32 v111, 0
	v_mov_b32_e32 v60, 0
	v_mov_b32_e32 v112, 0
	v_mov_b32_e32 v61, 0
	v_mov_b32_e32 v113, 0
	v_mov_b32_e32 v54, 0
	v_mov_b32_e32 v114, 0
	v_mov_b32_e32 v55, 0
	v_mov_b32_e32 v115, 0
	v_mov_b32_e32 v56, 0
	v_mov_b32_e32 v116, 0
	v_mov_b32_e32 v57, 0
	v_mov_b32_e32 v117, 0
	v_mov_b32_e32 v50, 0
	v_mov_b32_e32 v118, 0
	v_mov_b32_e32 v51, 0
	v_mov_b32_e32 v119, 0
	v_mov_b32_e32 v52, 0
	v_mov_b32_e32 v120, 0
	v_mov_b32_e32 v53, 0
	v_mov_b32_e32 v121, 0
	v_mov_b32_e32 v46, 0
	v_mov_b32_e32 v122, 0
	v_mov_b32_e32 v47, 0
	v_mov_b32_e32 v123, 0
	v_mov_b32_e32 v48, 0
	v_mov_b32_e32 v124, 0
	v_mov_b32_e32 v49, 0
	v_mov_b32_e32 v125, 0
	v_mov_b32_e32 v42, 0
	v_mov_b32_e32 v126, 0
	v_mov_b32_e32 v43, 0
	v_mov_b32_e32 v127, 0
	v_mov_b32_e32 v44, 0
	v_mov_b32_e32 v128, 0
	v_mov_b32_e32 v45, 0
	v_mov_b32_e32 v129, 0
	v_mov_b32_e32 v38, 0
	v_mov_b32_e32 v130, 0
	v_mov_b32_e32 v39, 0
	v_mov_b32_e32 v131, 0
	v_mov_b32_e32 v40, 0
	v_mov_b32_e32 v132, 0
	v_mov_b32_e32 v41, 0
	v_mov_b32_e32 v133, 0
	v_mov_b32_e32 v34, 0
	v_mov_b32_e32 v134, 0
	v_mov_b32_e32 v35, 0
	v_mov_b32_e32 v135, 0
	v_mov_b32_e32 v36, 0
	v_mov_b32_e32 v136, 0
	v_mov_b32_e32 v37, 0
	v_mov_b32_e32 v137, 0
	v_mov_b32_e32 v30, 0
	v_mov_b32_e32 v138, 0
	v_mov_b32_e32 v31, 0
	v_mov_b32_e32 v139, 0
	v_mov_b32_e32 v32, 0
	v_mov_b32_e32 v140, 0
	v_mov_b32_e32 v33, 0
	v_mov_b32_e32 v141, 0
	v_mov_b32_e32 v26, 0
	v_mov_b32_e32 v142, 0
	v_mov_b32_e32 v27, 0
	v_mov_b32_e32 v143, 0
	v_mov_b32_e32 v28, 0
	v_mov_b32_e32 v144, 0
	v_mov_b32_e32 v29, 0
	v_mov_b32_e32 v145, 0
	v_mov_b32_e32 v22, 0
	v_mov_b32_e32 v154, 0
	v_mov_b32_e32 v23, 0
	v_mov_b32_e32 v155, 0
	v_mov_b32_e32 v24, 0
	v_mov_b32_e32 v156, 0
	v_mov_b32_e32 v25, 0
	v_mov_b32_e32 v157, 0
	v_mov_b32_e32 v18, 0
	v_mov_b32_e32 v158, 0
	v_mov_b32_e32 v19, 0
	v_mov_b32_e32 v159, 0
	v_mov_b32_e32 v20, 0
	v_mov_b32_e32 v160, 0
	v_mov_b32_e32 v21, 0
	v_mov_b32_e32 v161, 0
	v_mov_b32_e32 v14, 0
	v_mov_b32_e32 v162, 0
	v_mov_b32_e32 v15, 0
	v_mov_b32_e32 v163, 0
	v_mov_b32_e32 v16, 0
	v_mov_b32_e32 v164, 0
	v_mov_b32_e32 v17, 0
	v_mov_b32_e32 v165, 0
	v_mov_b32_e32 v10, 0
	v_mov_b32_e32 v166, 0
	v_mov_b32_e32 v11, 0
	v_mov_b32_e32 v167, 0
	v_mov_b32_e32 v12, 0
	v_mov_b32_e32 v168, 0
	v_mov_b32_e32 v13, 0
	v_mov_b32_e32 v169, 0
	v_mov_b32_e32 v6, 0
	v_mov_b32_e32 v170, 0
	v_mov_b32_e32 v7, 0
	v_mov_b32_e32 v171, 0
	v_mov_b32_e32 v8, 0
	v_mov_b32_e32 v172, 0
	v_mov_b32_e32 v9, 0
	v_mov_b32_e32 v173, 0
	v_mov_b32_e32 v2, 0
	v_mov_b32_e32 v174, 0
	v_mov_b32_e32 v3, 0
	v_mov_b32_e32 v175, 0
	v_mov_b32_e32 v4, 0
	v_mov_b32_e32 v176, 0
	v_mov_b32_e32 v5, 0
	v_mov_b32_e32 v177, 0
	s_waitcnt vmcnt(4)
	s_barrier
	ds_read_b128 v[218:221], v102 offset:0
	ds_read_b128 v[222:225], v102 offset:2048
	ds_read_b128 v[226:229], v102 offset:4096
	ds_read_b128 v[230:233], v102 offset:6144
	ds_read_b128 v[66:69], v104 offset:49152
	ds_read_b128 v[70:73], v104 offset:51200
	ds_read_b128 v[74:77], v104 offset:53248
	ds_read_b128 v[78:81], v104 offset:55296
	ds_read_b128 v[234:237], v103 offset:0
	ds_read_b128 v[238:241], v103 offset:2048
	ds_read_b128 v[242:245], v103 offset:4096
	ds_read_b128 v[246:249], v103 offset:6144
	ds_read_b128 v[82:85], v105 offset:49152
	ds_read_b128 v[86:89], v105 offset:51200
	ds_read_b128 v[90:93], v105 offset:53248
	ds_read_b128 v[94:97], v105 offset:55296
	s_add_u32 m0, s4, 0x8000
	s_nop 0
	global_load_lds_dwordx4 v98, s[28:29]
	s_add_u32 m0, s4, 0x8400
	s_nop 0
	global_load_lds_dwordx4 v99, s[28:29]
	s_add_u32 m0, s4, 0x8800
	s_nop 0
	global_load_lds_dwordx4 v100, s[28:29]
	s_add_u32 m0, s4, 0x8c00
	s_nop 0
	global_load_lds_dwordx4 v101, s[28:29]
	s_add_u32 m0, s4, 0x10000
	s_nop 0
	global_load_lds_dwordx4 v98, s[48:49]
	s_add_u32 m0, s4, 0x10400
	s_nop 0
	global_load_lds_dwordx4 v99, s[48:49]
	s_add_u32 m0, s4, 0x10800
	s_nop 0
	global_load_lds_dwordx4 v100, s[48:49]
	s_add_u32 m0, s4, 0x10c00
	s_nop 0
	global_load_lds_dwordx4 v101, s[48:49]
	s_waitcnt lgkmcnt(8)
	v_mfma_f32_16x16x32_bf16 v[62:65], v[66:69], v[218:221], v[62:65]
	v_mfma_f32_16x16x32_bf16 v[46:49], v[66:69], v[222:225], v[46:49]
	v_mfma_f32_16x16x32_bf16 v[30:33], v[66:69], v[226:229], v[30:33]
	v_mfma_f32_16x16x32_bf16 v[14:17], v[66:69], v[230:233], v[14:17]
	v_mfma_f32_16x16x32_bf16 v[58:61], v[70:73], v[218:221], v[58:61]
	v_mfma_f32_16x16x32_bf16 v[42:45], v[70:73], v[222:225], v[42:45]
	v_mfma_f32_16x16x32_bf16 v[26:29], v[70:73], v[226:229], v[26:29]
	v_mfma_f32_16x16x32_bf16 v[10:13], v[70:73], v[230:233], v[10:13]
	v_mfma_f32_16x16x32_bf16 v[54:57], v[74:77], v[218:221], v[54:57]
	v_mfma_f32_16x16x32_bf16 v[38:41], v[74:77], v[222:225], v[38:41]
	v_mfma_f32_16x16x32_bf16 v[22:25], v[74:77], v[226:229], v[22:25]
	v_mfma_f32_16x16x32_bf16 v[6:9], v[74:77], v[230:233], v[6:9]
	v_mfma_f32_16x16x32_bf16 v[50:53], v[78:81], v[218:221], v[50:53]
	v_mfma_f32_16x16x32_bf16 v[34:37], v[78:81], v[222:225], v[34:37]
	v_mfma_f32_16x16x32_bf16 v[18:21], v[78:81], v[226:229], v[18:21]
	v_mfma_f32_16x16x32_bf16 v[2:5], v[78:81], v[230:233], v[2:5]
	s_waitcnt lgkmcnt(0)
	v_mfma_f32_16x16x32_bf16 v[62:65], v[82:85], v[234:237], v[62:65]
	v_mfma_f32_16x16x32_bf16 v[46:49], v[82:85], v[238:241], v[46:49]
	v_mfma_f32_16x16x32_bf16 v[30:33], v[82:85], v[242:245], v[30:33]
	v_mfma_f32_16x16x32_bf16 v[14:17], v[82:85], v[246:249], v[14:17]
	v_mfma_f32_16x16x32_bf16 v[58:61], v[86:89], v[234:237], v[58:61]
	v_mfma_f32_16x16x32_bf16 v[42:45], v[86:89], v[238:241], v[42:45]
	v_mfma_f32_16x16x32_bf16 v[26:29], v[86:89], v[242:245], v[26:29]
	v_mfma_f32_16x16x32_bf16 v[10:13], v[86:89], v[246:249], v[10:13]
	v_mfma_f32_16x16x32_bf16 v[54:57], v[90:93], v[234:237], v[54:57]
	v_mfma_f32_16x16x32_bf16 v[38:41], v[90:93], v[238:241], v[38:41]
	v_mfma_f32_16x16x32_bf16 v[22:25], v[90:93], v[242:245], v[22:25]
	v_mfma_f32_16x16x32_bf16 v[6:9], v[90:93], v[246:249], v[6:9]
	v_mfma_f32_16x16x32_bf16 v[50:53], v[94:97], v[234:237], v[50:53]
	v_mfma_f32_16x16x32_bf16 v[34:37], v[94:97], v[238:241], v[34:37]
	v_mfma_f32_16x16x32_bf16 v[18:21], v[94:97], v[242:245], v[18:21]
	v_mfma_f32_16x16x32_bf16 v[2:5], v[94:97], v[246:249], v[2:5]
	s_waitcnt vmcnt(8)
	s_barrier
	ds_read_b128 v[218:221], v102 offset:16384
	ds_read_b128 v[222:225], v102 offset:18432
	ds_read_b128 v[226:229], v102 offset:20480
	ds_read_b128 v[230:233], v102 offset:22528
	ds_read_b128 v[234:237], v103 offset:16384
	ds_read_b128 v[238:241], v103 offset:18432
	ds_read_b128 v[242:245], v103 offset:20480
	ds_read_b128 v[246:249], v103 offset:22528
	s_add_u32 m0, s4, 0x0
	s_nop 0
	global_load_lds_dwordx4 v98, s[6:7]
	s_add_u32 m0, s4, 0x400
	s_nop 0
	global_load_lds_dwordx4 v99, s[6:7]
	s_add_u32 m0, s4, 0x800
	s_nop 0
	global_load_lds_dwordx4 v100, s[6:7]
	s_add_u32 m0, s4, 0xc00
	s_nop 0
	global_load_lds_dwordx4 v101, s[6:7]
	v_add_u32_e32 v98, 0x80, v98
	v_add_u32_e32 v99, 0x80, v99
	v_add_u32_e32 v100, 0x80, v100
	v_add_u32_e32 v101, 0x80, v101
	s_waitcnt lgkmcnt(4)
	v_mfma_f32_16x16x32_bf16 v[106:109], v[66:69], v[218:221], v[106:109]
	v_mfma_f32_16x16x32_bf16 v[122:125], v[66:69], v[222:225], v[122:125]
	v_mfma_f32_16x16x32_bf16 v[138:141], v[66:69], v[226:229], v[138:141]
	v_mfma_f32_16x16x32_bf16 v[162:165], v[66:69], v[230:233], v[162:165]
	v_mfma_f32_16x16x32_bf16 v[110:113], v[70:73], v[218:221], v[110:113]
	v_mfma_f32_16x16x32_bf16 v[126:129], v[70:73], v[222:225], v[126:129]
	v_mfma_f32_16x16x32_bf16 v[142:145], v[70:73], v[226:229], v[142:145]
	v_mfma_f32_16x16x32_bf16 v[166:169], v[70:73], v[230:233], v[166:169]
	v_mfma_f32_16x16x32_bf16 v[114:117], v[74:77], v[218:221], v[114:117]
	v_mfma_f32_16x16x32_bf16 v[130:133], v[74:77], v[222:225], v[130:133]
	v_mfma_f32_16x16x32_bf16 v[154:157], v[74:77], v[226:229], v[154:157]
	v_mfma_f32_16x16x32_bf16 v[170:173], v[74:77], v[230:233], v[170:173]
	v_mfma_f32_16x16x32_bf16 v[118:121], v[78:81], v[218:221], v[118:121]
	v_mfma_f32_16x16x32_bf16 v[134:137], v[78:81], v[222:225], v[134:137]
	v_mfma_f32_16x16x32_bf16 v[158:161], v[78:81], v[226:229], v[158:161]
	v_mfma_f32_16x16x32_bf16 v[174:177], v[78:81], v[230:233], v[174:177]
	s_waitcnt lgkmcnt(0)
	v_mfma_f32_16x16x32_bf16 v[106:109], v[82:85], v[234:237], v[106:109]
	v_mfma_f32_16x16x32_bf16 v[122:125], v[82:85], v[238:241], v[122:125]
	v_mfma_f32_16x16x32_bf16 v[138:141], v[82:85], v[242:245], v[138:141]
	v_mfma_f32_16x16x32_bf16 v[162:165], v[82:85], v[246:249], v[162:165]
	v_mfma_f32_16x16x32_bf16 v[110:113], v[86:89], v[234:237], v[110:113]
	v_mfma_f32_16x16x32_bf16 v[126:129], v[86:89], v[238:241], v[126:129]
	v_mfma_f32_16x16x32_bf16 v[142:145], v[86:89], v[242:245], v[142:145]
	v_mfma_f32_16x16x32_bf16 v[166:169], v[86:89], v[246:249], v[166:169]
	v_mfma_f32_16x16x32_bf16 v[114:117], v[90:93], v[234:237], v[114:117]
	v_mfma_f32_16x16x32_bf16 v[130:133], v[90:93], v[238:241], v[130:133]
	v_mfma_f32_16x16x32_bf16 v[154:157], v[90:93], v[242:245], v[154:157]
	v_mfma_f32_16x16x32_bf16 v[170:173], v[90:93], v[246:249], v[170:173]
	v_mfma_f32_16x16x32_bf16 v[118:121], v[94:97], v[234:237], v[118:121]
	v_mfma_f32_16x16x32_bf16 v[134:137], v[94:97], v[238:241], v[134:137]
	v_mfma_f32_16x16x32_bf16 v[158:161], v[94:97], v[242:245], v[158:161]
	v_mfma_f32_16x16x32_bf16 v[174:177], v[94:97], v[246:249], v[174:177]
	s_waitcnt vmcnt(4)
	s_barrier
	ds_read_b128 v[218:221], v102 offset:32768
	ds_read_b128 v[222:225], v102 offset:34816
	ds_read_b128 v[226:229], v102 offset:36864
	ds_read_b128 v[230:233], v102 offset:38912
	ds_read_b128 v[66:69], v250 offset:49152
	ds_read_b128 v[70:73], v250 offset:51200
	ds_read_b128 v[74:77], v250 offset:53248
	ds_read_b128 v[78:81], v250 offset:55296
	ds_read_b128 v[234:237], v103 offset:32768
	ds_read_b128 v[238:241], v103 offset:34816
	ds_read_b128 v[242:245], v103 offset:36864
	ds_read_b128 v[246:249], v103 offset:38912
	ds_read_b128 v[82:85], v251 offset:49152
	ds_read_b128 v[86:89], v251 offset:51200
	ds_read_b128 v[90:93], v251 offset:53248
	ds_read_b128 v[94:97], v251 offset:55296
	s_add_u32 m0, s4, 0x4000
	s_nop 0
	global_load_lds_dwordx4 v98, s[28:29]
	s_add_u32 m0, s4, 0x4400
	s_nop 0
	global_load_lds_dwordx4 v99, s[28:29]
	s_add_u32 m0, s4, 0x4800
	s_nop 0
	global_load_lds_dwordx4 v100, s[28:29]
	s_add_u32 m0, s4, 0x4c00
	s_nop 0
	global_load_lds_dwordx4 v101, s[28:29]
	s_add_u32 m0, s4, 0xc000
	s_nop 0
	global_load_lds_dwordx4 v98, s[48:49]
	s_add_u32 m0, s4, 0xc400
	s_nop 0
	global_load_lds_dwordx4 v99, s[48:49]
	s_add_u32 m0, s4, 0xc800
	s_nop 0
	global_load_lds_dwordx4 v100, s[48:49]
	s_add_u32 m0, s4, 0xcc00
	s_nop 0
	global_load_lds_dwordx4 v101, s[48:49]
	s_waitcnt lgkmcnt(8)
	v_mfma_f32_16x16x32_bf16 v[62:65], v[66:69], v[218:221], v[62:65]
	v_mfma_f32_16x16x32_bf16 v[46:49], v[66:69], v[222:225], v[46:49]
	v_mfma_f32_16x16x32_bf16 v[30:33], v[66:69], v[226:229], v[30:33]
	v_mfma_f32_16x16x32_bf16 v[14:17], v[66:69], v[230:233], v[14:17]
	v_mfma_f32_16x16x32_bf16 v[58:61], v[70:73], v[218:221], v[58:61]
	v_mfma_f32_16x16x32_bf16 v[42:45], v[70:73], v[222:225], v[42:45]
	v_mfma_f32_16x16x32_bf16 v[26:29], v[70:73], v[226:229], v[26:29]
	v_mfma_f32_16x16x32_bf16 v[10:13], v[70:73], v[230:233], v[10:13]
	v_mfma_f32_16x16x32_bf16 v[54:57], v[74:77], v[218:221], v[54:57]
	v_mfma_f32_16x16x32_bf16 v[38:41], v[74:77], v[222:225], v[38:41]
	v_mfma_f32_16x16x32_bf16 v[22:25], v[74:77], v[226:229], v[22:25]
	v_mfma_f32_16x16x32_bf16 v[6:9], v[74:77], v[230:233], v[6:9]
	v_mfma_f32_16x16x32_bf16 v[50:53], v[78:81], v[218:221], v[50:53]
	v_mfma_f32_16x16x32_bf16 v[34:37], v[78:81], v[222:225], v[34:37]
	v_mfma_f32_16x16x32_bf16 v[18:21], v[78:81], v[226:229], v[18:21]
	v_mfma_f32_16x16x32_bf16 v[2:5], v[78:81], v[230:233], v[2:5]
	s_waitcnt lgkmcnt(0)
	v_mfma_f32_16x16x32_bf16 v[62:65], v[82:85], v[234:237], v[62:65]
	v_mfma_f32_16x16x32_bf16 v[46:49], v[82:85], v[238:241], v[46:49]
	v_mfma_f32_16x16x32_bf16 v[30:33], v[82:85], v[242:245], v[30:33]
	v_mfma_f32_16x16x32_bf16 v[14:17], v[82:85], v[246:249], v[14:17]
	v_mfma_f32_16x16x32_bf16 v[58:61], v[86:89], v[234:237], v[58:61]
	v_mfma_f32_16x16x32_bf16 v[42:45], v[86:89], v[238:241], v[42:45]
	v_mfma_f32_16x16x32_bf16 v[26:29], v[86:89], v[242:245], v[26:29]
	v_mfma_f32_16x16x32_bf16 v[10:13], v[86:89], v[246:249], v[10:13]
	v_mfma_f32_16x16x32_bf16 v[54:57], v[90:93], v[234:237], v[54:57]
	v_mfma_f32_16x16x32_bf16 v[38:41], v[90:93], v[238:241], v[38:41]
	v_mfma_f32_16x16x32_bf16 v[22:25], v[90:93], v[242:245], v[22:25]
	v_mfma_f32_16x16x32_bf16 v[6:9], v[90:93], v[246:249], v[6:9]
	v_mfma_f32_16x16x32_bf16 v[50:53], v[94:97], v[234:237], v[50:53]
	v_mfma_f32_16x16x32_bf16 v[34:37], v[94:97], v[238:241], v[34:37]
	v_mfma_f32_16x16x32_bf16 v[18:21], v[94:97], v[242:245], v[18:21]
	v_mfma_f32_16x16x32_bf16 v[2:5], v[94:97], v[246:249], v[2:5]
	s_waitcnt vmcnt(8)
	s_barrier
	ds_read_b128 v[218:221], v102 offset:0
	ds_read_b128 v[222:225], v102 offset:2048
	ds_read_b128 v[226:229], v102 offset:4096
	ds_read_b128 v[230:233], v102 offset:6144
	ds_read_b128 v[234:237], v103 offset:0
	ds_read_b128 v[238:241], v103 offset:2048
	ds_read_b128 v[242:245], v103 offset:4096
	ds_read_b128 v[246:249], v103 offset:6144
	s_add_u32 m0, s4, 0x8000
	s_nop 0
	global_load_lds_dwordx4 v98, s[6:7]
	s_add_u32 m0, s4, 0x8400
	s_nop 0
	global_load_lds_dwordx4 v99, s[6:7]
	s_add_u32 m0, s4, 0x8800
	s_nop 0
	global_load_lds_dwordx4 v100, s[6:7]
	s_add_u32 m0, s4, 0x8c00
	s_nop 0
	global_load_lds_dwordx4 v101, s[6:7]
	v_add_u32_e32 v98, 0x80, v98
	v_add_u32_e32 v99, 0x80, v99
	v_add_u32_e32 v100, 0x80, v100
	v_add_u32_e32 v101, 0x80, v101
	s_waitcnt lgkmcnt(4)
	v_mfma_f32_16x16x32_bf16 v[106:109], v[66:69], v[218:221], v[106:109]
	v_mfma_f32_16x16x32_bf16 v[122:125], v[66:69], v[222:225], v[122:125]
	v_mfma_f32_16x16x32_bf16 v[138:141], v[66:69], v[226:229], v[138:141]
	v_mfma_f32_16x16x32_bf16 v[162:165], v[66:69], v[230:233], v[162:165]
	v_mfma_f32_16x16x32_bf16 v[110:113], v[70:73], v[218:221], v[110:113]
	v_mfma_f32_16x16x32_bf16 v[126:129], v[70:73], v[222:225], v[126:129]
	v_mfma_f32_16x16x32_bf16 v[142:145], v[70:73], v[226:229], v[142:145]
	v_mfma_f32_16x16x32_bf16 v[166:169], v[70:73], v[230:233], v[166:169]
	v_mfma_f32_16x16x32_bf16 v[114:117], v[74:77], v[218:221], v[114:117]
	v_mfma_f32_16x16x32_bf16 v[130:133], v[74:77], v[222:225], v[130:133]
	v_mfma_f32_16x16x32_bf16 v[154:157], v[74:77], v[226:229], v[154:157]
	v_mfma_f32_16x16x32_bf16 v[170:173], v[74:77], v[230:233], v[170:173]
	v_mfma_f32_16x16x32_bf16 v[118:121], v[78:81], v[218:221], v[118:121]
	v_mfma_f32_16x16x32_bf16 v[134:137], v[78:81], v[222:225], v[134:137]
	v_mfma_f32_16x16x32_bf16 v[158:161], v[78:81], v[226:229], v[158:161]
	v_mfma_f32_16x16x32_bf16 v[174:177], v[78:81], v[230:233], v[174:177]
	s_waitcnt lgkmcnt(0)
	v_mfma_f32_16x16x32_bf16 v[106:109], v[82:85], v[234:237], v[106:109]
	v_mfma_f32_16x16x32_bf16 v[122:125], v[82:85], v[238:241], v[122:125]
	v_mfma_f32_16x16x32_bf16 v[138:141], v[82:85], v[242:245], v[138:141]
	v_mfma_f32_16x16x32_bf16 v[162:165], v[82:85], v[246:249], v[162:165]
	v_mfma_f32_16x16x32_bf16 v[110:113], v[86:89], v[234:237], v[110:113]
	v_mfma_f32_16x16x32_bf16 v[126:129], v[86:89], v[238:241], v[126:129]
	v_mfma_f32_16x16x32_bf16 v[142:145], v[86:89], v[242:245], v[142:145]
	v_mfma_f32_16x16x32_bf16 v[166:169], v[86:89], v[246:249], v[166:169]
	v_mfma_f32_16x16x32_bf16 v[114:117], v[90:93], v[234:237], v[114:117]
	v_mfma_f32_16x16x32_bf16 v[130:133], v[90:93], v[238:241], v[130:133]
	v_mfma_f32_16x16x32_bf16 v[154:157], v[90:93], v[242:245], v[154:157]
	v_mfma_f32_16x16x32_bf16 v[170:173], v[90:93], v[246:249], v[170:173]
	v_mfma_f32_16x16x32_bf16 v[118:121], v[94:97], v[234:237], v[118:121]
	v_mfma_f32_16x16x32_bf16 v[134:137], v[94:97], v[238:241], v[134:137]
	v_mfma_f32_16x16x32_bf16 v[158:161], v[94:97], v[242:245], v[158:161]
	v_mfma_f32_16x16x32_bf16 v[174:177], v[94:97], v[246:249], v[174:177]
	s_waitcnt vmcnt(4)
	s_barrier
	ds_read_b128 v[218:221], v102 offset:16384
	ds_read_b128 v[222:225], v102 offset:18432
	ds_read_b128 v[226:229], v102 offset:20480
	ds_read_b128 v[230:233], v102 offset:22528
	ds_read_b128 v[66:69], v104 offset:49152
	ds_read_b128 v[70:73], v104 offset:51200
	ds_read_b128 v[74:77], v104 offset:53248
	ds_read_b128 v[78:81], v104 offset:55296
	ds_read_b128 v[234:237], v103 offset:16384
	ds_read_b128 v[238:241], v103 offset:18432
	ds_read_b128 v[242:245], v103 offset:20480
	ds_read_b128 v[246:249], v103 offset:22528
	ds_read_b128 v[82:85], v105 offset:49152
	ds_read_b128 v[86:89], v105 offset:51200
	ds_read_b128 v[90:93], v105 offset:53248
	ds_read_b128 v[94:97], v105 offset:55296
	s_add_u32 m0, s4, 0x0
	s_nop 0
	global_load_lds_dwordx4 v98, s[28:29]
	s_add_u32 m0, s4, 0x400
	s_nop 0
	global_load_lds_dwordx4 v99, s[28:29]
	s_add_u32 m0, s4, 0x800
	s_nop 0
	global_load_lds_dwordx4 v100, s[28:29]
	s_add_u32 m0, s4, 0xc00
	s_nop 0
	global_load_lds_dwordx4 v101, s[28:29]
	s_add_u32 m0, s4, 0x10000
	s_nop 0
	global_load_lds_dwordx4 v98, s[48:49]
	s_add_u32 m0, s4, 0x10400
	s_nop 0
	global_load_lds_dwordx4 v99, s[48:49]
	s_add_u32 m0, s4, 0x10800
	s_nop 0
	global_load_lds_dwordx4 v100, s[48:49]
	s_add_u32 m0, s4, 0x10c00
	s_nop 0
	global_load_lds_dwordx4 v101, s[48:49]
	s_waitcnt lgkmcnt(8)
	v_mfma_f32_16x16x32_bf16 v[62:65], v[66:69], v[218:221], v[62:65]
	v_mfma_f32_16x16x32_bf16 v[46:49], v[66:69], v[222:225], v[46:49]
	v_mfma_f32_16x16x32_bf16 v[30:33], v[66:69], v[226:229], v[30:33]
	v_mfma_f32_16x16x32_bf16 v[14:17], v[66:69], v[230:233], v[14:17]
	v_mfma_f32_16x16x32_bf16 v[58:61], v[70:73], v[218:221], v[58:61]
	v_mfma_f32_16x16x32_bf16 v[42:45], v[70:73], v[222:225], v[42:45]
	v_mfma_f32_16x16x32_bf16 v[26:29], v[70:73], v[226:229], v[26:29]
	v_mfma_f32_16x16x32_bf16 v[10:13], v[70:73], v[230:233], v[10:13]
	v_mfma_f32_16x16x32_bf16 v[54:57], v[74:77], v[218:221], v[54:57]
	v_mfma_f32_16x16x32_bf16 v[38:41], v[74:77], v[222:225], v[38:41]
	v_mfma_f32_16x16x32_bf16 v[22:25], v[74:77], v[226:229], v[22:25]
	v_mfma_f32_16x16x32_bf16 v[6:9], v[74:77], v[230:233], v[6:9]
	v_mfma_f32_16x16x32_bf16 v[50:53], v[78:81], v[218:221], v[50:53]
	v_mfma_f32_16x16x32_bf16 v[34:37], v[78:81], v[222:225], v[34:37]
	v_mfma_f32_16x16x32_bf16 v[18:21], v[78:81], v[226:229], v[18:21]
	v_mfma_f32_16x16x32_bf16 v[2:5], v[78:81], v[230:233], v[2:5]
	s_waitcnt lgkmcnt(0)
	v_mfma_f32_16x16x32_bf16 v[62:65], v[82:85], v[234:237], v[62:65]
	v_mfma_f32_16x16x32_bf16 v[46:49], v[82:85], v[238:241], v[46:49]
	v_mfma_f32_16x16x32_bf16 v[30:33], v[82:85], v[242:245], v[30:33]
	v_mfma_f32_16x16x32_bf16 v[14:17], v[82:85], v[246:249], v[14:17]
	v_mfma_f32_16x16x32_bf16 v[58:61], v[86:89], v[234:237], v[58:61]
	v_mfma_f32_16x16x32_bf16 v[42:45], v[86:89], v[238:241], v[42:45]
	v_mfma_f32_16x16x32_bf16 v[26:29], v[86:89], v[242:245], v[26:29]
	v_mfma_f32_16x16x32_bf16 v[10:13], v[86:89], v[246:249], v[10:13]
	v_mfma_f32_16x16x32_bf16 v[54:57], v[90:93], v[234:237], v[54:57]
	v_mfma_f32_16x16x32_bf16 v[38:41], v[90:93], v[238:241], v[38:41]
	v_mfma_f32_16x16x32_bf16 v[22:25], v[90:93], v[242:245], v[22:25]
	v_mfma_f32_16x16x32_bf16 v[6:9], v[90:93], v[246:249], v[6:9]
	v_mfma_f32_16x16x32_bf16 v[50:53], v[94:97], v[234:237], v[50:53]
	v_mfma_f32_16x16x32_bf16 v[34:37], v[94:97], v[238:241], v[34:37]
	v_mfma_f32_16x16x32_bf16 v[18:21], v[94:97], v[242:245], v[18:21]
	v_mfma_f32_16x16x32_bf16 v[2:5], v[94:97], v[246:249], v[2:5]
	s_waitcnt vmcnt(8)
	s_barrier
	ds_read_b128 v[218:221], v102 offset:32768
	ds_read_b128 v[222:225], v102 offset:34816
	ds_read_b128 v[226:229], v102 offset:36864
	ds_read_b128 v[230:233], v102 offset:38912
	ds_read_b128 v[234:237], v103 offset:32768
	ds_read_b128 v[238:241], v103 offset:34816
	ds_read_b128 v[242:245], v103 offset:36864
	ds_read_b128 v[246:249], v103 offset:38912
	s_add_u32 m0, s4, 0x4000
	s_nop 0
	global_load_lds_dwordx4 v98, s[6:7]
	s_add_u32 m0, s4, 0x4400
	s_nop 0
	global_load_lds_dwordx4 v99, s[6:7]
	s_add_u32 m0, s4, 0x4800
	s_nop 0
	global_load_lds_dwordx4 v100, s[6:7]
	s_add_u32 m0, s4, 0x4c00
	s_nop 0
	global_load_lds_dwordx4 v101, s[6:7]
	v_add_u32_e32 v98, 0x80, v98
	v_add_u32_e32 v99, 0x80, v99
	v_add_u32_e32 v100, 0x80, v100
	v_add_u32_e32 v101, 0x80, v101
	s_waitcnt lgkmcnt(4)
	v_mfma_f32_16x16x32_bf16 v[106:109], v[66:69], v[218:221], v[106:109]
	v_mfma_f32_16x16x32_bf16 v[122:125], v[66:69], v[222:225], v[122:125]
	v_mfma_f32_16x16x32_bf16 v[138:141], v[66:69], v[226:229], v[138:141]
	v_mfma_f32_16x16x32_bf16 v[162:165], v[66:69], v[230:233], v[162:165]
	v_mfma_f32_16x16x32_bf16 v[110:113], v[70:73], v[218:221], v[110:113]
	v_mfma_f32_16x16x32_bf16 v[126:129], v[70:73], v[222:225], v[126:129]
	v_mfma_f32_16x16x32_bf16 v[142:145], v[70:73], v[226:229], v[142:145]
	v_mfma_f32_16x16x32_bf16 v[166:169], v[70:73], v[230:233], v[166:169]
	v_mfma_f32_16x16x32_bf16 v[114:117], v[74:77], v[218:221], v[114:117]
	v_mfma_f32_16x16x32_bf16 v[130:133], v[74:77], v[222:225], v[130:133]
	v_mfma_f32_16x16x32_bf16 v[154:157], v[74:77], v[226:229], v[154:157]
	v_mfma_f32_16x16x32_bf16 v[170:173], v[74:77], v[230:233], v[170:173]
	v_mfma_f32_16x16x32_bf16 v[118:121], v[78:81], v[218:221], v[118:121]
	v_mfma_f32_16x16x32_bf16 v[134:137], v[78:81], v[222:225], v[134:137]
	v_mfma_f32_16x16x32_bf16 v[158:161], v[78:81], v[226:229], v[158:161]
	v_mfma_f32_16x16x32_bf16 v[174:177], v[78:81], v[230:233], v[174:177]
	s_waitcnt lgkmcnt(0)
	v_mfma_f32_16x16x32_bf16 v[106:109], v[82:85], v[234:237], v[106:109]
	v_mfma_f32_16x16x32_bf16 v[122:125], v[82:85], v[238:241], v[122:125]
	v_mfma_f32_16x16x32_bf16 v[138:141], v[82:85], v[242:245], v[138:141]
	v_mfma_f32_16x16x32_bf16 v[162:165], v[82:85], v[246:249], v[162:165]
	v_mfma_f32_16x16x32_bf16 v[110:113], v[86:89], v[234:237], v[110:113]
	v_mfma_f32_16x16x32_bf16 v[126:129], v[86:89], v[238:241], v[126:129]
	v_mfma_f32_16x16x32_bf16 v[142:145], v[86:89], v[242:245], v[142:145]
	v_mfma_f32_16x16x32_bf16 v[166:169], v[86:89], v[246:249], v[166:169]
	v_mfma_f32_16x16x32_bf16 v[114:117], v[90:93], v[234:237], v[114:117]
	v_mfma_f32_16x16x32_bf16 v[130:133], v[90:93], v[238:241], v[130:133]
	v_mfma_f32_16x16x32_bf16 v[154:157], v[90:93], v[242:245], v[154:157]
	v_mfma_f32_16x16x32_bf16 v[170:173], v[90:93], v[246:249], v[170:173]
	v_mfma_f32_16x16x32_bf16 v[118:121], v[94:97], v[234:237], v[118:121]
	v_mfma_f32_16x16x32_bf16 v[134:137], v[94:97], v[238:241], v[134:137]
	v_mfma_f32_16x16x32_bf16 v[158:161], v[94:97], v[242:245], v[158:161]
	v_mfma_f32_16x16x32_bf16 v[174:177], v[94:97], v[246:249], v[174:177]
	s_waitcnt vmcnt(4)
	s_barrier
	ds_read_b128 v[218:221], v102 offset:0
	ds_read_b128 v[222:225], v102 offset:2048
	ds_read_b128 v[226:229], v102 offset:4096
	ds_read_b128 v[230:233], v102 offset:6144
	ds_read_b128 v[66:69], v250 offset:49152
	ds_read_b128 v[70:73], v250 offset:51200
	ds_read_b128 v[74:77], v250 offset:53248
	ds_read_b128 v[78:81], v250 offset:55296
	ds_read_b128 v[234:237], v103 offset:0
	ds_read_b128 v[238:241], v103 offset:2048
	ds_read_b128 v[242:245], v103 offset:4096
	ds_read_b128 v[246:249], v103 offset:6144
	ds_read_b128 v[82:85], v251 offset:49152
	ds_read_b128 v[86:89], v251 offset:51200
	ds_read_b128 v[90:93], v251 offset:53248
	ds_read_b128 v[94:97], v251 offset:55296
	s_add_u32 m0, s4, 0x8000
	s_nop 0
	global_load_lds_dwordx4 v98, s[28:29]
	s_add_u32 m0, s4, 0x8400
	s_nop 0
	global_load_lds_dwordx4 v99, s[28:29]
	s_add_u32 m0, s4, 0x8800
	s_nop 0
	global_load_lds_dwordx4 v100, s[28:29]
	s_add_u32 m0, s4, 0x8c00
	s_nop 0
	global_load_lds_dwordx4 v101, s[28:29]
	s_add_u32 m0, s4, 0xc000
	s_nop 0
	global_load_lds_dwordx4 v98, s[48:49]
	s_add_u32 m0, s4, 0xc400
	s_nop 0
	global_load_lds_dwordx4 v99, s[48:49]
	s_add_u32 m0, s4, 0xc800
	s_nop 0
	global_load_lds_dwordx4 v100, s[48:49]
	s_add_u32 m0, s4, 0xcc00
	s_nop 0
	global_load_lds_dwordx4 v101, s[48:49]
	s_waitcnt lgkmcnt(8)
	v_mfma_f32_16x16x32_bf16 v[62:65], v[66:69], v[218:221], v[62:65]
	v_mfma_f32_16x16x32_bf16 v[46:49], v[66:69], v[222:225], v[46:49]
	v_mfma_f32_16x16x32_bf16 v[30:33], v[66:69], v[226:229], v[30:33]
	v_mfma_f32_16x16x32_bf16 v[14:17], v[66:69], v[230:233], v[14:17]
	v_mfma_f32_16x16x32_bf16 v[58:61], v[70:73], v[218:221], v[58:61]
	v_mfma_f32_16x16x32_bf16 v[42:45], v[70:73], v[222:225], v[42:45]
	v_mfma_f32_16x16x32_bf16 v[26:29], v[70:73], v[226:229], v[26:29]
	v_mfma_f32_16x16x32_bf16 v[10:13], v[70:73], v[230:233], v[10:13]
	v_mfma_f32_16x16x32_bf16 v[54:57], v[74:77], v[218:221], v[54:57]
	v_mfma_f32_16x16x32_bf16 v[38:41], v[74:77], v[222:225], v[38:41]
	v_mfma_f32_16x16x32_bf16 v[22:25], v[74:77], v[226:229], v[22:25]
	v_mfma_f32_16x16x32_bf16 v[6:9], v[74:77], v[230:233], v[6:9]
	v_mfma_f32_16x16x32_bf16 v[50:53], v[78:81], v[218:221], v[50:53]
	v_mfma_f32_16x16x32_bf16 v[34:37], v[78:81], v[222:225], v[34:37]
	v_mfma_f32_16x16x32_bf16 v[18:21], v[78:81], v[226:229], v[18:21]
	v_mfma_f32_16x16x32_bf16 v[2:5], v[78:81], v[230:233], v[2:5]
	s_waitcnt lgkmcnt(0)
	v_mfma_f32_16x16x32_bf16 v[62:65], v[82:85], v[234:237], v[62:65]
	v_mfma_f32_16x16x32_bf16 v[46:49], v[82:85], v[238:241], v[46:49]
	v_mfma_f32_16x16x32_bf16 v[30:33], v[82:85], v[242:245], v[30:33]
	v_mfma_f32_16x16x32_bf16 v[14:17], v[82:85], v[246:249], v[14:17]
	v_mfma_f32_16x16x32_bf16 v[58:61], v[86:89], v[234:237], v[58:61]
	v_mfma_f32_16x16x32_bf16 v[42:45], v[86:89], v[238:241], v[42:45]
	v_mfma_f32_16x16x32_bf16 v[26:29], v[86:89], v[242:245], v[26:29]
	v_mfma_f32_16x16x32_bf16 v[10:13], v[86:89], v[246:249], v[10:13]
	v_mfma_f32_16x16x32_bf16 v[54:57], v[90:93], v[234:237], v[54:57]
	v_mfma_f32_16x16x32_bf16 v[38:41], v[90:93], v[238:241], v[38:41]
	v_mfma_f32_16x16x32_bf16 v[22:25], v[90:93], v[242:245], v[22:25]
	v_mfma_f32_16x16x32_bf16 v[6:9], v[90:93], v[246:249], v[6:9]
	v_mfma_f32_16x16x32_bf16 v[50:53], v[94:97], v[234:237], v[50:53]
	v_mfma_f32_16x16x32_bf16 v[34:37], v[94:97], v[238:241], v[34:37]
	v_mfma_f32_16x16x32_bf16 v[18:21], v[94:97], v[242:245], v[18:21]
	v_mfma_f32_16x16x32_bf16 v[2:5], v[94:97], v[246:249], v[2:5]
	s_waitcnt vmcnt(8)
	s_barrier
	ds_read_b128 v[218:221], v102 offset:16384
	ds_read_b128 v[222:225], v102 offset:18432
	ds_read_b128 v[226:229], v102 offset:20480
	ds_read_b128 v[230:233], v102 offset:22528
	ds_read_b128 v[234:237], v103 offset:16384
	ds_read_b128 v[238:241], v103 offset:18432
	ds_read_b128 v[242:245], v103 offset:20480
	ds_read_b128 v[246:249], v103 offset:22528
	s_add_u32 m0, s4, 0x0
	s_nop 0
	global_load_lds_dwordx4 v98, s[6:7]
	s_add_u32 m0, s4, 0x400
	s_nop 0
	global_load_lds_dwordx4 v99, s[6:7]
	s_add_u32 m0, s4, 0x800
	s_nop 0
	global_load_lds_dwordx4 v100, s[6:7]
	s_add_u32 m0, s4, 0xc00
	s_nop 0
	global_load_lds_dwordx4 v101, s[6:7]
	v_add_u32_e32 v98, 0x80, v98
	v_add_u32_e32 v99, 0x80, v99
	v_add_u32_e32 v100, 0x80, v100
	v_add_u32_e32 v101, 0x80, v101
	s_waitcnt lgkmcnt(4)
	v_mfma_f32_16x16x32_bf16 v[106:109], v[66:69], v[218:221], v[106:109]
	v_mfma_f32_16x16x32_bf16 v[122:125], v[66:69], v[222:225], v[122:125]
	v_mfma_f32_16x16x32_bf16 v[138:141], v[66:69], v[226:229], v[138:141]
	v_mfma_f32_16x16x32_bf16 v[162:165], v[66:69], v[230:233], v[162:165]
	v_mfma_f32_16x16x32_bf16 v[110:113], v[70:73], v[218:221], v[110:113]
	v_mfma_f32_16x16x32_bf16 v[126:129], v[70:73], v[222:225], v[126:129]
	v_mfma_f32_16x16x32_bf16 v[142:145], v[70:73], v[226:229], v[142:145]
	v_mfma_f32_16x16x32_bf16 v[166:169], v[70:73], v[230:233], v[166:169]
	v_mfma_f32_16x16x32_bf16 v[114:117], v[74:77], v[218:221], v[114:117]
	v_mfma_f32_16x16x32_bf16 v[130:133], v[74:77], v[222:225], v[130:133]
	v_mfma_f32_16x16x32_bf16 v[154:157], v[74:77], v[226:229], v[154:157]
	v_mfma_f32_16x16x32_bf16 v[170:173], v[74:77], v[230:233], v[170:173]
	v_mfma_f32_16x16x32_bf16 v[118:121], v[78:81], v[218:221], v[118:121]
	v_mfma_f32_16x16x32_bf16 v[134:137], v[78:81], v[222:225], v[134:137]
	v_mfma_f32_16x16x32_bf16 v[158:161], v[78:81], v[226:229], v[158:161]
	v_mfma_f32_16x16x32_bf16 v[174:177], v[78:81], v[230:233], v[174:177]
	s_waitcnt lgkmcnt(0)
	v_mfma_f32_16x16x32_bf16 v[106:109], v[82:85], v[234:237], v[106:109]
	v_mfma_f32_16x16x32_bf16 v[122:125], v[82:85], v[238:241], v[122:125]
	v_mfma_f32_16x16x32_bf16 v[138:141], v[82:85], v[242:245], v[138:141]
	v_mfma_f32_16x16x32_bf16 v[162:165], v[82:85], v[246:249], v[162:165]
	v_mfma_f32_16x16x32_bf16 v[110:113], v[86:89], v[234:237], v[110:113]
	v_mfma_f32_16x16x32_bf16 v[126:129], v[86:89], v[238:241], v[126:129]
	v_mfma_f32_16x16x32_bf16 v[142:145], v[86:89], v[242:245], v[142:145]
	v_mfma_f32_16x16x32_bf16 v[166:169], v[86:89], v[246:249], v[166:169]
	v_mfma_f32_16x16x32_bf16 v[114:117], v[90:93], v[234:237], v[114:117]
	v_mfma_f32_16x16x32_bf16 v[130:133], v[90:93], v[238:241], v[130:133]
	v_mfma_f32_16x16x32_bf16 v[154:157], v[90:93], v[242:245], v[154:157]
	v_mfma_f32_16x16x32_bf16 v[170:173], v[90:93], v[246:249], v[170:173]
	v_mfma_f32_16x16x32_bf16 v[118:121], v[94:97], v[234:237], v[118:121]
	v_mfma_f32_16x16x32_bf16 v[134:137], v[94:97], v[238:241], v[134:137]
	v_mfma_f32_16x16x32_bf16 v[158:161], v[94:97], v[242:245], v[158:161]
	v_mfma_f32_16x16x32_bf16 v[174:177], v[94:97], v[246:249], v[174:177]
	s_waitcnt vmcnt(4)
	s_barrier
	ds_read_b128 v[218:221], v102 offset:32768
	ds_read_b128 v[222:225], v102 offset:34816
	ds_read_b128 v[226:229], v102 offset:36864
	ds_read_b128 v[230:233], v102 offset:38912
	ds_read_b128 v[66:69], v104 offset:49152
	ds_read_b128 v[70:73], v104 offset:51200
	ds_read_b128 v[74:77], v104 offset:53248
	ds_read_b128 v[78:81], v104 offset:55296
	ds_read_b128 v[234:237], v103 offset:32768
	ds_read_b128 v[238:241], v103 offset:34816
	ds_read_b128 v[242:245], v103 offset:36864
	ds_read_b128 v[246:249], v103 offset:38912
	ds_read_b128 v[82:85], v105 offset:49152
	ds_read_b128 v[86:89], v105 offset:51200
	ds_read_b128 v[90:93], v105 offset:53248
	ds_read_b128 v[94:97], v105 offset:55296
	s_add_u32 m0, s4, 0x4000
	s_nop 0
	global_load_lds_dwordx4 v98, s[28:29]
	s_add_u32 m0, s4, 0x4400
	s_nop 0
	global_load_lds_dwordx4 v99, s[28:29]
	s_add_u32 m0, s4, 0x4800
	s_nop 0
	global_load_lds_dwordx4 v100, s[28:29]
	s_add_u32 m0, s4, 0x4c00
	s_nop 0
	global_load_lds_dwordx4 v101, s[28:29]
	s_add_u32 m0, s4, 0x10000
	s_nop 0
	global_load_lds_dwordx4 v98, s[48:49]
	s_add_u32 m0, s4, 0x10400
	s_nop 0
	global_load_lds_dwordx4 v99, s[48:49]
	s_add_u32 m0, s4, 0x10800
	s_nop 0
	global_load_lds_dwordx4 v100, s[48:49]
	s_add_u32 m0, s4, 0x10c00
	s_nop 0
	global_load_lds_dwordx4 v101, s[48:49]
	s_waitcnt lgkmcnt(8)
	v_mfma_f32_16x16x32_bf16 v[62:65], v[66:69], v[218:221], v[62:65]
	v_mfma_f32_16x16x32_bf16 v[46:49], v[66:69], v[222:225], v[46:49]
	v_mfma_f32_16x16x32_bf16 v[30:33], v[66:69], v[226:229], v[30:33]
	v_mfma_f32_16x16x32_bf16 v[14:17], v[66:69], v[230:233], v[14:17]
	v_mfma_f32_16x16x32_bf16 v[58:61], v[70:73], v[218:221], v[58:61]
	v_mfma_f32_16x16x32_bf16 v[42:45], v[70:73], v[222:225], v[42:45]
	v_mfma_f32_16x16x32_bf16 v[26:29], v[70:73], v[226:229], v[26:29]
	v_mfma_f32_16x16x32_bf16 v[10:13], v[70:73], v[230:233], v[10:13]
	v_mfma_f32_16x16x32_bf16 v[54:57], v[74:77], v[218:221], v[54:57]
	v_mfma_f32_16x16x32_bf16 v[38:41], v[74:77], v[222:225], v[38:41]
	v_mfma_f32_16x16x32_bf16 v[22:25], v[74:77], v[226:229], v[22:25]
	v_mfma_f32_16x16x32_bf16 v[6:9], v[74:77], v[230:233], v[6:9]
	v_mfma_f32_16x16x32_bf16 v[50:53], v[78:81], v[218:221], v[50:53]
	v_mfma_f32_16x16x32_bf16 v[34:37], v[78:81], v[222:225], v[34:37]
	v_mfma_f32_16x16x32_bf16 v[18:21], v[78:81], v[226:229], v[18:21]
	v_mfma_f32_16x16x32_bf16 v[2:5], v[78:81], v[230:233], v[2:5]
	s_waitcnt lgkmcnt(0)
	v_mfma_f32_16x16x32_bf16 v[62:65], v[82:85], v[234:237], v[62:65]
	v_mfma_f32_16x16x32_bf16 v[46:49], v[82:85], v[238:241], v[46:49]
	v_mfma_f32_16x16x32_bf16 v[30:33], v[82:85], v[242:245], v[30:33]
	v_mfma_f32_16x16x32_bf16 v[14:17], v[82:85], v[246:249], v[14:17]
	v_mfma_f32_16x16x32_bf16 v[58:61], v[86:89], v[234:237], v[58:61]
	v_mfma_f32_16x16x32_bf16 v[42:45], v[86:89], v[238:241], v[42:45]
	v_mfma_f32_16x16x32_bf16 v[26:29], v[86:89], v[242:245], v[26:29]
	v_mfma_f32_16x16x32_bf16 v[10:13], v[86:89], v[246:249], v[10:13]
	v_mfma_f32_16x16x32_bf16 v[54:57], v[90:93], v[234:237], v[54:57]
	v_mfma_f32_16x16x32_bf16 v[38:41], v[90:93], v[238:241], v[38:41]
	v_mfma_f32_16x16x32_bf16 v[22:25], v[90:93], v[242:245], v[22:25]
	v_mfma_f32_16x16x32_bf16 v[6:9], v[90:93], v[246:249], v[6:9]
	v_mfma_f32_16x16x32_bf16 v[50:53], v[94:97], v[234:237], v[50:53]
	v_mfma_f32_16x16x32_bf16 v[34:37], v[94:97], v[238:241], v[34:37]
	v_mfma_f32_16x16x32_bf16 v[18:21], v[94:97], v[242:245], v[18:21]
	v_mfma_f32_16x16x32_bf16 v[2:5], v[94:97], v[246:249], v[2:5]
	s_waitcnt vmcnt(8)
	s_barrier
	ds_read_b128 v[218:221], v102 offset:0
	ds_read_b128 v[222:225], v102 offset:2048
	ds_read_b128 v[226:229], v102 offset:4096
	ds_read_b128 v[230:233], v102 offset:6144
	ds_read_b128 v[234:237], v103 offset:0
	ds_read_b128 v[238:241], v103 offset:2048
	ds_read_b128 v[242:245], v103 offset:4096
	ds_read_b128 v[246:249], v103 offset:6144
	s_add_u32 m0, s4, 0x8000
	s_nop 0
	global_load_lds_dwordx4 v98, s[6:7]
	s_add_u32 m0, s4, 0x8400
	s_nop 0
	global_load_lds_dwordx4 v99, s[6:7]
	s_add_u32 m0, s4, 0x8800
	s_nop 0
	global_load_lds_dwordx4 v100, s[6:7]
	s_add_u32 m0, s4, 0x8c00
	s_nop 0
	global_load_lds_dwordx4 v101, s[6:7]
	v_add_u32_e32 v98, 0x80, v98
	v_add_u32_e32 v99, 0x80, v99
	v_add_u32_e32 v100, 0x80, v100
	v_add_u32_e32 v101, 0x80, v101
	s_waitcnt lgkmcnt(4)
	v_mfma_f32_16x16x32_bf16 v[106:109], v[66:69], v[218:221], v[106:109]
	v_mfma_f32_16x16x32_bf16 v[122:125], v[66:69], v[222:225], v[122:125]
	v_mfma_f32_16x16x32_bf16 v[138:141], v[66:69], v[226:229], v[138:141]
	v_mfma_f32_16x16x32_bf16 v[162:165], v[66:69], v[230:233], v[162:165]
	v_mfma_f32_16x16x32_bf16 v[110:113], v[70:73], v[218:221], v[110:113]
	v_mfma_f32_16x16x32_bf16 v[126:129], v[70:73], v[222:225], v[126:129]
	v_mfma_f32_16x16x32_bf16 v[142:145], v[70:73], v[226:229], v[142:145]
	v_mfma_f32_16x16x32_bf16 v[166:169], v[70:73], v[230:233], v[166:169]
	v_mfma_f32_16x16x32_bf16 v[114:117], v[74:77], v[218:221], v[114:117]
	v_mfma_f32_16x16x32_bf16 v[130:133], v[74:77], v[222:225], v[130:133]
	v_mfma_f32_16x16x32_bf16 v[154:157], v[74:77], v[226:229], v[154:157]
	v_mfma_f32_16x16x32_bf16 v[170:173], v[74:77], v[230:233], v[170:173]
	v_mfma_f32_16x16x32_bf16 v[118:121], v[78:81], v[218:221], v[118:121]
	v_mfma_f32_16x16x32_bf16 v[134:137], v[78:81], v[222:225], v[134:137]
	v_mfma_f32_16x16x32_bf16 v[158:161], v[78:81], v[226:229], v[158:161]
	v_mfma_f32_16x16x32_bf16 v[174:177], v[78:81], v[230:233], v[174:177]
	s_waitcnt lgkmcnt(0)
	v_mfma_f32_16x16x32_bf16 v[106:109], v[82:85], v[234:237], v[106:109]
	v_mfma_f32_16x16x32_bf16 v[122:125], v[82:85], v[238:241], v[122:125]
	v_mfma_f32_16x16x32_bf16 v[138:141], v[82:85], v[242:245], v[138:141]
	v_mfma_f32_16x16x32_bf16 v[162:165], v[82:85], v[246:249], v[162:165]
	v_mfma_f32_16x16x32_bf16 v[110:113], v[86:89], v[234:237], v[110:113]
	v_mfma_f32_16x16x32_bf16 v[126:129], v[86:89], v[238:241], v[126:129]
	v_mfma_f32_16x16x32_bf16 v[142:145], v[86:89], v[242:245], v[142:145]
	v_mfma_f32_16x16x32_bf16 v[166:169], v[86:89], v[246:249], v[166:169]
	v_mfma_f32_16x16x32_bf16 v[114:117], v[90:93], v[234:237], v[114:117]
	v_mfma_f32_16x16x32_bf16 v[130:133], v[90:93], v[238:241], v[130:133]
	v_mfma_f32_16x16x32_bf16 v[154:157], v[90:93], v[242:245], v[154:157]
	v_mfma_f32_16x16x32_bf16 v[170:173], v[90:93], v[246:249], v[170:173]
	v_mfma_f32_16x16x32_bf16 v[118:121], v[94:97], v[234:237], v[118:121]
	v_mfma_f32_16x16x32_bf16 v[134:137], v[94:97], v[238:241], v[134:137]
	v_mfma_f32_16x16x32_bf16 v[158:161], v[94:97], v[242:245], v[158:161]
	v_mfma_f32_16x16x32_bf16 v[174:177], v[94:97], v[246:249], v[174:177]
	s_waitcnt vmcnt(4)
	s_barrier
	ds_read_b128 v[218:221], v102 offset:16384
	ds_read_b128 v[222:225], v102 offset:18432
	ds_read_b128 v[226:229], v102 offset:20480
	ds_read_b128 v[230:233], v102 offset:22528
	ds_read_b128 v[66:69], v250 offset:49152
	ds_read_b128 v[70:73], v250 offset:51200
	ds_read_b128 v[74:77], v250 offset:53248
	ds_read_b128 v[78:81], v250 offset:55296
	ds_read_b128 v[234:237], v103 offset:16384
	ds_read_b128 v[238:241], v103 offset:18432
	ds_read_b128 v[242:245], v103 offset:20480
	ds_read_b128 v[246:249], v103 offset:22528
	ds_read_b128 v[82:85], v251 offset:49152
	ds_read_b128 v[86:89], v251 offset:51200
	ds_read_b128 v[90:93], v251 offset:53248
	ds_read_b128 v[94:97], v251 offset:55296
	s_add_u32 m0, s4, 0x0
	s_nop 0
	global_load_lds_dwordx4 v98, s[28:29]
	s_add_u32 m0, s4, 0x400
	s_nop 0
	global_load_lds_dwordx4 v99, s[28:29]
	s_add_u32 m0, s4, 0x800
	s_nop 0
	global_load_lds_dwordx4 v100, s[28:29]
	s_add_u32 m0, s4, 0xc00
	s_nop 0
	global_load_lds_dwordx4 v101, s[28:29]
	s_add_u32 m0, s4, 0xc000
	s_nop 0
	global_load_lds_dwordx4 v98, s[48:49]
	s_add_u32 m0, s4, 0xc400
	s_nop 0
	global_load_lds_dwordx4 v99, s[48:49]
	s_add_u32 m0, s4, 0xc800
	s_nop 0
	global_load_lds_dwordx4 v100, s[48:49]
	s_add_u32 m0, s4, 0xcc00
	s_nop 0
	global_load_lds_dwordx4 v101, s[48:49]
	s_waitcnt lgkmcnt(8)
	v_mfma_f32_16x16x32_bf16 v[62:65], v[66:69], v[218:221], v[62:65]
	v_mfma_f32_16x16x32_bf16 v[46:49], v[66:69], v[222:225], v[46:49]
	v_mfma_f32_16x16x32_bf16 v[30:33], v[66:69], v[226:229], v[30:33]
	v_mfma_f32_16x16x32_bf16 v[14:17], v[66:69], v[230:233], v[14:17]
	v_mfma_f32_16x16x32_bf16 v[58:61], v[70:73], v[218:221], v[58:61]
	v_mfma_f32_16x16x32_bf16 v[42:45], v[70:73], v[222:225], v[42:45]
	v_mfma_f32_16x16x32_bf16 v[26:29], v[70:73], v[226:229], v[26:29]
	v_mfma_f32_16x16x32_bf16 v[10:13], v[70:73], v[230:233], v[10:13]
	v_mfma_f32_16x16x32_bf16 v[54:57], v[74:77], v[218:221], v[54:57]
	v_mfma_f32_16x16x32_bf16 v[38:41], v[74:77], v[222:225], v[38:41]
	v_mfma_f32_16x16x32_bf16 v[22:25], v[74:77], v[226:229], v[22:25]
	v_mfma_f32_16x16x32_bf16 v[6:9], v[74:77], v[230:233], v[6:9]
	v_mfma_f32_16x16x32_bf16 v[50:53], v[78:81], v[218:221], v[50:53]
	v_mfma_f32_16x16x32_bf16 v[34:37], v[78:81], v[222:225], v[34:37]
	v_mfma_f32_16x16x32_bf16 v[18:21], v[78:81], v[226:229], v[18:21]
	v_mfma_f32_16x16x32_bf16 v[2:5], v[78:81], v[230:233], v[2:5]
	s_waitcnt lgkmcnt(0)
	v_mfma_f32_16x16x32_bf16 v[62:65], v[82:85], v[234:237], v[62:65]
	v_mfma_f32_16x16x32_bf16 v[46:49], v[82:85], v[238:241], v[46:49]
	v_mfma_f32_16x16x32_bf16 v[30:33], v[82:85], v[242:245], v[30:33]
	v_mfma_f32_16x16x32_bf16 v[14:17], v[82:85], v[246:249], v[14:17]
	v_mfma_f32_16x16x32_bf16 v[58:61], v[86:89], v[234:237], v[58:61]
	v_mfma_f32_16x16x32_bf16 v[42:45], v[86:89], v[238:241], v[42:45]
	v_mfma_f32_16x16x32_bf16 v[26:29], v[86:89], v[242:245], v[26:29]
	v_mfma_f32_16x16x32_bf16 v[10:13], v[86:89], v[246:249], v[10:13]
	v_mfma_f32_16x16x32_bf16 v[54:57], v[90:93], v[234:237], v[54:57]
	v_mfma_f32_16x16x32_bf16 v[38:41], v[90:93], v[238:241], v[38:41]
	v_mfma_f32_16x16x32_bf16 v[22:25], v[90:93], v[242:245], v[22:25]
	v_mfma_f32_16x16x32_bf16 v[6:9], v[90:93], v[246:249], v[6:9]
	v_mfma_f32_16x16x32_bf16 v[50:53], v[94:97], v[234:237], v[50:53]
	v_mfma_f32_16x16x32_bf16 v[34:37], v[94:97], v[238:241], v[34:37]
	v_mfma_f32_16x16x32_bf16 v[18:21], v[94:97], v[242:245], v[18:21]
	v_mfma_f32_16x16x32_bf16 v[2:5], v[94:97], v[246:249], v[2:5]
	s_waitcnt vmcnt(8)
	s_barrier
	ds_read_b128 v[218:221], v102 offset:32768
	ds_read_b128 v[222:225], v102 offset:34816
	ds_read_b128 v[226:229], v102 offset:36864
	ds_read_b128 v[230:233], v102 offset:38912
	ds_read_b128 v[234:237], v103 offset:32768
	ds_read_b128 v[238:241], v103 offset:34816
	ds_read_b128 v[242:245], v103 offset:36864
	ds_read_b128 v[246:249], v103 offset:38912
	s_add_u32 m0, s4, 0x4000
	s_nop 0
	global_load_lds_dwordx4 v98, s[6:7]
	s_add_u32 m0, s4, 0x4400
	s_nop 0
	global_load_lds_dwordx4 v99, s[6:7]
	s_add_u32 m0, s4, 0x4800
	s_nop 0
	global_load_lds_dwordx4 v100, s[6:7]
	s_add_u32 m0, s4, 0x4c00
	s_nop 0
	global_load_lds_dwordx4 v101, s[6:7]
	v_add_u32_e32 v98, 0x80, v98
	v_add_u32_e32 v99, 0x80, v99
	v_add_u32_e32 v100, 0x80, v100
	v_add_u32_e32 v101, 0x80, v101
	s_waitcnt lgkmcnt(4)
	v_mfma_f32_16x16x32_bf16 v[106:109], v[66:69], v[218:221], v[106:109]
	v_mfma_f32_16x16x32_bf16 v[122:125], v[66:69], v[222:225], v[122:125]
	v_mfma_f32_16x16x32_bf16 v[138:141], v[66:69], v[226:229], v[138:141]
	v_mfma_f32_16x16x32_bf16 v[162:165], v[66:69], v[230:233], v[162:165]
	v_mfma_f32_16x16x32_bf16 v[110:113], v[70:73], v[218:221], v[110:113]
	v_mfma_f32_16x16x32_bf16 v[126:129], v[70:73], v[222:225], v[126:129]
	v_mfma_f32_16x16x32_bf16 v[142:145], v[70:73], v[226:229], v[142:145]
	v_mfma_f32_16x16x32_bf16 v[166:169], v[70:73], v[230:233], v[166:169]
	v_mfma_f32_16x16x32_bf16 v[114:117], v[74:77], v[218:221], v[114:117]
	v_mfma_f32_16x16x32_bf16 v[130:133], v[74:77], v[222:225], v[130:133]
	v_mfma_f32_16x16x32_bf16 v[154:157], v[74:77], v[226:229], v[154:157]
	v_mfma_f32_16x16x32_bf16 v[170:173], v[74:77], v[230:233], v[170:173]
	v_mfma_f32_16x16x32_bf16 v[118:121], v[78:81], v[218:221], v[118:121]
	v_mfma_f32_16x16x32_bf16 v[134:137], v[78:81], v[222:225], v[134:137]
	v_mfma_f32_16x16x32_bf16 v[158:161], v[78:81], v[226:229], v[158:161]
	v_mfma_f32_16x16x32_bf16 v[174:177], v[78:81], v[230:233], v[174:177]
	s_waitcnt lgkmcnt(0)
	v_mfma_f32_16x16x32_bf16 v[106:109], v[82:85], v[234:237], v[106:109]
	v_mfma_f32_16x16x32_bf16 v[122:125], v[82:85], v[238:241], v[122:125]
	v_mfma_f32_16x16x32_bf16 v[138:141], v[82:85], v[242:245], v[138:141]
	v_mfma_f32_16x16x32_bf16 v[162:165], v[82:85], v[246:249], v[162:165]
	v_mfma_f32_16x16x32_bf16 v[110:113], v[86:89], v[234:237], v[110:113]
	v_mfma_f32_16x16x32_bf16 v[126:129], v[86:89], v[238:241], v[126:129]
	v_mfma_f32_16x16x32_bf16 v[142:145], v[86:89], v[242:245], v[142:145]
	v_mfma_f32_16x16x32_bf16 v[166:169], v[86:89], v[246:249], v[166:169]
	v_mfma_f32_16x16x32_bf16 v[114:117], v[90:93], v[234:237], v[114:117]
	v_mfma_f32_16x16x32_bf16 v[130:133], v[90:93], v[238:241], v[130:133]
	v_mfma_f32_16x16x32_bf16 v[154:157], v[90:93], v[242:245], v[154:157]
	v_mfma_f32_16x16x32_bf16 v[170:173], v[90:93], v[246:249], v[170:173]
	v_mfma_f32_16x16x32_bf16 v[118:121], v[94:97], v[234:237], v[118:121]
	v_mfma_f32_16x16x32_bf16 v[134:137], v[94:97], v[238:241], v[134:137]
	v_mfma_f32_16x16x32_bf16 v[158:161], v[94:97], v[242:245], v[158:161]
	v_mfma_f32_16x16x32_bf16 v[174:177], v[94:97], v[246:249], v[174:177]
	s_waitcnt vmcnt(4)
	s_barrier
	ds_read_b128 v[218:221], v102 offset:0
	ds_read_b128 v[222:225], v102 offset:2048
	ds_read_b128 v[226:229], v102 offset:4096
	ds_read_b128 v[230:233], v102 offset:6144
	ds_read_b128 v[66:69], v104 offset:49152
	ds_read_b128 v[70:73], v104 offset:51200
	ds_read_b128 v[74:77], v104 offset:53248
	ds_read_b128 v[78:81], v104 offset:55296
	ds_read_b128 v[234:237], v103 offset:0
	ds_read_b128 v[238:241], v103 offset:2048
	ds_read_b128 v[242:245], v103 offset:4096
	ds_read_b128 v[246:249], v103 offset:6144
	ds_read_b128 v[82:85], v105 offset:49152
	ds_read_b128 v[86:89], v105 offset:51200
	ds_read_b128 v[90:93], v105 offset:53248
	ds_read_b128 v[94:97], v105 offset:55296
	s_add_u32 m0, s4, 0x8000
	s_nop 0
	global_load_lds_dwordx4 v98, s[28:29]
	s_add_u32 m0, s4, 0x8400
	s_nop 0
	global_load_lds_dwordx4 v99, s[28:29]
	s_add_u32 m0, s4, 0x8800
	s_nop 0
	global_load_lds_dwordx4 v100, s[28:29]
	s_add_u32 m0, s4, 0x8c00
	s_nop 0
	global_load_lds_dwordx4 v101, s[28:29]
	s_add_u32 m0, s4, 0x10000
	s_nop 0
	global_load_lds_dwordx4 v98, s[48:49]
	s_add_u32 m0, s4, 0x10400
	s_nop 0
	global_load_lds_dwordx4 v99, s[48:49]
	s_add_u32 m0, s4, 0x10800
	s_nop 0
	global_load_lds_dwordx4 v100, s[48:49]
	s_add_u32 m0, s4, 0x10c00
	s_nop 0
	global_load_lds_dwordx4 v101, s[48:49]
	s_waitcnt lgkmcnt(8)
	v_mfma_f32_16x16x32_bf16 v[62:65], v[66:69], v[218:221], v[62:65]
	v_mfma_f32_16x16x32_bf16 v[46:49], v[66:69], v[222:225], v[46:49]
	v_mfma_f32_16x16x32_bf16 v[30:33], v[66:69], v[226:229], v[30:33]
	v_mfma_f32_16x16x32_bf16 v[14:17], v[66:69], v[230:233], v[14:17]
	v_mfma_f32_16x16x32_bf16 v[58:61], v[70:73], v[218:221], v[58:61]
	v_mfma_f32_16x16x32_bf16 v[42:45], v[70:73], v[222:225], v[42:45]
	v_mfma_f32_16x16x32_bf16 v[26:29], v[70:73], v[226:229], v[26:29]
	v_mfma_f32_16x16x32_bf16 v[10:13], v[70:73], v[230:233], v[10:13]
	v_mfma_f32_16x16x32_bf16 v[54:57], v[74:77], v[218:221], v[54:57]
	v_mfma_f32_16x16x32_bf16 v[38:41], v[74:77], v[222:225], v[38:41]
	v_mfma_f32_16x16x32_bf16 v[22:25], v[74:77], v[226:229], v[22:25]
	v_mfma_f32_16x16x32_bf16 v[6:9], v[74:77], v[230:233], v[6:9]
	v_mfma_f32_16x16x32_bf16 v[50:53], v[78:81], v[218:221], v[50:53]
	v_mfma_f32_16x16x32_bf16 v[34:37], v[78:81], v[222:225], v[34:37]
	v_mfma_f32_16x16x32_bf16 v[18:21], v[78:81], v[226:229], v[18:21]
	v_mfma_f32_16x16x32_bf16 v[2:5], v[78:81], v[230:233], v[2:5]
	s_waitcnt lgkmcnt(0)
	v_mfma_f32_16x16x32_bf16 v[62:65], v[82:85], v[234:237], v[62:65]
	v_mfma_f32_16x16x32_bf16 v[46:49], v[82:85], v[238:241], v[46:49]
	v_mfma_f32_16x16x32_bf16 v[30:33], v[82:85], v[242:245], v[30:33]
	v_mfma_f32_16x16x32_bf16 v[14:17], v[82:85], v[246:249], v[14:17]
	v_mfma_f32_16x16x32_bf16 v[58:61], v[86:89], v[234:237], v[58:61]
	v_mfma_f32_16x16x32_bf16 v[42:45], v[86:89], v[238:241], v[42:45]
	v_mfma_f32_16x16x32_bf16 v[26:29], v[86:89], v[242:245], v[26:29]
	v_mfma_f32_16x16x32_bf16 v[10:13], v[86:89], v[246:249], v[10:13]
	v_mfma_f32_16x16x32_bf16 v[54:57], v[90:93], v[234:237], v[54:57]
	v_mfma_f32_16x16x32_bf16 v[38:41], v[90:93], v[238:241], v[38:41]
	v_mfma_f32_16x16x32_bf16 v[22:25], v[90:93], v[242:245], v[22:25]
	v_mfma_f32_16x16x32_bf16 v[6:9], v[90:93], v[246:249], v[6:9]
	v_mfma_f32_16x16x32_bf16 v[50:53], v[94:97], v[234:237], v[50:53]
	v_mfma_f32_16x16x32_bf16 v[34:37], v[94:97], v[238:241], v[34:37]
	v_mfma_f32_16x16x32_bf16 v[18:21], v[94:97], v[242:245], v[18:21]
	v_mfma_f32_16x16x32_bf16 v[2:5], v[94:97], v[246:249], v[2:5]
	s_waitcnt vmcnt(8)
	s_barrier
	ds_read_b128 v[218:221], v102 offset:16384
	ds_read_b128 v[222:225], v102 offset:18432
	ds_read_b128 v[226:229], v102 offset:20480
	ds_read_b128 v[230:233], v102 offset:22528
	ds_read_b128 v[234:237], v103 offset:16384
	ds_read_b128 v[238:241], v103 offset:18432
	ds_read_b128 v[242:245], v103 offset:20480
	ds_read_b128 v[246:249], v103 offset:22528
	s_add_u32 m0, s4, 0x0
	s_nop 0
	global_load_lds_dwordx4 v98, s[6:7]
	s_add_u32 m0, s4, 0x400
	s_nop 0
	global_load_lds_dwordx4 v99, s[6:7]
	s_add_u32 m0, s4, 0x800
	s_nop 0
	global_load_lds_dwordx4 v100, s[6:7]
	s_add_u32 m0, s4, 0xc00
	s_nop 0
	global_load_lds_dwordx4 v101, s[6:7]
	v_add_u32_e32 v98, 0x80, v98
	v_add_u32_e32 v99, 0x80, v99
	v_add_u32_e32 v100, 0x80, v100
	v_add_u32_e32 v101, 0x80, v101
	s_waitcnt lgkmcnt(4)
	v_mfma_f32_16x16x32_bf16 v[106:109], v[66:69], v[218:221], v[106:109]
	v_mfma_f32_16x16x32_bf16 v[122:125], v[66:69], v[222:225], v[122:125]
	v_mfma_f32_16x16x32_bf16 v[138:141], v[66:69], v[226:229], v[138:141]
	v_mfma_f32_16x16x32_bf16 v[162:165], v[66:69], v[230:233], v[162:165]
	v_mfma_f32_16x16x32_bf16 v[110:113], v[70:73], v[218:221], v[110:113]
	v_mfma_f32_16x16x32_bf16 v[126:129], v[70:73], v[222:225], v[126:129]
	v_mfma_f32_16x16x32_bf16 v[142:145], v[70:73], v[226:229], v[142:145]
	v_mfma_f32_16x16x32_bf16 v[166:169], v[70:73], v[230:233], v[166:169]
	v_mfma_f32_16x16x32_bf16 v[114:117], v[74:77], v[218:221], v[114:117]
	v_mfma_f32_16x16x32_bf16 v[130:133], v[74:77], v[222:225], v[130:133]
	v_mfma_f32_16x16x32_bf16 v[154:157], v[74:77], v[226:229], v[154:157]
	v_mfma_f32_16x16x32_bf16 v[170:173], v[74:77], v[230:233], v[170:173]
	v_mfma_f32_16x16x32_bf16 v[118:121], v[78:81], v[218:221], v[118:121]
	v_mfma_f32_16x16x32_bf16 v[134:137], v[78:81], v[222:225], v[134:137]
	v_mfma_f32_16x16x32_bf16 v[158:161], v[78:81], v[226:229], v[158:161]
	v_mfma_f32_16x16x32_bf16 v[174:177], v[78:81], v[230:233], v[174:177]
	s_waitcnt lgkmcnt(0)
	v_mfma_f32_16x16x32_bf16 v[106:109], v[82:85], v[234:237], v[106:109]
	v_mfma_f32_16x16x32_bf16 v[122:125], v[82:85], v[238:241], v[122:125]
	v_mfma_f32_16x16x32_bf16 v[138:141], v[82:85], v[242:245], v[138:141]
	v_mfma_f32_16x16x32_bf16 v[162:165], v[82:85], v[246:249], v[162:165]
	v_mfma_f32_16x16x32_bf16 v[110:113], v[86:89], v[234:237], v[110:113]
	v_mfma_f32_16x16x32_bf16 v[126:129], v[86:89], v[238:241], v[126:129]
	v_mfma_f32_16x16x32_bf16 v[142:145], v[86:89], v[242:245], v[142:145]
	v_mfma_f32_16x16x32_bf16 v[166:169], v[86:89], v[246:249], v[166:169]
	v_mfma_f32_16x16x32_bf16 v[114:117], v[90:93], v[234:237], v[114:117]
	v_mfma_f32_16x16x32_bf16 v[130:133], v[90:93], v[238:241], v[130:133]
	v_mfma_f32_16x16x32_bf16 v[154:157], v[90:93], v[242:245], v[154:157]
	v_mfma_f32_16x16x32_bf16 v[170:173], v[90:93], v[246:249], v[170:173]
	v_mfma_f32_16x16x32_bf16 v[118:121], v[94:97], v[234:237], v[118:121]
	v_mfma_f32_16x16x32_bf16 v[134:137], v[94:97], v[238:241], v[134:137]
	v_mfma_f32_16x16x32_bf16 v[158:161], v[94:97], v[242:245], v[158:161]
	v_mfma_f32_16x16x32_bf16 v[174:177], v[94:97], v[246:249], v[174:177]
	s_waitcnt vmcnt(4)
	s_barrier
	ds_read_b128 v[218:221], v102 offset:32768
	ds_read_b128 v[222:225], v102 offset:34816
	ds_read_b128 v[226:229], v102 offset:36864
	ds_read_b128 v[230:233], v102 offset:38912
	ds_read_b128 v[66:69], v250 offset:49152
	ds_read_b128 v[70:73], v250 offset:51200
	ds_read_b128 v[74:77], v250 offset:53248
	ds_read_b128 v[78:81], v250 offset:55296
	ds_read_b128 v[234:237], v103 offset:32768
	ds_read_b128 v[238:241], v103 offset:34816
	ds_read_b128 v[242:245], v103 offset:36864
	ds_read_b128 v[246:249], v103 offset:38912
	ds_read_b128 v[82:85], v251 offset:49152
	ds_read_b128 v[86:89], v251 offset:51200
	ds_read_b128 v[90:93], v251 offset:53248
	ds_read_b128 v[94:97], v251 offset:55296
	s_add_u32 m0, s4, 0x4000
	s_nop 0
	global_load_lds_dwordx4 v98, s[28:29]
	s_add_u32 m0, s4, 0x4400
	s_nop 0
	global_load_lds_dwordx4 v99, s[28:29]
	s_add_u32 m0, s4, 0x4800
	s_nop 0
	global_load_lds_dwordx4 v100, s[28:29]
	s_add_u32 m0, s4, 0x4c00
	s_nop 0
	global_load_lds_dwordx4 v101, s[28:29]
	s_add_u32 m0, s4, 0xc000
	s_nop 0
	global_load_lds_dwordx4 v98, s[48:49]
	s_add_u32 m0, s4, 0xc400
	s_nop 0
	global_load_lds_dwordx4 v99, s[48:49]
	s_add_u32 m0, s4, 0xc800
	s_nop 0
	global_load_lds_dwordx4 v100, s[48:49]
	s_add_u32 m0, s4, 0xcc00
	s_nop 0
	global_load_lds_dwordx4 v101, s[48:49]
	s_waitcnt lgkmcnt(8)
	v_mfma_f32_16x16x32_bf16 v[62:65], v[66:69], v[218:221], v[62:65]
	v_mfma_f32_16x16x32_bf16 v[46:49], v[66:69], v[222:225], v[46:49]
	v_mfma_f32_16x16x32_bf16 v[30:33], v[66:69], v[226:229], v[30:33]
	v_mfma_f32_16x16x32_bf16 v[14:17], v[66:69], v[230:233], v[14:17]
	v_mfma_f32_16x16x32_bf16 v[58:61], v[70:73], v[218:221], v[58:61]
	v_mfma_f32_16x16x32_bf16 v[42:45], v[70:73], v[222:225], v[42:45]
	v_mfma_f32_16x16x32_bf16 v[26:29], v[70:73], v[226:229], v[26:29]
	v_mfma_f32_16x16x32_bf16 v[10:13], v[70:73], v[230:233], v[10:13]
	v_mfma_f32_16x16x32_bf16 v[54:57], v[74:77], v[218:221], v[54:57]
	v_mfma_f32_16x16x32_bf16 v[38:41], v[74:77], v[222:225], v[38:41]
	v_mfma_f32_16x16x32_bf16 v[22:25], v[74:77], v[226:229], v[22:25]
	v_mfma_f32_16x16x32_bf16 v[6:9], v[74:77], v[230:233], v[6:9]
	v_mfma_f32_16x16x32_bf16 v[50:53], v[78:81], v[218:221], v[50:53]
	v_mfma_f32_16x16x32_bf16 v[34:37], v[78:81], v[222:225], v[34:37]
	v_mfma_f32_16x16x32_bf16 v[18:21], v[78:81], v[226:229], v[18:21]
	v_mfma_f32_16x16x32_bf16 v[2:5], v[78:81], v[230:233], v[2:5]
	s_waitcnt lgkmcnt(0)
	v_mfma_f32_16x16x32_bf16 v[62:65], v[82:85], v[234:237], v[62:65]
	v_mfma_f32_16x16x32_bf16 v[46:49], v[82:85], v[238:241], v[46:49]
	v_mfma_f32_16x16x32_bf16 v[30:33], v[82:85], v[242:245], v[30:33]
	v_mfma_f32_16x16x32_bf16 v[14:17], v[82:85], v[246:249], v[14:17]
	v_mfma_f32_16x16x32_bf16 v[58:61], v[86:89], v[234:237], v[58:61]
	v_mfma_f32_16x16x32_bf16 v[42:45], v[86:89], v[238:241], v[42:45]
	v_mfma_f32_16x16x32_bf16 v[26:29], v[86:89], v[242:245], v[26:29]
	v_mfma_f32_16x16x32_bf16 v[10:13], v[86:89], v[246:249], v[10:13]
	v_mfma_f32_16x16x32_bf16 v[54:57], v[90:93], v[234:237], v[54:57]
	v_mfma_f32_16x16x32_bf16 v[38:41], v[90:93], v[238:241], v[38:41]
	v_mfma_f32_16x16x32_bf16 v[22:25], v[90:93], v[242:245], v[22:25]
	v_mfma_f32_16x16x32_bf16 v[6:9], v[90:93], v[246:249], v[6:9]
	v_mfma_f32_16x16x32_bf16 v[50:53], v[94:97], v[234:237], v[50:53]
	v_mfma_f32_16x16x32_bf16 v[34:37], v[94:97], v[238:241], v[34:37]
	v_mfma_f32_16x16x32_bf16 v[18:21], v[94:97], v[242:245], v[18:21]
	v_mfma_f32_16x16x32_bf16 v[2:5], v[94:97], v[246:249], v[2:5]
	s_waitcnt vmcnt(8)
	s_barrier
	ds_read_b128 v[218:221], v102 offset:0
	ds_read_b128 v[222:225], v102 offset:2048
	ds_read_b128 v[226:229], v102 offset:4096
	ds_read_b128 v[230:233], v102 offset:6144
	ds_read_b128 v[234:237], v103 offset:0
	ds_read_b128 v[238:241], v103 offset:2048
	ds_read_b128 v[242:245], v103 offset:4096
	ds_read_b128 v[246:249], v103 offset:6144
	s_add_u32 m0, s4, 0x8000
	s_nop 0
	global_load_lds_dwordx4 v98, s[6:7]
	s_add_u32 m0, s4, 0x8400
	s_nop 0
	global_load_lds_dwordx4 v99, s[6:7]
	s_add_u32 m0, s4, 0x8800
	s_nop 0
	global_load_lds_dwordx4 v100, s[6:7]
	s_add_u32 m0, s4, 0x8c00
	s_nop 0
	global_load_lds_dwordx4 v101, s[6:7]
	v_add_u32_e32 v98, 0x80, v98
	v_add_u32_e32 v99, 0x80, v99
	v_add_u32_e32 v100, 0x80, v100
	v_add_u32_e32 v101, 0x80, v101
	s_waitcnt lgkmcnt(4)
	v_mfma_f32_16x16x32_bf16 v[106:109], v[66:69], v[218:221], v[106:109]
	v_mfma_f32_16x16x32_bf16 v[122:125], v[66:69], v[222:225], v[122:125]
	v_mfma_f32_16x16x32_bf16 v[138:141], v[66:69], v[226:229], v[138:141]
	v_mfma_f32_16x16x32_bf16 v[162:165], v[66:69], v[230:233], v[162:165]
	v_mfma_f32_16x16x32_bf16 v[110:113], v[70:73], v[218:221], v[110:113]
	v_mfma_f32_16x16x32_bf16 v[126:129], v[70:73], v[222:225], v[126:129]
	v_mfma_f32_16x16x32_bf16 v[142:145], v[70:73], v[226:229], v[142:145]
	v_mfma_f32_16x16x32_bf16 v[166:169], v[70:73], v[230:233], v[166:169]
	v_mfma_f32_16x16x32_bf16 v[114:117], v[74:77], v[218:221], v[114:117]
	v_mfma_f32_16x16x32_bf16 v[130:133], v[74:77], v[222:225], v[130:133]
	v_mfma_f32_16x16x32_bf16 v[154:157], v[74:77], v[226:229], v[154:157]
	v_mfma_f32_16x16x32_bf16 v[170:173], v[74:77], v[230:233], v[170:173]
	v_mfma_f32_16x16x32_bf16 v[118:121], v[78:81], v[218:221], v[118:121]
	v_mfma_f32_16x16x32_bf16 v[134:137], v[78:81], v[222:225], v[134:137]
	v_mfma_f32_16x16x32_bf16 v[158:161], v[78:81], v[226:229], v[158:161]
	v_mfma_f32_16x16x32_bf16 v[174:177], v[78:81], v[230:233], v[174:177]
	s_waitcnt lgkmcnt(0)
	v_mfma_f32_16x16x32_bf16 v[106:109], v[82:85], v[234:237], v[106:109]
	v_mfma_f32_16x16x32_bf16 v[122:125], v[82:85], v[238:241], v[122:125]
	v_mfma_f32_16x16x32_bf16 v[138:141], v[82:85], v[242:245], v[138:141]
	v_mfma_f32_16x16x32_bf16 v[162:165], v[82:85], v[246:249], v[162:165]
	v_mfma_f32_16x16x32_bf16 v[110:113], v[86:89], v[234:237], v[110:113]
	v_mfma_f32_16x16x32_bf16 v[126:129], v[86:89], v[238:241], v[126:129]
	v_mfma_f32_16x16x32_bf16 v[142:145], v[86:89], v[242:245], v[142:145]
	v_mfma_f32_16x16x32_bf16 v[166:169], v[86:89], v[246:249], v[166:169]
	v_mfma_f32_16x16x32_bf16 v[114:117], v[90:93], v[234:237], v[114:117]
	v_mfma_f32_16x16x32_bf16 v[130:133], v[90:93], v[238:241], v[130:133]
	v_mfma_f32_16x16x32_bf16 v[154:157], v[90:93], v[242:245], v[154:157]
	v_mfma_f32_16x16x32_bf16 v[170:173], v[90:93], v[246:249], v[170:173]
	v_mfma_f32_16x16x32_bf16 v[118:121], v[94:97], v[234:237], v[118:121]
	v_mfma_f32_16x16x32_bf16 v[134:137], v[94:97], v[238:241], v[134:137]
	v_mfma_f32_16x16x32_bf16 v[158:161], v[94:97], v[242:245], v[158:161]
	v_mfma_f32_16x16x32_bf16 v[174:177], v[94:97], v[246:249], v[174:177]
	s_waitcnt vmcnt(4)
	s_barrier
	ds_read_b128 v[218:221], v102 offset:16384
	ds_read_b128 v[222:225], v102 offset:18432
	ds_read_b128 v[226:229], v102 offset:20480
	ds_read_b128 v[230:233], v102 offset:22528
	ds_read_b128 v[66:69], v104 offset:49152
	ds_read_b128 v[70:73], v104 offset:51200
	ds_read_b128 v[74:77], v104 offset:53248
	ds_read_b128 v[78:81], v104 offset:55296
	ds_read_b128 v[234:237], v103 offset:16384
	ds_read_b128 v[238:241], v103 offset:18432
	ds_read_b128 v[242:245], v103 offset:20480
	ds_read_b128 v[246:249], v103 offset:22528
	ds_read_b128 v[82:85], v105 offset:49152
	ds_read_b128 v[86:89], v105 offset:51200
	ds_read_b128 v[90:93], v105 offset:53248
	ds_read_b128 v[94:97], v105 offset:55296
	s_add_u32 m0, s4, 0x0
	s_nop 0
	global_load_lds_dwordx4 v98, s[28:29]
	s_add_u32 m0, s4, 0x400
	s_nop 0
	global_load_lds_dwordx4 v99, s[28:29]
	s_add_u32 m0, s4, 0x800
	s_nop 0
	global_load_lds_dwordx4 v100, s[28:29]
	s_add_u32 m0, s4, 0xc00
	s_nop 0
	global_load_lds_dwordx4 v101, s[28:29]
	s_add_u32 m0, s4, 0x10000
	s_nop 0
	global_load_lds_dwordx4 v98, s[48:49]
	s_add_u32 m0, s4, 0x10400
	s_nop 0
	global_load_lds_dwordx4 v99, s[48:49]
	s_add_u32 m0, s4, 0x10800
	s_nop 0
	global_load_lds_dwordx4 v100, s[48:49]
	s_add_u32 m0, s4, 0x10c00
	s_nop 0
	global_load_lds_dwordx4 v101, s[48:49]
	s_waitcnt lgkmcnt(8)
	v_mfma_f32_16x16x32_bf16 v[62:65], v[66:69], v[218:221], v[62:65]
	v_mfma_f32_16x16x32_bf16 v[46:49], v[66:69], v[222:225], v[46:49]
	v_mfma_f32_16x16x32_bf16 v[30:33], v[66:69], v[226:229], v[30:33]
	v_mfma_f32_16x16x32_bf16 v[14:17], v[66:69], v[230:233], v[14:17]
	v_mfma_f32_16x16x32_bf16 v[58:61], v[70:73], v[218:221], v[58:61]
	v_mfma_f32_16x16x32_bf16 v[42:45], v[70:73], v[222:225], v[42:45]
	v_mfma_f32_16x16x32_bf16 v[26:29], v[70:73], v[226:229], v[26:29]
	v_mfma_f32_16x16x32_bf16 v[10:13], v[70:73], v[230:233], v[10:13]
	v_mfma_f32_16x16x32_bf16 v[54:57], v[74:77], v[218:221], v[54:57]
	v_mfma_f32_16x16x32_bf16 v[38:41], v[74:77], v[222:225], v[38:41]
	v_mfma_f32_16x16x32_bf16 v[22:25], v[74:77], v[226:229], v[22:25]
	v_mfma_f32_16x16x32_bf16 v[6:9], v[74:77], v[230:233], v[6:9]
	v_mfma_f32_16x16x32_bf16 v[50:53], v[78:81], v[218:221], v[50:53]
	v_mfma_f32_16x16x32_bf16 v[34:37], v[78:81], v[222:225], v[34:37]
	v_mfma_f32_16x16x32_bf16 v[18:21], v[78:81], v[226:229], v[18:21]
	v_mfma_f32_16x16x32_bf16 v[2:5], v[78:81], v[230:233], v[2:5]
	s_waitcnt lgkmcnt(0)
	v_mfma_f32_16x16x32_bf16 v[62:65], v[82:85], v[234:237], v[62:65]
	v_mfma_f32_16x16x32_bf16 v[46:49], v[82:85], v[238:241], v[46:49]
	v_mfma_f32_16x16x32_bf16 v[30:33], v[82:85], v[242:245], v[30:33]
	v_mfma_f32_16x16x32_bf16 v[14:17], v[82:85], v[246:249], v[14:17]
	v_mfma_f32_16x16x32_bf16 v[58:61], v[86:89], v[234:237], v[58:61]
	v_mfma_f32_16x16x32_bf16 v[42:45], v[86:89], v[238:241], v[42:45]
	v_mfma_f32_16x16x32_bf16 v[26:29], v[86:89], v[242:245], v[26:29]
	v_mfma_f32_16x16x32_bf16 v[10:13], v[86:89], v[246:249], v[10:13]
	v_mfma_f32_16x16x32_bf16 v[54:57], v[90:93], v[234:237], v[54:57]
	v_mfma_f32_16x16x32_bf16 v[38:41], v[90:93], v[238:241], v[38:41]
	v_mfma_f32_16x16x32_bf16 v[22:25], v[90:93], v[242:245], v[22:25]
	v_mfma_f32_16x16x32_bf16 v[6:9], v[90:93], v[246:249], v[6:9]
	v_mfma_f32_16x16x32_bf16 v[50:53], v[94:97], v[234:237], v[50:53]
	v_mfma_f32_16x16x32_bf16 v[34:37], v[94:97], v[238:241], v[34:37]
	v_mfma_f32_16x16x32_bf16 v[18:21], v[94:97], v[242:245], v[18:21]
	v_mfma_f32_16x16x32_bf16 v[2:5], v[94:97], v[246:249], v[2:5]
	s_waitcnt vmcnt(8)
	s_barrier
	ds_read_b128 v[218:221], v102 offset:32768
	ds_read_b128 v[222:225], v102 offset:34816
	ds_read_b128 v[226:229], v102 offset:36864
	ds_read_b128 v[230:233], v102 offset:38912
	ds_read_b128 v[234:237], v103 offset:32768
	ds_read_b128 v[238:241], v103 offset:34816
	ds_read_b128 v[242:245], v103 offset:36864
	ds_read_b128 v[246:249], v103 offset:38912
	s_add_u32 m0, s4, 0x4000
	s_nop 0
	global_load_lds_dwordx4 v98, s[6:7]
	s_add_u32 m0, s4, 0x4400
	s_nop 0
	global_load_lds_dwordx4 v99, s[6:7]
	s_add_u32 m0, s4, 0x4800
	s_nop 0
	global_load_lds_dwordx4 v100, s[6:7]
	s_add_u32 m0, s4, 0x4c00
	s_nop 0
	global_load_lds_dwordx4 v101, s[6:7]
	v_add_u32_e32 v98, 0x80, v98
	v_add_u32_e32 v99, 0x80, v99
	v_add_u32_e32 v100, 0x80, v100
	v_add_u32_e32 v101, 0x80, v101
	s_waitcnt lgkmcnt(4)
	v_mfma_f32_16x16x32_bf16 v[106:109], v[66:69], v[218:221], v[106:109]
	v_mfma_f32_16x16x32_bf16 v[122:125], v[66:69], v[222:225], v[122:125]
	v_mfma_f32_16x16x32_bf16 v[138:141], v[66:69], v[226:229], v[138:141]
	v_mfma_f32_16x16x32_bf16 v[162:165], v[66:69], v[230:233], v[162:165]
	v_mfma_f32_16x16x32_bf16 v[110:113], v[70:73], v[218:221], v[110:113]
	v_mfma_f32_16x16x32_bf16 v[126:129], v[70:73], v[222:225], v[126:129]
	v_mfma_f32_16x16x32_bf16 v[142:145], v[70:73], v[226:229], v[142:145]
	v_mfma_f32_16x16x32_bf16 v[166:169], v[70:73], v[230:233], v[166:169]
	v_mfma_f32_16x16x32_bf16 v[114:117], v[74:77], v[218:221], v[114:117]
	v_mfma_f32_16x16x32_bf16 v[130:133], v[74:77], v[222:225], v[130:133]
	v_mfma_f32_16x16x32_bf16 v[154:157], v[74:77], v[226:229], v[154:157]
	v_mfma_f32_16x16x32_bf16 v[170:173], v[74:77], v[230:233], v[170:173]
	v_mfma_f32_16x16x32_bf16 v[118:121], v[78:81], v[218:221], v[118:121]
	v_mfma_f32_16x16x32_bf16 v[134:137], v[78:81], v[222:225], v[134:137]
	v_mfma_f32_16x16x32_bf16 v[158:161], v[78:81], v[226:229], v[158:161]
	v_mfma_f32_16x16x32_bf16 v[174:177], v[78:81], v[230:233], v[174:177]
	s_waitcnt lgkmcnt(0)
	v_mfma_f32_16x16x32_bf16 v[106:109], v[82:85], v[234:237], v[106:109]
	v_mfma_f32_16x16x32_bf16 v[122:125], v[82:85], v[238:241], v[122:125]
	v_mfma_f32_16x16x32_bf16 v[138:141], v[82:85], v[242:245], v[138:141]
	v_mfma_f32_16x16x32_bf16 v[162:165], v[82:85], v[246:249], v[162:165]
	v_mfma_f32_16x16x32_bf16 v[110:113], v[86:89], v[234:237], v[110:113]
	v_mfma_f32_16x16x32_bf16 v[126:129], v[86:89], v[238:241], v[126:129]
	v_mfma_f32_16x16x32_bf16 v[142:145], v[86:89], v[242:245], v[142:145]
	v_mfma_f32_16x16x32_bf16 v[166:169], v[86:89], v[246:249], v[166:169]
	v_mfma_f32_16x16x32_bf16 v[114:117], v[90:93], v[234:237], v[114:117]
	v_mfma_f32_16x16x32_bf16 v[130:133], v[90:93], v[238:241], v[130:133]
	v_mfma_f32_16x16x32_bf16 v[154:157], v[90:93], v[242:245], v[154:157]
	v_mfma_f32_16x16x32_bf16 v[170:173], v[90:93], v[246:249], v[170:173]
	v_mfma_f32_16x16x32_bf16 v[118:121], v[94:97], v[234:237], v[118:121]
	v_mfma_f32_16x16x32_bf16 v[134:137], v[94:97], v[238:241], v[134:137]
	v_mfma_f32_16x16x32_bf16 v[158:161], v[94:97], v[242:245], v[158:161]
	v_mfma_f32_16x16x32_bf16 v[174:177], v[94:97], v[246:249], v[174:177]
	s_waitcnt vmcnt(4)
	s_barrier
	ds_read_b128 v[218:221], v102 offset:0
	ds_read_b128 v[222:225], v102 offset:2048
	ds_read_b128 v[226:229], v102 offset:4096
	ds_read_b128 v[230:233], v102 offset:6144
	ds_read_b128 v[66:69], v250 offset:49152
	ds_read_b128 v[70:73], v250 offset:51200
	ds_read_b128 v[74:77], v250 offset:53248
	ds_read_b128 v[78:81], v250 offset:55296
	ds_read_b128 v[234:237], v103 offset:0
	ds_read_b128 v[238:241], v103 offset:2048
	ds_read_b128 v[242:245], v103 offset:4096
	ds_read_b128 v[246:249], v103 offset:6144
	ds_read_b128 v[82:85], v251 offset:49152
	ds_read_b128 v[86:89], v251 offset:51200
	ds_read_b128 v[90:93], v251 offset:53248
	ds_read_b128 v[94:97], v251 offset:55296
	s_add_u32 m0, s4, 0x8000
	s_nop 0
	global_load_lds_dwordx4 v98, s[28:29]
	s_add_u32 m0, s4, 0x8400
	s_nop 0
	global_load_lds_dwordx4 v99, s[28:29]
	s_add_u32 m0, s4, 0x8800
	s_nop 0
	global_load_lds_dwordx4 v100, s[28:29]
	s_add_u32 m0, s4, 0x8c00
	s_nop 0
	global_load_lds_dwordx4 v101, s[28:29]
	s_add_u32 m0, s4, 0xc000
	s_nop 0
	global_load_lds_dwordx4 v98, s[48:49]
	s_add_u32 m0, s4, 0xc400
	s_nop 0
	global_load_lds_dwordx4 v99, s[48:49]
	s_add_u32 m0, s4, 0xc800
	s_nop 0
	global_load_lds_dwordx4 v100, s[48:49]
	s_add_u32 m0, s4, 0xcc00
	s_nop 0
	global_load_lds_dwordx4 v101, s[48:49]
	s_waitcnt lgkmcnt(8)
	v_mfma_f32_16x16x32_bf16 v[62:65], v[66:69], v[218:221], v[62:65]
	v_mfma_f32_16x16x32_bf16 v[46:49], v[66:69], v[222:225], v[46:49]
	v_mfma_f32_16x16x32_bf16 v[30:33], v[66:69], v[226:229], v[30:33]
	v_mfma_f32_16x16x32_bf16 v[14:17], v[66:69], v[230:233], v[14:17]
	v_mfma_f32_16x16x32_bf16 v[58:61], v[70:73], v[218:221], v[58:61]
	v_mfma_f32_16x16x32_bf16 v[42:45], v[70:73], v[222:225], v[42:45]
	v_mfma_f32_16x16x32_bf16 v[26:29], v[70:73], v[226:229], v[26:29]
	v_mfma_f32_16x16x32_bf16 v[10:13], v[70:73], v[230:233], v[10:13]
	v_mfma_f32_16x16x32_bf16 v[54:57], v[74:77], v[218:221], v[54:57]
	v_mfma_f32_16x16x32_bf16 v[38:41], v[74:77], v[222:225], v[38:41]
	v_mfma_f32_16x16x32_bf16 v[22:25], v[74:77], v[226:229], v[22:25]
	v_mfma_f32_16x16x32_bf16 v[6:9], v[74:77], v[230:233], v[6:9]
	v_mfma_f32_16x16x32_bf16 v[50:53], v[78:81], v[218:221], v[50:53]
	v_mfma_f32_16x16x32_bf16 v[34:37], v[78:81], v[222:225], v[34:37]
	v_mfma_f32_16x16x32_bf16 v[18:21], v[78:81], v[226:229], v[18:21]
	v_mfma_f32_16x16x32_bf16 v[2:5], v[78:81], v[230:233], v[2:5]
	s_waitcnt lgkmcnt(0)
	v_mfma_f32_16x16x32_bf16 v[62:65], v[82:85], v[234:237], v[62:65]
	v_mfma_f32_16x16x32_bf16 v[46:49], v[82:85], v[238:241], v[46:49]
	v_mfma_f32_16x16x32_bf16 v[30:33], v[82:85], v[242:245], v[30:33]
	v_mfma_f32_16x16x32_bf16 v[14:17], v[82:85], v[246:249], v[14:17]
	v_mfma_f32_16x16x32_bf16 v[58:61], v[86:89], v[234:237], v[58:61]
	v_mfma_f32_16x16x32_bf16 v[42:45], v[86:89], v[238:241], v[42:45]
	v_mfma_f32_16x16x32_bf16 v[26:29], v[86:89], v[242:245], v[26:29]
	v_mfma_f32_16x16x32_bf16 v[10:13], v[86:89], v[246:249], v[10:13]
	v_mfma_f32_16x16x32_bf16 v[54:57], v[90:93], v[234:237], v[54:57]
	v_mfma_f32_16x16x32_bf16 v[38:41], v[90:93], v[238:241], v[38:41]
	v_mfma_f32_16x16x32_bf16 v[22:25], v[90:93], v[242:245], v[22:25]
	v_mfma_f32_16x16x32_bf16 v[6:9], v[90:93], v[246:249], v[6:9]
	v_mfma_f32_16x16x32_bf16 v[50:53], v[94:97], v[234:237], v[50:53]
	v_mfma_f32_16x16x32_bf16 v[34:37], v[94:97], v[238:241], v[34:37]
	v_mfma_f32_16x16x32_bf16 v[18:21], v[94:97], v[242:245], v[18:21]
	v_mfma_f32_16x16x32_bf16 v[2:5], v[94:97], v[246:249], v[2:5]
	s_waitcnt vmcnt(8)
	s_barrier
	ds_read_b128 v[218:221], v102 offset:16384
	ds_read_b128 v[222:225], v102 offset:18432
	ds_read_b128 v[226:229], v102 offset:20480
	ds_read_b128 v[230:233], v102 offset:22528
	ds_read_b128 v[234:237], v103 offset:16384
	ds_read_b128 v[238:241], v103 offset:18432
	ds_read_b128 v[242:245], v103 offset:20480
	ds_read_b128 v[246:249], v103 offset:22528
	s_add_u32 m0, s4, 0x0
	s_nop 0
	global_load_lds_dwordx4 v98, s[6:7]
	s_add_u32 m0, s4, 0x400
	s_nop 0
	global_load_lds_dwordx4 v99, s[6:7]
	s_add_u32 m0, s4, 0x800
	s_nop 0
	global_load_lds_dwordx4 v100, s[6:7]
	s_add_u32 m0, s4, 0xc00
	s_nop 0
	global_load_lds_dwordx4 v101, s[6:7]
	v_add_u32_e32 v98, 0x80, v98
	v_add_u32_e32 v99, 0x80, v99
	v_add_u32_e32 v100, 0x80, v100
	v_add_u32_e32 v101, 0x80, v101
	s_waitcnt lgkmcnt(4)
	v_mfma_f32_16x16x32_bf16 v[106:109], v[66:69], v[218:221], v[106:109]
	v_mfma_f32_16x16x32_bf16 v[122:125], v[66:69], v[222:225], v[122:125]
	v_mfma_f32_16x16x32_bf16 v[138:141], v[66:69], v[226:229], v[138:141]
	v_mfma_f32_16x16x32_bf16 v[162:165], v[66:69], v[230:233], v[162:165]
	v_mfma_f32_16x16x32_bf16 v[110:113], v[70:73], v[218:221], v[110:113]
	v_mfma_f32_16x16x32_bf16 v[126:129], v[70:73], v[222:225], v[126:129]
	v_mfma_f32_16x16x32_bf16 v[142:145], v[70:73], v[226:229], v[142:145]
	v_mfma_f32_16x16x32_bf16 v[166:169], v[70:73], v[230:233], v[166:169]
	v_mfma_f32_16x16x32_bf16 v[114:117], v[74:77], v[218:221], v[114:117]
	v_mfma_f32_16x16x32_bf16 v[130:133], v[74:77], v[222:225], v[130:133]
	v_mfma_f32_16x16x32_bf16 v[154:157], v[74:77], v[226:229], v[154:157]
	v_mfma_f32_16x16x32_bf16 v[170:173], v[74:77], v[230:233], v[170:173]
	v_mfma_f32_16x16x32_bf16 v[118:121], v[78:81], v[218:221], v[118:121]
	v_mfma_f32_16x16x32_bf16 v[134:137], v[78:81], v[222:225], v[134:137]
	v_mfma_f32_16x16x32_bf16 v[158:161], v[78:81], v[226:229], v[158:161]
	v_mfma_f32_16x16x32_bf16 v[174:177], v[78:81], v[230:233], v[174:177]
	s_waitcnt lgkmcnt(0)
	v_mfma_f32_16x16x32_bf16 v[106:109], v[82:85], v[234:237], v[106:109]
	v_mfma_f32_16x16x32_bf16 v[122:125], v[82:85], v[238:241], v[122:125]
	v_mfma_f32_16x16x32_bf16 v[138:141], v[82:85], v[242:245], v[138:141]
	v_mfma_f32_16x16x32_bf16 v[162:165], v[82:85], v[246:249], v[162:165]
	v_mfma_f32_16x16x32_bf16 v[110:113], v[86:89], v[234:237], v[110:113]
	v_mfma_f32_16x16x32_bf16 v[126:129], v[86:89], v[238:241], v[126:129]
	v_mfma_f32_16x16x32_bf16 v[142:145], v[86:89], v[242:245], v[142:145]
	v_mfma_f32_16x16x32_bf16 v[166:169], v[86:89], v[246:249], v[166:169]
	v_mfma_f32_16x16x32_bf16 v[114:117], v[90:93], v[234:237], v[114:117]
	v_mfma_f32_16x16x32_bf16 v[130:133], v[90:93], v[238:241], v[130:133]
	v_mfma_f32_16x16x32_bf16 v[154:157], v[90:93], v[242:245], v[154:157]
	v_mfma_f32_16x16x32_bf16 v[170:173], v[90:93], v[246:249], v[170:173]
	v_mfma_f32_16x16x32_bf16 v[118:121], v[94:97], v[234:237], v[118:121]
	v_mfma_f32_16x16x32_bf16 v[134:137], v[94:97], v[238:241], v[134:137]
	v_mfma_f32_16x16x32_bf16 v[158:161], v[94:97], v[242:245], v[158:161]
	v_mfma_f32_16x16x32_bf16 v[174:177], v[94:97], v[246:249], v[174:177]
	s_waitcnt vmcnt(4)
	s_barrier
	ds_read_b128 v[218:221], v102 offset:32768
	ds_read_b128 v[222:225], v102 offset:34816
	ds_read_b128 v[226:229], v102 offset:36864
	ds_read_b128 v[230:233], v102 offset:38912
	ds_read_b128 v[66:69], v104 offset:49152
	ds_read_b128 v[70:73], v104 offset:51200
	ds_read_b128 v[74:77], v104 offset:53248
	ds_read_b128 v[78:81], v104 offset:55296
	ds_read_b128 v[234:237], v103 offset:32768
	ds_read_b128 v[238:241], v103 offset:34816
	ds_read_b128 v[242:245], v103 offset:36864
	ds_read_b128 v[246:249], v103 offset:38912
	ds_read_b128 v[82:85], v105 offset:49152
	ds_read_b128 v[86:89], v105 offset:51200
	ds_read_b128 v[90:93], v105 offset:53248
	ds_read_b128 v[94:97], v105 offset:55296
	s_add_u32 m0, s4, 0x4000
	s_nop 0
	global_load_lds_dwordx4 v98, s[28:29]
	s_add_u32 m0, s4, 0x4400
	s_nop 0
	global_load_lds_dwordx4 v99, s[28:29]
	s_add_u32 m0, s4, 0x4800
	s_nop 0
	global_load_lds_dwordx4 v100, s[28:29]
	s_add_u32 m0, s4, 0x4c00
	s_nop 0
	global_load_lds_dwordx4 v101, s[28:29]
	s_add_u32 m0, s4, 0x10000
	s_nop 0
	global_load_lds_dwordx4 v98, s[48:49]
	s_add_u32 m0, s4, 0x10400
	s_nop 0
	global_load_lds_dwordx4 v99, s[48:49]
	s_add_u32 m0, s4, 0x10800
	s_nop 0
	global_load_lds_dwordx4 v100, s[48:49]
	s_add_u32 m0, s4, 0x10c00
	s_nop 0
	global_load_lds_dwordx4 v101, s[48:49]
	s_waitcnt lgkmcnt(8)
	v_mfma_f32_16x16x32_bf16 v[62:65], v[66:69], v[218:221], v[62:65]
	v_mfma_f32_16x16x32_bf16 v[46:49], v[66:69], v[222:225], v[46:49]
	v_mfma_f32_16x16x32_bf16 v[30:33], v[66:69], v[226:229], v[30:33]
	v_mfma_f32_16x16x32_bf16 v[14:17], v[66:69], v[230:233], v[14:17]
	v_mfma_f32_16x16x32_bf16 v[58:61], v[70:73], v[218:221], v[58:61]
	v_mfma_f32_16x16x32_bf16 v[42:45], v[70:73], v[222:225], v[42:45]
	v_mfma_f32_16x16x32_bf16 v[26:29], v[70:73], v[226:229], v[26:29]
	v_mfma_f32_16x16x32_bf16 v[10:13], v[70:73], v[230:233], v[10:13]
	v_mfma_f32_16x16x32_bf16 v[54:57], v[74:77], v[218:221], v[54:57]
	v_mfma_f32_16x16x32_bf16 v[38:41], v[74:77], v[222:225], v[38:41]
	v_mfma_f32_16x16x32_bf16 v[22:25], v[74:77], v[226:229], v[22:25]
	v_mfma_f32_16x16x32_bf16 v[6:9], v[74:77], v[230:233], v[6:9]
	v_mfma_f32_16x16x32_bf16 v[50:53], v[78:81], v[218:221], v[50:53]
	v_mfma_f32_16x16x32_bf16 v[34:37], v[78:81], v[222:225], v[34:37]
	v_mfma_f32_16x16x32_bf16 v[18:21], v[78:81], v[226:229], v[18:21]
	v_mfma_f32_16x16x32_bf16 v[2:5], v[78:81], v[230:233], v[2:5]
	s_waitcnt lgkmcnt(0)
	v_mfma_f32_16x16x32_bf16 v[62:65], v[82:85], v[234:237], v[62:65]
	v_mfma_f32_16x16x32_bf16 v[46:49], v[82:85], v[238:241], v[46:49]
	v_mfma_f32_16x16x32_bf16 v[30:33], v[82:85], v[242:245], v[30:33]
	v_mfma_f32_16x16x32_bf16 v[14:17], v[82:85], v[246:249], v[14:17]
	v_mfma_f32_16x16x32_bf16 v[58:61], v[86:89], v[234:237], v[58:61]
	v_mfma_f32_16x16x32_bf16 v[42:45], v[86:89], v[238:241], v[42:45]
	v_mfma_f32_16x16x32_bf16 v[26:29], v[86:89], v[242:245], v[26:29]
	v_mfma_f32_16x16x32_bf16 v[10:13], v[86:89], v[246:249], v[10:13]
	v_mfma_f32_16x16x32_bf16 v[54:57], v[90:93], v[234:237], v[54:57]
	v_mfma_f32_16x16x32_bf16 v[38:41], v[90:93], v[238:241], v[38:41]
	v_mfma_f32_16x16x32_bf16 v[22:25], v[90:93], v[242:245], v[22:25]
	v_mfma_f32_16x16x32_bf16 v[6:9], v[90:93], v[246:249], v[6:9]
	v_mfma_f32_16x16x32_bf16 v[50:53], v[94:97], v[234:237], v[50:53]
	v_mfma_f32_16x16x32_bf16 v[34:37], v[94:97], v[238:241], v[34:37]
	v_mfma_f32_16x16x32_bf16 v[18:21], v[94:97], v[242:245], v[18:21]
	v_mfma_f32_16x16x32_bf16 v[2:5], v[94:97], v[246:249], v[2:5]
	s_waitcnt vmcnt(8)
	s_barrier
	ds_read_b128 v[218:221], v102 offset:0
	ds_read_b128 v[222:225], v102 offset:2048
	ds_read_b128 v[226:229], v102 offset:4096
	ds_read_b128 v[230:233], v102 offset:6144
	ds_read_b128 v[234:237], v103 offset:0
	ds_read_b128 v[238:241], v103 offset:2048
	ds_read_b128 v[242:245], v103 offset:4096
	ds_read_b128 v[246:249], v103 offset:6144
	s_add_u32 m0, s4, 0x8000
	s_nop 0
	global_load_lds_dwordx4 v98, s[6:7]
	s_add_u32 m0, s4, 0x8400
	s_nop 0
	global_load_lds_dwordx4 v99, s[6:7]
	s_add_u32 m0, s4, 0x8800
	s_nop 0
	global_load_lds_dwordx4 v100, s[6:7]
	s_add_u32 m0, s4, 0x8c00
	s_nop 0
	global_load_lds_dwordx4 v101, s[6:7]
	v_add_u32_e32 v98, 0x80, v98
	v_add_u32_e32 v99, 0x80, v99
	v_add_u32_e32 v100, 0x80, v100
	v_add_u32_e32 v101, 0x80, v101
	s_waitcnt lgkmcnt(4)
	v_mfma_f32_16x16x32_bf16 v[106:109], v[66:69], v[218:221], v[106:109]
	v_mfma_f32_16x16x32_bf16 v[122:125], v[66:69], v[222:225], v[122:125]
	v_mfma_f32_16x16x32_bf16 v[138:141], v[66:69], v[226:229], v[138:141]
	v_mfma_f32_16x16x32_bf16 v[162:165], v[66:69], v[230:233], v[162:165]
	v_mfma_f32_16x16x32_bf16 v[110:113], v[70:73], v[218:221], v[110:113]
	v_mfma_f32_16x16x32_bf16 v[126:129], v[70:73], v[222:225], v[126:129]
	v_mfma_f32_16x16x32_bf16 v[142:145], v[70:73], v[226:229], v[142:145]
	v_mfma_f32_16x16x32_bf16 v[166:169], v[70:73], v[230:233], v[166:169]
	v_mfma_f32_16x16x32_bf16 v[114:117], v[74:77], v[218:221], v[114:117]
	v_mfma_f32_16x16x32_bf16 v[130:133], v[74:77], v[222:225], v[130:133]
	v_mfma_f32_16x16x32_bf16 v[154:157], v[74:77], v[226:229], v[154:157]
	v_mfma_f32_16x16x32_bf16 v[170:173], v[74:77], v[230:233], v[170:173]
	v_mfma_f32_16x16x32_bf16 v[118:121], v[78:81], v[218:221], v[118:121]
	v_mfma_f32_16x16x32_bf16 v[134:137], v[78:81], v[222:225], v[134:137]
	v_mfma_f32_16x16x32_bf16 v[158:161], v[78:81], v[226:229], v[158:161]
	v_mfma_f32_16x16x32_bf16 v[174:177], v[78:81], v[230:233], v[174:177]
	s_waitcnt lgkmcnt(0)
	v_mfma_f32_16x16x32_bf16 v[106:109], v[82:85], v[234:237], v[106:109]
	v_mfma_f32_16x16x32_bf16 v[122:125], v[82:85], v[238:241], v[122:125]
	v_mfma_f32_16x16x32_bf16 v[138:141], v[82:85], v[242:245], v[138:141]
	v_mfma_f32_16x16x32_bf16 v[162:165], v[82:85], v[246:249], v[162:165]
	v_mfma_f32_16x16x32_bf16 v[110:113], v[86:89], v[234:237], v[110:113]
	v_mfma_f32_16x16x32_bf16 v[126:129], v[86:89], v[238:241], v[126:129]
	v_mfma_f32_16x16x32_bf16 v[142:145], v[86:89], v[242:245], v[142:145]
	v_mfma_f32_16x16x32_bf16 v[166:169], v[86:89], v[246:249], v[166:169]
	v_mfma_f32_16x16x32_bf16 v[114:117], v[90:93], v[234:237], v[114:117]
	v_mfma_f32_16x16x32_bf16 v[130:133], v[90:93], v[238:241], v[130:133]
	v_mfma_f32_16x16x32_bf16 v[154:157], v[90:93], v[242:245], v[154:157]
	v_mfma_f32_16x16x32_bf16 v[170:173], v[90:93], v[246:249], v[170:173]
	v_mfma_f32_16x16x32_bf16 v[118:121], v[94:97], v[234:237], v[118:121]
	v_mfma_f32_16x16x32_bf16 v[134:137], v[94:97], v[238:241], v[134:137]
	v_mfma_f32_16x16x32_bf16 v[158:161], v[94:97], v[242:245], v[158:161]
	v_mfma_f32_16x16x32_bf16 v[174:177], v[94:97], v[246:249], v[174:177]
	s_waitcnt vmcnt(4)
	s_barrier
	ds_read_b128 v[218:221], v102 offset:16384
	ds_read_b128 v[222:225], v102 offset:18432
	ds_read_b128 v[226:229], v102 offset:20480
	ds_read_b128 v[230:233], v102 offset:22528
	ds_read_b128 v[66:69], v250 offset:49152
	ds_read_b128 v[70:73], v250 offset:51200
	ds_read_b128 v[74:77], v250 offset:53248
	ds_read_b128 v[78:81], v250 offset:55296
	ds_read_b128 v[234:237], v103 offset:16384
	ds_read_b128 v[238:241], v103 offset:18432
	ds_read_b128 v[242:245], v103 offset:20480
	ds_read_b128 v[246:249], v103 offset:22528
	ds_read_b128 v[82:85], v251 offset:49152
	ds_read_b128 v[86:89], v251 offset:51200
	ds_read_b128 v[90:93], v251 offset:53248
	ds_read_b128 v[94:97], v251 offset:55296
	s_add_u32 m0, s4, 0x0
	s_nop 0
	global_load_lds_dwordx4 v98, s[28:29]
	s_add_u32 m0, s4, 0x400
	s_nop 0
	global_load_lds_dwordx4 v99, s[28:29]
	s_add_u32 m0, s4, 0x800
	s_nop 0
	global_load_lds_dwordx4 v100, s[28:29]
	s_add_u32 m0, s4, 0xc00
	s_nop 0
	global_load_lds_dwordx4 v101, s[28:29]
	s_add_u32 m0, s4, 0xc000
	s_nop 0
	global_load_lds_dwordx4 v98, s[48:49]
	s_add_u32 m0, s4, 0xc400
	s_nop 0
	global_load_lds_dwordx4 v99, s[48:49]
	s_add_u32 m0, s4, 0xc800
	s_nop 0
	global_load_lds_dwordx4 v100, s[48:49]
	s_add_u32 m0, s4, 0xcc00
	s_nop 0
	global_load_lds_dwordx4 v101, s[48:49]
	s_waitcnt lgkmcnt(8)
	v_mfma_f32_16x16x32_bf16 v[62:65], v[66:69], v[218:221], v[62:65]
	v_mfma_f32_16x16x32_bf16 v[46:49], v[66:69], v[222:225], v[46:49]
	v_mfma_f32_16x16x32_bf16 v[30:33], v[66:69], v[226:229], v[30:33]
	v_mfma_f32_16x16x32_bf16 v[14:17], v[66:69], v[230:233], v[14:17]
	v_mfma_f32_16x16x32_bf16 v[58:61], v[70:73], v[218:221], v[58:61]
	v_mfma_f32_16x16x32_bf16 v[42:45], v[70:73], v[222:225], v[42:45]
	v_mfma_f32_16x16x32_bf16 v[26:29], v[70:73], v[226:229], v[26:29]
	v_mfma_f32_16x16x32_bf16 v[10:13], v[70:73], v[230:233], v[10:13]
	v_mfma_f32_16x16x32_bf16 v[54:57], v[74:77], v[218:221], v[54:57]
	v_mfma_f32_16x16x32_bf16 v[38:41], v[74:77], v[222:225], v[38:41]
	v_mfma_f32_16x16x32_bf16 v[22:25], v[74:77], v[226:229], v[22:25]
	v_mfma_f32_16x16x32_bf16 v[6:9], v[74:77], v[230:233], v[6:9]
	v_mfma_f32_16x16x32_bf16 v[50:53], v[78:81], v[218:221], v[50:53]
	v_mfma_f32_16x16x32_bf16 v[34:37], v[78:81], v[222:225], v[34:37]
	v_mfma_f32_16x16x32_bf16 v[18:21], v[78:81], v[226:229], v[18:21]
	v_mfma_f32_16x16x32_bf16 v[2:5], v[78:81], v[230:233], v[2:5]
	s_waitcnt lgkmcnt(0)
	v_mfma_f32_16x16x32_bf16 v[62:65], v[82:85], v[234:237], v[62:65]
	v_mfma_f32_16x16x32_bf16 v[46:49], v[82:85], v[238:241], v[46:49]
	v_mfma_f32_16x16x32_bf16 v[30:33], v[82:85], v[242:245], v[30:33]
	v_mfma_f32_16x16x32_bf16 v[14:17], v[82:85], v[246:249], v[14:17]
	v_mfma_f32_16x16x32_bf16 v[58:61], v[86:89], v[234:237], v[58:61]
	v_mfma_f32_16x16x32_bf16 v[42:45], v[86:89], v[238:241], v[42:45]
	v_mfma_f32_16x16x32_bf16 v[26:29], v[86:89], v[242:245], v[26:29]
	v_mfma_f32_16x16x32_bf16 v[10:13], v[86:89], v[246:249], v[10:13]
	v_mfma_f32_16x16x32_bf16 v[54:57], v[90:93], v[234:237], v[54:57]
	v_mfma_f32_16x16x32_bf16 v[38:41], v[90:93], v[238:241], v[38:41]
	v_mfma_f32_16x16x32_bf16 v[22:25], v[90:93], v[242:245], v[22:25]
	v_mfma_f32_16x16x32_bf16 v[6:9], v[90:93], v[246:249], v[6:9]
	v_mfma_f32_16x16x32_bf16 v[50:53], v[94:97], v[234:237], v[50:53]
	v_mfma_f32_16x16x32_bf16 v[34:37], v[94:97], v[238:241], v[34:37]
	v_mfma_f32_16x16x32_bf16 v[18:21], v[94:97], v[242:245], v[18:21]
	v_mfma_f32_16x16x32_bf16 v[2:5], v[94:97], v[246:249], v[2:5]
	s_waitcnt vmcnt(8)
	s_barrier
	ds_read_b128 v[218:221], v102 offset:32768
	ds_read_b128 v[222:225], v102 offset:34816
	ds_read_b128 v[226:229], v102 offset:36864
	ds_read_b128 v[230:233], v102 offset:38912
	ds_read_b128 v[234:237], v103 offset:32768
	ds_read_b128 v[238:241], v103 offset:34816
	ds_read_b128 v[242:245], v103 offset:36864
	ds_read_b128 v[246:249], v103 offset:38912
	s_add_u32 m0, s4, 0x4000
	s_nop 0
	global_load_lds_dwordx4 v98, s[6:7]
	s_add_u32 m0, s4, 0x4400
	s_nop 0
	global_load_lds_dwordx4 v99, s[6:7]
	s_add_u32 m0, s4, 0x4800
	s_nop 0
	global_load_lds_dwordx4 v100, s[6:7]
	s_add_u32 m0, s4, 0x4c00
	s_nop 0
	global_load_lds_dwordx4 v101, s[6:7]
	v_add_u32_e32 v98, 0x80, v98
	v_add_u32_e32 v99, 0x80, v99
	v_add_u32_e32 v100, 0x80, v100
	v_add_u32_e32 v101, 0x80, v101
	s_waitcnt lgkmcnt(4)
	v_mfma_f32_16x16x32_bf16 v[106:109], v[66:69], v[218:221], v[106:109]
	v_mfma_f32_16x16x32_bf16 v[122:125], v[66:69], v[222:225], v[122:125]
	v_mfma_f32_16x16x32_bf16 v[138:141], v[66:69], v[226:229], v[138:141]
	v_mfma_f32_16x16x32_bf16 v[162:165], v[66:69], v[230:233], v[162:165]
	v_mfma_f32_16x16x32_bf16 v[110:113], v[70:73], v[218:221], v[110:113]
	v_mfma_f32_16x16x32_bf16 v[126:129], v[70:73], v[222:225], v[126:129]
	v_mfma_f32_16x16x32_bf16 v[142:145], v[70:73], v[226:229], v[142:145]
	v_mfma_f32_16x16x32_bf16 v[166:169], v[70:73], v[230:233], v[166:169]
	v_mfma_f32_16x16x32_bf16 v[114:117], v[74:77], v[218:221], v[114:117]
	v_mfma_f32_16x16x32_bf16 v[130:133], v[74:77], v[222:225], v[130:133]
	v_mfma_f32_16x16x32_bf16 v[154:157], v[74:77], v[226:229], v[154:157]
	v_mfma_f32_16x16x32_bf16 v[170:173], v[74:77], v[230:233], v[170:173]
	v_mfma_f32_16x16x32_bf16 v[118:121], v[78:81], v[218:221], v[118:121]
	v_mfma_f32_16x16x32_bf16 v[134:137], v[78:81], v[222:225], v[134:137]
	v_mfma_f32_16x16x32_bf16 v[158:161], v[78:81], v[226:229], v[158:161]
	v_mfma_f32_16x16x32_bf16 v[174:177], v[78:81], v[230:233], v[174:177]
	s_waitcnt lgkmcnt(0)
	v_mfma_f32_16x16x32_bf16 v[106:109], v[82:85], v[234:237], v[106:109]
	v_mfma_f32_16x16x32_bf16 v[122:125], v[82:85], v[238:241], v[122:125]
	v_mfma_f32_16x16x32_bf16 v[138:141], v[82:85], v[242:245], v[138:141]
	v_mfma_f32_16x16x32_bf16 v[162:165], v[82:85], v[246:249], v[162:165]
	v_mfma_f32_16x16x32_bf16 v[110:113], v[86:89], v[234:237], v[110:113]
	v_mfma_f32_16x16x32_bf16 v[126:129], v[86:89], v[238:241], v[126:129]
	v_mfma_f32_16x16x32_bf16 v[142:145], v[86:89], v[242:245], v[142:145]
	v_mfma_f32_16x16x32_bf16 v[166:169], v[86:89], v[246:249], v[166:169]
	v_mfma_f32_16x16x32_bf16 v[114:117], v[90:93], v[234:237], v[114:117]
	v_mfma_f32_16x16x32_bf16 v[130:133], v[90:93], v[238:241], v[130:133]
	v_mfma_f32_16x16x32_bf16 v[154:157], v[90:93], v[242:245], v[154:157]
	v_mfma_f32_16x16x32_bf16 v[170:173], v[90:93], v[246:249], v[170:173]
	v_mfma_f32_16x16x32_bf16 v[118:121], v[94:97], v[234:237], v[118:121]
	v_mfma_f32_16x16x32_bf16 v[134:137], v[94:97], v[238:241], v[134:137]
	v_mfma_f32_16x16x32_bf16 v[158:161], v[94:97], v[242:245], v[158:161]
	v_mfma_f32_16x16x32_bf16 v[174:177], v[94:97], v[246:249], v[174:177]
	s_waitcnt vmcnt(4)
	s_barrier
	ds_read_b128 v[218:221], v102 offset:0
	ds_read_b128 v[222:225], v102 offset:2048
	ds_read_b128 v[226:229], v102 offset:4096
	ds_read_b128 v[230:233], v102 offset:6144
	ds_read_b128 v[66:69], v104 offset:49152
	ds_read_b128 v[70:73], v104 offset:51200
	ds_read_b128 v[74:77], v104 offset:53248
	ds_read_b128 v[78:81], v104 offset:55296
	ds_read_b128 v[234:237], v103 offset:0
	ds_read_b128 v[238:241], v103 offset:2048
	ds_read_b128 v[242:245], v103 offset:4096
	ds_read_b128 v[246:249], v103 offset:6144
	ds_read_b128 v[82:85], v105 offset:49152
	ds_read_b128 v[86:89], v105 offset:51200
	ds_read_b128 v[90:93], v105 offset:53248
	ds_read_b128 v[94:97], v105 offset:55296
	s_add_u32 m0, s4, 0x8000
	s_nop 0
	global_load_lds_dwordx4 v98, s[28:29]
	s_add_u32 m0, s4, 0x8400
	s_nop 0
	global_load_lds_dwordx4 v99, s[28:29]
	s_add_u32 m0, s4, 0x8800
	s_nop 0
	global_load_lds_dwordx4 v100, s[28:29]
	s_add_u32 m0, s4, 0x8c00
	s_nop 0
	global_load_lds_dwordx4 v101, s[28:29]
	s_add_u32 m0, s4, 0x10000
	s_nop 0
	global_load_lds_dwordx4 v98, s[48:49]
	s_add_u32 m0, s4, 0x10400
	s_nop 0
	global_load_lds_dwordx4 v99, s[48:49]
	s_add_u32 m0, s4, 0x10800
	s_nop 0
	global_load_lds_dwordx4 v100, s[48:49]
	s_add_u32 m0, s4, 0x10c00
	s_nop 0
	global_load_lds_dwordx4 v101, s[48:49]
	s_waitcnt lgkmcnt(8)
	v_mfma_f32_16x16x32_bf16 v[62:65], v[66:69], v[218:221], v[62:65]
	v_mfma_f32_16x16x32_bf16 v[46:49], v[66:69], v[222:225], v[46:49]
	v_mfma_f32_16x16x32_bf16 v[30:33], v[66:69], v[226:229], v[30:33]
	v_mfma_f32_16x16x32_bf16 v[14:17], v[66:69], v[230:233], v[14:17]
	v_mfma_f32_16x16x32_bf16 v[58:61], v[70:73], v[218:221], v[58:61]
	v_mfma_f32_16x16x32_bf16 v[42:45], v[70:73], v[222:225], v[42:45]
	v_mfma_f32_16x16x32_bf16 v[26:29], v[70:73], v[226:229], v[26:29]
	v_mfma_f32_16x16x32_bf16 v[10:13], v[70:73], v[230:233], v[10:13]
	v_mfma_f32_16x16x32_bf16 v[54:57], v[74:77], v[218:221], v[54:57]
	v_mfma_f32_16x16x32_bf16 v[38:41], v[74:77], v[222:225], v[38:41]
	v_mfma_f32_16x16x32_bf16 v[22:25], v[74:77], v[226:229], v[22:25]
	v_mfma_f32_16x16x32_bf16 v[6:9], v[74:77], v[230:233], v[6:9]
	v_mfma_f32_16x16x32_bf16 v[50:53], v[78:81], v[218:221], v[50:53]
	v_mfma_f32_16x16x32_bf16 v[34:37], v[78:81], v[222:225], v[34:37]
	v_mfma_f32_16x16x32_bf16 v[18:21], v[78:81], v[226:229], v[18:21]
	v_mfma_f32_16x16x32_bf16 v[2:5], v[78:81], v[230:233], v[2:5]
	s_waitcnt lgkmcnt(0)
	v_mfma_f32_16x16x32_bf16 v[62:65], v[82:85], v[234:237], v[62:65]
	v_mfma_f32_16x16x32_bf16 v[46:49], v[82:85], v[238:241], v[46:49]
	v_mfma_f32_16x16x32_bf16 v[30:33], v[82:85], v[242:245], v[30:33]
	v_mfma_f32_16x16x32_bf16 v[14:17], v[82:85], v[246:249], v[14:17]
	v_mfma_f32_16x16x32_bf16 v[58:61], v[86:89], v[234:237], v[58:61]
	v_mfma_f32_16x16x32_bf16 v[42:45], v[86:89], v[238:241], v[42:45]
	v_mfma_f32_16x16x32_bf16 v[26:29], v[86:89], v[242:245], v[26:29]
	v_mfma_f32_16x16x32_bf16 v[10:13], v[86:89], v[246:249], v[10:13]
	v_mfma_f32_16x16x32_bf16 v[54:57], v[90:93], v[234:237], v[54:57]
	v_mfma_f32_16x16x32_bf16 v[38:41], v[90:93], v[238:241], v[38:41]
	v_mfma_f32_16x16x32_bf16 v[22:25], v[90:93], v[242:245], v[22:25]
	v_mfma_f32_16x16x32_bf16 v[6:9], v[90:93], v[246:249], v[6:9]
	v_mfma_f32_16x16x32_bf16 v[50:53], v[94:97], v[234:237], v[50:53]
	v_mfma_f32_16x16x32_bf16 v[34:37], v[94:97], v[238:241], v[34:37]
	v_mfma_f32_16x16x32_bf16 v[18:21], v[94:97], v[242:245], v[18:21]
	v_mfma_f32_16x16x32_bf16 v[2:5], v[94:97], v[246:249], v[2:5]
	s_waitcnt vmcnt(8)
	s_barrier
	ds_read_b128 v[218:221], v102 offset:16384
	ds_read_b128 v[222:225], v102 offset:18432
	ds_read_b128 v[226:229], v102 offset:20480
	ds_read_b128 v[230:233], v102 offset:22528
	ds_read_b128 v[234:237], v103 offset:16384
	ds_read_b128 v[238:241], v103 offset:18432
	ds_read_b128 v[242:245], v103 offset:20480
	ds_read_b128 v[246:249], v103 offset:22528
	s_add_u32 m0, s4, 0x0
	s_nop 0
	global_load_lds_dwordx4 v98, s[6:7]
	s_add_u32 m0, s4, 0x400
	s_nop 0
	global_load_lds_dwordx4 v99, s[6:7]
	s_add_u32 m0, s4, 0x800
	s_nop 0
	global_load_lds_dwordx4 v100, s[6:7]
	s_add_u32 m0, s4, 0xc00
	s_nop 0
	global_load_lds_dwordx4 v101, s[6:7]
	v_add_u32_e32 v98, 0x80, v98
	v_add_u32_e32 v99, 0x80, v99
	v_add_u32_e32 v100, 0x80, v100
	v_add_u32_e32 v101, 0x80, v101
	s_waitcnt lgkmcnt(4)
	v_mfma_f32_16x16x32_bf16 v[106:109], v[66:69], v[218:221], v[106:109]
	v_mfma_f32_16x16x32_bf16 v[122:125], v[66:69], v[222:225], v[122:125]
	v_mfma_f32_16x16x32_bf16 v[138:141], v[66:69], v[226:229], v[138:141]
	v_mfma_f32_16x16x32_bf16 v[162:165], v[66:69], v[230:233], v[162:165]
	v_mfma_f32_16x16x32_bf16 v[110:113], v[70:73], v[218:221], v[110:113]
	v_mfma_f32_16x16x32_bf16 v[126:129], v[70:73], v[222:225], v[126:129]
	v_mfma_f32_16x16x32_bf16 v[142:145], v[70:73], v[226:229], v[142:145]
	v_mfma_f32_16x16x32_bf16 v[166:169], v[70:73], v[230:233], v[166:169]
	v_mfma_f32_16x16x32_bf16 v[114:117], v[74:77], v[218:221], v[114:117]
	v_mfma_f32_16x16x32_bf16 v[130:133], v[74:77], v[222:225], v[130:133]
	v_mfma_f32_16x16x32_bf16 v[154:157], v[74:77], v[226:229], v[154:157]
	v_mfma_f32_16x16x32_bf16 v[170:173], v[74:77], v[230:233], v[170:173]
	v_mfma_f32_16x16x32_bf16 v[118:121], v[78:81], v[218:221], v[118:121]
	v_mfma_f32_16x16x32_bf16 v[134:137], v[78:81], v[222:225], v[134:137]
	v_mfma_f32_16x16x32_bf16 v[158:161], v[78:81], v[226:229], v[158:161]
	v_mfma_f32_16x16x32_bf16 v[174:177], v[78:81], v[230:233], v[174:177]
	s_waitcnt lgkmcnt(0)
	v_mfma_f32_16x16x32_bf16 v[106:109], v[82:85], v[234:237], v[106:109]
	v_mfma_f32_16x16x32_bf16 v[122:125], v[82:85], v[238:241], v[122:125]
	v_mfma_f32_16x16x32_bf16 v[138:141], v[82:85], v[242:245], v[138:141]
	v_mfma_f32_16x16x32_bf16 v[162:165], v[82:85], v[246:249], v[162:165]
	v_mfma_f32_16x16x32_bf16 v[110:113], v[86:89], v[234:237], v[110:113]
	v_mfma_f32_16x16x32_bf16 v[126:129], v[86:89], v[238:241], v[126:129]
	v_mfma_f32_16x16x32_bf16 v[142:145], v[86:89], v[242:245], v[142:145]
	v_mfma_f32_16x16x32_bf16 v[166:169], v[86:89], v[246:249], v[166:169]
	v_mfma_f32_16x16x32_bf16 v[114:117], v[90:93], v[234:237], v[114:117]
	v_mfma_f32_16x16x32_bf16 v[130:133], v[90:93], v[238:241], v[130:133]
	v_mfma_f32_16x16x32_bf16 v[154:157], v[90:93], v[242:245], v[154:157]
	v_mfma_f32_16x16x32_bf16 v[170:173], v[90:93], v[246:249], v[170:173]
	v_mfma_f32_16x16x32_bf16 v[118:121], v[94:97], v[234:237], v[118:121]
	v_mfma_f32_16x16x32_bf16 v[134:137], v[94:97], v[238:241], v[134:137]
	v_mfma_f32_16x16x32_bf16 v[158:161], v[94:97], v[242:245], v[158:161]
	v_mfma_f32_16x16x32_bf16 v[174:177], v[94:97], v[246:249], v[174:177]
	s_waitcnt vmcnt(4)
	s_barrier
	ds_read_b128 v[218:221], v102 offset:32768
	ds_read_b128 v[222:225], v102 offset:34816
	ds_read_b128 v[226:229], v102 offset:36864
	ds_read_b128 v[230:233], v102 offset:38912
	ds_read_b128 v[66:69], v250 offset:49152
	ds_read_b128 v[70:73], v250 offset:51200
	ds_read_b128 v[74:77], v250 offset:53248
	ds_read_b128 v[78:81], v250 offset:55296
	ds_read_b128 v[234:237], v103 offset:32768
	ds_read_b128 v[238:241], v103 offset:34816
	ds_read_b128 v[242:245], v103 offset:36864
	ds_read_b128 v[246:249], v103 offset:38912
	ds_read_b128 v[82:85], v251 offset:49152
	ds_read_b128 v[86:89], v251 offset:51200
	ds_read_b128 v[90:93], v251 offset:53248
	ds_read_b128 v[94:97], v251 offset:55296
	s_add_u32 m0, s4, 0x4000
	s_nop 0
	global_load_lds_dwordx4 v98, s[28:29]
	s_add_u32 m0, s4, 0x4400
	s_nop 0
	global_load_lds_dwordx4 v99, s[28:29]
	s_add_u32 m0, s4, 0x4800
	s_nop 0
	global_load_lds_dwordx4 v100, s[28:29]
	s_add_u32 m0, s4, 0x4c00
	s_nop 0
	global_load_lds_dwordx4 v101, s[28:29]
	s_add_u32 m0, s4, 0xc000
	s_nop 0
	global_load_lds_dwordx4 v98, s[48:49]
	s_add_u32 m0, s4, 0xc400
	s_nop 0
	global_load_lds_dwordx4 v99, s[48:49]
	s_add_u32 m0, s4, 0xc800
	s_nop 0
	global_load_lds_dwordx4 v100, s[48:49]
	s_add_u32 m0, s4, 0xcc00
	s_nop 0
	global_load_lds_dwordx4 v101, s[48:49]
	s_waitcnt lgkmcnt(8)
	v_mfma_f32_16x16x32_bf16 v[62:65], v[66:69], v[218:221], v[62:65]
	v_mfma_f32_16x16x32_bf16 v[46:49], v[66:69], v[222:225], v[46:49]
	v_mfma_f32_16x16x32_bf16 v[30:33], v[66:69], v[226:229], v[30:33]
	v_mfma_f32_16x16x32_bf16 v[14:17], v[66:69], v[230:233], v[14:17]
	v_mfma_f32_16x16x32_bf16 v[58:61], v[70:73], v[218:221], v[58:61]
	v_mfma_f32_16x16x32_bf16 v[42:45], v[70:73], v[222:225], v[42:45]
	v_mfma_f32_16x16x32_bf16 v[26:29], v[70:73], v[226:229], v[26:29]
	v_mfma_f32_16x16x32_bf16 v[10:13], v[70:73], v[230:233], v[10:13]
	v_mfma_f32_16x16x32_bf16 v[54:57], v[74:77], v[218:221], v[54:57]
	v_mfma_f32_16x16x32_bf16 v[38:41], v[74:77], v[222:225], v[38:41]
	v_mfma_f32_16x16x32_bf16 v[22:25], v[74:77], v[226:229], v[22:25]
	v_mfma_f32_16x16x32_bf16 v[6:9], v[74:77], v[230:233], v[6:9]
	v_mfma_f32_16x16x32_bf16 v[50:53], v[78:81], v[218:221], v[50:53]
	v_mfma_f32_16x16x32_bf16 v[34:37], v[78:81], v[222:225], v[34:37]
	v_mfma_f32_16x16x32_bf16 v[18:21], v[78:81], v[226:229], v[18:21]
	v_mfma_f32_16x16x32_bf16 v[2:5], v[78:81], v[230:233], v[2:5]
	s_waitcnt lgkmcnt(0)
	v_mfma_f32_16x16x32_bf16 v[62:65], v[82:85], v[234:237], v[62:65]
	v_mfma_f32_16x16x32_bf16 v[46:49], v[82:85], v[238:241], v[46:49]
	v_mfma_f32_16x16x32_bf16 v[30:33], v[82:85], v[242:245], v[30:33]
	v_mfma_f32_16x16x32_bf16 v[14:17], v[82:85], v[246:249], v[14:17]
	v_mfma_f32_16x16x32_bf16 v[58:61], v[86:89], v[234:237], v[58:61]
	v_mfma_f32_16x16x32_bf16 v[42:45], v[86:89], v[238:241], v[42:45]
	v_mfma_f32_16x16x32_bf16 v[26:29], v[86:89], v[242:245], v[26:29]
	v_mfma_f32_16x16x32_bf16 v[10:13], v[86:89], v[246:249], v[10:13]
	v_mfma_f32_16x16x32_bf16 v[54:57], v[90:93], v[234:237], v[54:57]
	v_mfma_f32_16x16x32_bf16 v[38:41], v[90:93], v[238:241], v[38:41]
	v_mfma_f32_16x16x32_bf16 v[22:25], v[90:93], v[242:245], v[22:25]
	v_mfma_f32_16x16x32_bf16 v[6:9], v[90:93], v[246:249], v[6:9]
	v_mfma_f32_16x16x32_bf16 v[50:53], v[94:97], v[234:237], v[50:53]
	v_mfma_f32_16x16x32_bf16 v[34:37], v[94:97], v[238:241], v[34:37]
	v_mfma_f32_16x16x32_bf16 v[18:21], v[94:97], v[242:245], v[18:21]
	v_mfma_f32_16x16x32_bf16 v[2:5], v[94:97], v[246:249], v[2:5]
	s_waitcnt vmcnt(8)
	s_barrier
	ds_read_b128 v[218:221], v102 offset:0
	ds_read_b128 v[222:225], v102 offset:2048
	ds_read_b128 v[226:229], v102 offset:4096
	ds_read_b128 v[230:233], v102 offset:6144
	ds_read_b128 v[234:237], v103 offset:0
	ds_read_b128 v[238:241], v103 offset:2048
	ds_read_b128 v[242:245], v103 offset:4096
	ds_read_b128 v[246:249], v103 offset:6144
	s_add_u32 m0, s4, 0x8000
	s_nop 0
	global_load_lds_dwordx4 v98, s[6:7]
	s_add_u32 m0, s4, 0x8400
	s_nop 0
	global_load_lds_dwordx4 v99, s[6:7]
	s_add_u32 m0, s4, 0x8800
	s_nop 0
	global_load_lds_dwordx4 v100, s[6:7]
	s_add_u32 m0, s4, 0x8c00
	s_nop 0
	global_load_lds_dwordx4 v101, s[6:7]
	v_add_u32_e32 v98, 0x80, v98
	v_add_u32_e32 v99, 0x80, v99
	v_add_u32_e32 v100, 0x80, v100
	v_add_u32_e32 v101, 0x80, v101
	s_waitcnt lgkmcnt(4)
	v_mfma_f32_16x16x32_bf16 v[106:109], v[66:69], v[218:221], v[106:109]
	v_mfma_f32_16x16x32_bf16 v[122:125], v[66:69], v[222:225], v[122:125]
	v_mfma_f32_16x16x32_bf16 v[138:141], v[66:69], v[226:229], v[138:141]
	v_mfma_f32_16x16x32_bf16 v[162:165], v[66:69], v[230:233], v[162:165]
	v_mfma_f32_16x16x32_bf16 v[110:113], v[70:73], v[218:221], v[110:113]
	v_mfma_f32_16x16x32_bf16 v[126:129], v[70:73], v[222:225], v[126:129]
	v_mfma_f32_16x16x32_bf16 v[142:145], v[70:73], v[226:229], v[142:145]
	v_mfma_f32_16x16x32_bf16 v[166:169], v[70:73], v[230:233], v[166:169]
	v_mfma_f32_16x16x32_bf16 v[114:117], v[74:77], v[218:221], v[114:117]
	v_mfma_f32_16x16x32_bf16 v[130:133], v[74:77], v[222:225], v[130:133]
	v_mfma_f32_16x16x32_bf16 v[154:157], v[74:77], v[226:229], v[154:157]
	v_mfma_f32_16x16x32_bf16 v[170:173], v[74:77], v[230:233], v[170:173]
	v_mfma_f32_16x16x32_bf16 v[118:121], v[78:81], v[218:221], v[118:121]
	v_mfma_f32_16x16x32_bf16 v[134:137], v[78:81], v[222:225], v[134:137]
	v_mfma_f32_16x16x32_bf16 v[158:161], v[78:81], v[226:229], v[158:161]
	v_mfma_f32_16x16x32_bf16 v[174:177], v[78:81], v[230:233], v[174:177]
	s_waitcnt lgkmcnt(0)
	v_mfma_f32_16x16x32_bf16 v[106:109], v[82:85], v[234:237], v[106:109]
	v_mfma_f32_16x16x32_bf16 v[122:125], v[82:85], v[238:241], v[122:125]
	v_mfma_f32_16x16x32_bf16 v[138:141], v[82:85], v[242:245], v[138:141]
	v_mfma_f32_16x16x32_bf16 v[162:165], v[82:85], v[246:249], v[162:165]
	v_mfma_f32_16x16x32_bf16 v[110:113], v[86:89], v[234:237], v[110:113]
	v_mfma_f32_16x16x32_bf16 v[126:129], v[86:89], v[238:241], v[126:129]
	v_mfma_f32_16x16x32_bf16 v[142:145], v[86:89], v[242:245], v[142:145]
	v_mfma_f32_16x16x32_bf16 v[166:169], v[86:89], v[246:249], v[166:169]
	v_mfma_f32_16x16x32_bf16 v[114:117], v[90:93], v[234:237], v[114:117]
	v_mfma_f32_16x16x32_bf16 v[130:133], v[90:93], v[238:241], v[130:133]
	v_mfma_f32_16x16x32_bf16 v[154:157], v[90:93], v[242:245], v[154:157]
	v_mfma_f32_16x16x32_bf16 v[170:173], v[90:93], v[246:249], v[170:173]
	v_mfma_f32_16x16x32_bf16 v[118:121], v[94:97], v[234:237], v[118:121]
	v_mfma_f32_16x16x32_bf16 v[134:137], v[94:97], v[238:241], v[134:137]
	v_mfma_f32_16x16x32_bf16 v[158:161], v[94:97], v[242:245], v[158:161]
	v_mfma_f32_16x16x32_bf16 v[174:177], v[94:97], v[246:249], v[174:177]
	s_waitcnt vmcnt(4)
	s_barrier
	ds_read_b128 v[218:221], v102 offset:16384
	ds_read_b128 v[222:225], v102 offset:18432
	ds_read_b128 v[226:229], v102 offset:20480
	ds_read_b128 v[230:233], v102 offset:22528
	ds_read_b128 v[66:69], v104 offset:49152
	ds_read_b128 v[70:73], v104 offset:51200
	ds_read_b128 v[74:77], v104 offset:53248
	ds_read_b128 v[78:81], v104 offset:55296
	ds_read_b128 v[234:237], v103 offset:16384
	ds_read_b128 v[238:241], v103 offset:18432
	ds_read_b128 v[242:245], v103 offset:20480
	ds_read_b128 v[246:249], v103 offset:22528
	ds_read_b128 v[82:85], v105 offset:49152
	ds_read_b128 v[86:89], v105 offset:51200
	ds_read_b128 v[90:93], v105 offset:53248
	ds_read_b128 v[94:97], v105 offset:55296
	s_add_u32 m0, s4, 0x0
	s_nop 0
	global_load_lds_dwordx4 v98, s[28:29]
	s_add_u32 m0, s4, 0x400
	s_nop 0
	global_load_lds_dwordx4 v99, s[28:29]
	s_add_u32 m0, s4, 0x800
	s_nop 0
	global_load_lds_dwordx4 v100, s[28:29]
	s_add_u32 m0, s4, 0xc00
	s_nop 0
	global_load_lds_dwordx4 v101, s[28:29]
	s_add_u32 m0, s4, 0x10000
	s_nop 0
	global_load_lds_dwordx4 v98, s[48:49]
	s_add_u32 m0, s4, 0x10400
	s_nop 0
	global_load_lds_dwordx4 v99, s[48:49]
	s_add_u32 m0, s4, 0x10800
	s_nop 0
	global_load_lds_dwordx4 v100, s[48:49]
	s_add_u32 m0, s4, 0x10c00
	s_nop 0
	global_load_lds_dwordx4 v101, s[48:49]
	s_waitcnt lgkmcnt(8)
	v_mfma_f32_16x16x32_bf16 v[62:65], v[66:69], v[218:221], v[62:65]
	v_mfma_f32_16x16x32_bf16 v[46:49], v[66:69], v[222:225], v[46:49]
	v_mfma_f32_16x16x32_bf16 v[30:33], v[66:69], v[226:229], v[30:33]
	v_mfma_f32_16x16x32_bf16 v[14:17], v[66:69], v[230:233], v[14:17]
	v_mfma_f32_16x16x32_bf16 v[58:61], v[70:73], v[218:221], v[58:61]
	v_mfma_f32_16x16x32_bf16 v[42:45], v[70:73], v[222:225], v[42:45]
	v_mfma_f32_16x16x32_bf16 v[26:29], v[70:73], v[226:229], v[26:29]
	v_mfma_f32_16x16x32_bf16 v[10:13], v[70:73], v[230:233], v[10:13]
	v_mfma_f32_16x16x32_bf16 v[54:57], v[74:77], v[218:221], v[54:57]
	v_mfma_f32_16x16x32_bf16 v[38:41], v[74:77], v[222:225], v[38:41]
	v_mfma_f32_16x16x32_bf16 v[22:25], v[74:77], v[226:229], v[22:25]
	v_mfma_f32_16x16x32_bf16 v[6:9], v[74:77], v[230:233], v[6:9]
	v_mfma_f32_16x16x32_bf16 v[50:53], v[78:81], v[218:221], v[50:53]
	v_mfma_f32_16x16x32_bf16 v[34:37], v[78:81], v[222:225], v[34:37]
	v_mfma_f32_16x16x32_bf16 v[18:21], v[78:81], v[226:229], v[18:21]
	v_mfma_f32_16x16x32_bf16 v[2:5], v[78:81], v[230:233], v[2:5]
	s_waitcnt lgkmcnt(0)
	v_mfma_f32_16x16x32_bf16 v[62:65], v[82:85], v[234:237], v[62:65]
	v_mfma_f32_16x16x32_bf16 v[46:49], v[82:85], v[238:241], v[46:49]
	v_mfma_f32_16x16x32_bf16 v[30:33], v[82:85], v[242:245], v[30:33]
	v_mfma_f32_16x16x32_bf16 v[14:17], v[82:85], v[246:249], v[14:17]
	v_mfma_f32_16x16x32_bf16 v[58:61], v[86:89], v[234:237], v[58:61]
	v_mfma_f32_16x16x32_bf16 v[42:45], v[86:89], v[238:241], v[42:45]
	v_mfma_f32_16x16x32_bf16 v[26:29], v[86:89], v[242:245], v[26:29]
	v_mfma_f32_16x16x32_bf16 v[10:13], v[86:89], v[246:249], v[10:13]
	v_mfma_f32_16x16x32_bf16 v[54:57], v[90:93], v[234:237], v[54:57]
	v_mfma_f32_16x16x32_bf16 v[38:41], v[90:93], v[238:241], v[38:41]
	v_mfma_f32_16x16x32_bf16 v[22:25], v[90:93], v[242:245], v[22:25]
	v_mfma_f32_16x16x32_bf16 v[6:9], v[90:93], v[246:249], v[6:9]
	v_mfma_f32_16x16x32_bf16 v[50:53], v[94:97], v[234:237], v[50:53]
	v_mfma_f32_16x16x32_bf16 v[34:37], v[94:97], v[238:241], v[34:37]
	v_mfma_f32_16x16x32_bf16 v[18:21], v[94:97], v[242:245], v[18:21]
	v_mfma_f32_16x16x32_bf16 v[2:5], v[94:97], v[246:249], v[2:5]
	s_waitcnt vmcnt(8)
	s_barrier
	ds_read_b128 v[218:221], v102 offset:32768
	ds_read_b128 v[222:225], v102 offset:34816
	ds_read_b128 v[226:229], v102 offset:36864
	ds_read_b128 v[230:233], v102 offset:38912
	ds_read_b128 v[234:237], v103 offset:32768
	ds_read_b128 v[238:241], v103 offset:34816
	ds_read_b128 v[242:245], v103 offset:36864
	ds_read_b128 v[246:249], v103 offset:38912
	s_add_u32 m0, s4, 0x4000
	s_nop 0
	global_load_lds_dwordx4 v98, s[6:7]
	s_add_u32 m0, s4, 0x4400
	s_nop 0
	global_load_lds_dwordx4 v99, s[6:7]
	s_add_u32 m0, s4, 0x4800
	s_nop 0
	global_load_lds_dwordx4 v100, s[6:7]
	s_add_u32 m0, s4, 0x4c00
	s_nop 0
	global_load_lds_dwordx4 v101, s[6:7]
	v_add_u32_e32 v98, 0x80, v98
	v_add_u32_e32 v99, 0x80, v99
	v_add_u32_e32 v100, 0x80, v100
	v_add_u32_e32 v101, 0x80, v101
	s_waitcnt lgkmcnt(4)
	v_mfma_f32_16x16x32_bf16 v[106:109], v[66:69], v[218:221], v[106:109]
	v_mfma_f32_16x16x32_bf16 v[122:125], v[66:69], v[222:225], v[122:125]
	v_mfma_f32_16x16x32_bf16 v[138:141], v[66:69], v[226:229], v[138:141]
	v_mfma_f32_16x16x32_bf16 v[162:165], v[66:69], v[230:233], v[162:165]
	v_mfma_f32_16x16x32_bf16 v[110:113], v[70:73], v[218:221], v[110:113]
	v_mfma_f32_16x16x32_bf16 v[126:129], v[70:73], v[222:225], v[126:129]
	v_mfma_f32_16x16x32_bf16 v[142:145], v[70:73], v[226:229], v[142:145]
	v_mfma_f32_16x16x32_bf16 v[166:169], v[70:73], v[230:233], v[166:169]
	v_mfma_f32_16x16x32_bf16 v[114:117], v[74:77], v[218:221], v[114:117]
	v_mfma_f32_16x16x32_bf16 v[130:133], v[74:77], v[222:225], v[130:133]
	v_mfma_f32_16x16x32_bf16 v[154:157], v[74:77], v[226:229], v[154:157]
	v_mfma_f32_16x16x32_bf16 v[170:173], v[74:77], v[230:233], v[170:173]
	v_mfma_f32_16x16x32_bf16 v[118:121], v[78:81], v[218:221], v[118:121]
	v_mfma_f32_16x16x32_bf16 v[134:137], v[78:81], v[222:225], v[134:137]
	v_mfma_f32_16x16x32_bf16 v[158:161], v[78:81], v[226:229], v[158:161]
	v_mfma_f32_16x16x32_bf16 v[174:177], v[78:81], v[230:233], v[174:177]
	s_waitcnt lgkmcnt(0)
	v_mfma_f32_16x16x32_bf16 v[106:109], v[82:85], v[234:237], v[106:109]
	v_mfma_f32_16x16x32_bf16 v[122:125], v[82:85], v[238:241], v[122:125]
	v_mfma_f32_16x16x32_bf16 v[138:141], v[82:85], v[242:245], v[138:141]
	v_mfma_f32_16x16x32_bf16 v[162:165], v[82:85], v[246:249], v[162:165]
	v_mfma_f32_16x16x32_bf16 v[110:113], v[86:89], v[234:237], v[110:113]
	v_mfma_f32_16x16x32_bf16 v[126:129], v[86:89], v[238:241], v[126:129]
	v_mfma_f32_16x16x32_bf16 v[142:145], v[86:89], v[242:245], v[142:145]
	v_mfma_f32_16x16x32_bf16 v[166:169], v[86:89], v[246:249], v[166:169]
	v_mfma_f32_16x16x32_bf16 v[114:117], v[90:93], v[234:237], v[114:117]
	v_mfma_f32_16x16x32_bf16 v[130:133], v[90:93], v[238:241], v[130:133]
	v_mfma_f32_16x16x32_bf16 v[154:157], v[90:93], v[242:245], v[154:157]
	v_mfma_f32_16x16x32_bf16 v[170:173], v[90:93], v[246:249], v[170:173]
	v_mfma_f32_16x16x32_bf16 v[118:121], v[94:97], v[234:237], v[118:121]
	v_mfma_f32_16x16x32_bf16 v[134:137], v[94:97], v[238:241], v[134:137]
	v_mfma_f32_16x16x32_bf16 v[158:161], v[94:97], v[242:245], v[158:161]
	v_mfma_f32_16x16x32_bf16 v[174:177], v[94:97], v[246:249], v[174:177]
	s_waitcnt vmcnt(4)
	s_barrier
	ds_read_b128 v[218:221], v102 offset:0
	ds_read_b128 v[222:225], v102 offset:2048
	ds_read_b128 v[226:229], v102 offset:4096
	ds_read_b128 v[230:233], v102 offset:6144
	ds_read_b128 v[66:69], v250 offset:49152
	ds_read_b128 v[70:73], v250 offset:51200
	ds_read_b128 v[74:77], v250 offset:53248
	ds_read_b128 v[78:81], v250 offset:55296
	ds_read_b128 v[234:237], v103 offset:0
	ds_read_b128 v[238:241], v103 offset:2048
	ds_read_b128 v[242:245], v103 offset:4096
	ds_read_b128 v[246:249], v103 offset:6144
	ds_read_b128 v[82:85], v251 offset:49152
	ds_read_b128 v[86:89], v251 offset:51200
	ds_read_b128 v[90:93], v251 offset:53248
	ds_read_b128 v[94:97], v251 offset:55296
	s_waitcnt lgkmcnt(8)
	v_mfma_f32_16x16x32_bf16 v[62:65], v[66:69], v[218:221], v[62:65]
	v_mfma_f32_16x16x32_bf16 v[46:49], v[66:69], v[222:225], v[46:49]
	v_mfma_f32_16x16x32_bf16 v[30:33], v[66:69], v[226:229], v[30:33]
	v_mfma_f32_16x16x32_bf16 v[14:17], v[66:69], v[230:233], v[14:17]
	v_mfma_f32_16x16x32_bf16 v[58:61], v[70:73], v[218:221], v[58:61]
	v_mfma_f32_16x16x32_bf16 v[42:45], v[70:73], v[222:225], v[42:45]
	v_mfma_f32_16x16x32_bf16 v[26:29], v[70:73], v[226:229], v[26:29]
	v_mfma_f32_16x16x32_bf16 v[10:13], v[70:73], v[230:233], v[10:13]
	v_mfma_f32_16x16x32_bf16 v[54:57], v[74:77], v[218:221], v[54:57]
	v_mfma_f32_16x16x32_bf16 v[38:41], v[74:77], v[222:225], v[38:41]
	v_mfma_f32_16x16x32_bf16 v[22:25], v[74:77], v[226:229], v[22:25]
	v_mfma_f32_16x16x32_bf16 v[6:9], v[74:77], v[230:233], v[6:9]
	v_mfma_f32_16x16x32_bf16 v[50:53], v[78:81], v[218:221], v[50:53]
	v_mfma_f32_16x16x32_bf16 v[34:37], v[78:81], v[222:225], v[34:37]
	v_mfma_f32_16x16x32_bf16 v[18:21], v[78:81], v[226:229], v[18:21]
	v_mfma_f32_16x16x32_bf16 v[2:5], v[78:81], v[230:233], v[2:5]
	s_waitcnt lgkmcnt(0)
	v_mfma_f32_16x16x32_bf16 v[62:65], v[82:85], v[234:237], v[62:65]
	v_mfma_f32_16x16x32_bf16 v[46:49], v[82:85], v[238:241], v[46:49]
	v_mfma_f32_16x16x32_bf16 v[30:33], v[82:85], v[242:245], v[30:33]
	v_mfma_f32_16x16x32_bf16 v[14:17], v[82:85], v[246:249], v[14:17]
	v_mfma_f32_16x16x32_bf16 v[58:61], v[86:89], v[234:237], v[58:61]
	v_mfma_f32_16x16x32_bf16 v[42:45], v[86:89], v[238:241], v[42:45]
	v_mfma_f32_16x16x32_bf16 v[26:29], v[86:89], v[242:245], v[26:29]
	v_mfma_f32_16x16x32_bf16 v[10:13], v[86:89], v[246:249], v[10:13]
	v_mfma_f32_16x16x32_bf16 v[54:57], v[90:93], v[234:237], v[54:57]
	v_mfma_f32_16x16x32_bf16 v[38:41], v[90:93], v[238:241], v[38:41]
	v_mfma_f32_16x16x32_bf16 v[22:25], v[90:93], v[242:245], v[22:25]
	v_mfma_f32_16x16x32_bf16 v[6:9], v[90:93], v[246:249], v[6:9]
	v_mfma_f32_16x16x32_bf16 v[50:53], v[94:97], v[234:237], v[50:53]
	v_mfma_f32_16x16x32_bf16 v[34:37], v[94:97], v[238:241], v[34:37]
	v_mfma_f32_16x16x32_bf16 v[18:21], v[94:97], v[242:245], v[18:21]
	v_mfma_f32_16x16x32_bf16 v[2:5], v[94:97], v[246:249], v[2:5]
	s_waitcnt vmcnt(0)
	s_barrier
	ds_read_b128 v[218:221], v102 offset:16384
	ds_read_b128 v[222:225], v102 offset:18432
	ds_read_b128 v[226:229], v102 offset:20480
	ds_read_b128 v[230:233], v102 offset:22528
	ds_read_b128 v[234:237], v103 offset:16384
	ds_read_b128 v[238:241], v103 offset:18432
	ds_read_b128 v[242:245], v103 offset:20480
	ds_read_b128 v[246:249], v103 offset:22528
	s_waitcnt lgkmcnt(4)
	v_mfma_f32_16x16x32_bf16 v[106:109], v[66:69], v[218:221], v[106:109]
	v_mfma_f32_16x16x32_bf16 v[122:125], v[66:69], v[222:225], v[122:125]
	v_mfma_f32_16x16x32_bf16 v[138:141], v[66:69], v[226:229], v[138:141]
	v_mfma_f32_16x16x32_bf16 v[162:165], v[66:69], v[230:233], v[162:165]
	v_mfma_f32_16x16x32_bf16 v[110:113], v[70:73], v[218:221], v[110:113]
	v_mfma_f32_16x16x32_bf16 v[126:129], v[70:73], v[222:225], v[126:129]
	v_mfma_f32_16x16x32_bf16 v[142:145], v[70:73], v[226:229], v[142:145]
	v_mfma_f32_16x16x32_bf16 v[166:169], v[70:73], v[230:233], v[166:169]
	v_mfma_f32_16x16x32_bf16 v[114:117], v[74:77], v[218:221], v[114:117]
	v_mfma_f32_16x16x32_bf16 v[130:133], v[74:77], v[222:225], v[130:133]
	v_mfma_f32_16x16x32_bf16 v[154:157], v[74:77], v[226:229], v[154:157]
	v_mfma_f32_16x16x32_bf16 v[170:173], v[74:77], v[230:233], v[170:173]
	v_mfma_f32_16x16x32_bf16 v[118:121], v[78:81], v[218:221], v[118:121]
	v_mfma_f32_16x16x32_bf16 v[134:137], v[78:81], v[222:225], v[134:137]
	v_mfma_f32_16x16x32_bf16 v[158:161], v[78:81], v[226:229], v[158:161]
	v_mfma_f32_16x16x32_bf16 v[174:177], v[78:81], v[230:233], v[174:177]
	s_waitcnt lgkmcnt(0)
	v_mfma_f32_16x16x32_bf16 v[106:109], v[82:85], v[234:237], v[106:109]
	v_mfma_f32_16x16x32_bf16 v[122:125], v[82:85], v[238:241], v[122:125]
	v_mfma_f32_16x16x32_bf16 v[138:141], v[82:85], v[242:245], v[138:141]
	v_mfma_f32_16x16x32_bf16 v[162:165], v[82:85], v[246:249], v[162:165]
	v_mfma_f32_16x16x32_bf16 v[110:113], v[86:89], v[234:237], v[110:113]
	v_mfma_f32_16x16x32_bf16 v[126:129], v[86:89], v[238:241], v[126:129]
	v_mfma_f32_16x16x32_bf16 v[142:145], v[86:89], v[242:245], v[142:145]
	v_mfma_f32_16x16x32_bf16 v[166:169], v[86:89], v[246:249], v[166:169]
	v_mfma_f32_16x16x32_bf16 v[114:117], v[90:93], v[234:237], v[114:117]
	v_mfma_f32_16x16x32_bf16 v[130:133], v[90:93], v[238:241], v[130:133]
	v_mfma_f32_16x16x32_bf16 v[154:157], v[90:93], v[242:245], v[154:157]
	v_mfma_f32_16x16x32_bf16 v[170:173], v[90:93], v[246:249], v[170:173]
	v_mfma_f32_16x16x32_bf16 v[118:121], v[94:97], v[234:237], v[118:121]
	v_mfma_f32_16x16x32_bf16 v[134:137], v[94:97], v[238:241], v[134:137]
	v_mfma_f32_16x16x32_bf16 v[158:161], v[94:97], v[242:245], v[158:161]
	v_mfma_f32_16x16x32_bf16 v[174:177], v[94:97], v[246:249], v[174:177]
	s_nop 7
	s_barrier
	v_mov_b32_e32 v0, 0x13ff0
	v_mov_b32_e32 v218, s5
	v_mov_b32_e32 v219, s101
	ds_write_b64 v0, v[218:219]
	s_mov_b64 s[84:85], 0
	s_branch .LBB0_208
.Lpk_sw_unpark:
	s_barrier
	v_mov_b32_e32 v62, v106
	v_mov_b32_e32 v63, v107
	v_mov_b32_e32 v64, v108
	v_mov_b32_e32 v65, v109
	v_mov_b32_e32 v58, v110
	v_mov_b32_e32 v59, v111
	v_mov_b32_e32 v60, v112
	v_mov_b32_e32 v61, v113
	v_mov_b32_e32 v54, v114
	v_mov_b32_e32 v55, v115
	v_mov_b32_e32 v56, v116
	v_mov_b32_e32 v57, v117
	v_mov_b32_e32 v50, v118
	v_mov_b32_e32 v51, v119
	v_mov_b32_e32 v52, v120
	v_mov_b32_e32 v53, v121
	v_mov_b32_e32 v46, v122
	v_mov_b32_e32 v47, v123
	v_mov_b32_e32 v48, v124
	v_mov_b32_e32 v49, v125
	v_mov_b32_e32 v42, v126
	v_mov_b32_e32 v43, v127
	v_mov_b32_e32 v44, v128
	v_mov_b32_e32 v45, v129
	v_mov_b32_e32 v38, v130
	v_mov_b32_e32 v39, v131
	v_mov_b32_e32 v40, v132
	v_mov_b32_e32 v41, v133
	v_mov_b32_e32 v34, v134
	v_mov_b32_e32 v35, v135
	v_mov_b32_e32 v36, v136
	v_mov_b32_e32 v37, v137
	v_mov_b32_e32 v30, v138
	v_mov_b32_e32 v31, v139
	v_mov_b32_e32 v32, v140
	v_mov_b32_e32 v33, v141
	v_mov_b32_e32 v26, v142
	v_mov_b32_e32 v27, v143
	v_mov_b32_e32 v28, v144
	v_mov_b32_e32 v29, v145
	v_mov_b32_e32 v22, v154
	v_mov_b32_e32 v23, v155
	v_mov_b32_e32 v24, v156
	v_mov_b32_e32 v25, v157
	v_mov_b32_e32 v18, v158
	v_mov_b32_e32 v19, v159
	v_mov_b32_e32 v20, v160
	v_mov_b32_e32 v21, v161
	v_mov_b32_e32 v14, v162
	v_mov_b32_e32 v15, v163
	v_mov_b32_e32 v16, v164
	v_mov_b32_e32 v17, v165
	v_mov_b32_e32 v10, v166
	v_mov_b32_e32 v11, v167
	v_mov_b32_e32 v12, v168
	v_mov_b32_e32 v13, v169
	v_mov_b32_e32 v6, v170
	v_mov_b32_e32 v7, v171
	v_mov_b32_e32 v8, v172
	v_mov_b32_e32 v9, v173
	v_mov_b32_e32 v2, v174
	v_mov_b32_e32 v3, v175
	v_mov_b32_e32 v4, v176
	v_mov_b32_e32 v5, v177
	s_mov_b64 s[84:85], 0
	s_branch .LBB0_208
.Lpk_sw_orig:
	v_mov_b32_e32 v8, v151
	s_movk_i32 s5, 0x9c00
	v_bfe_u32 v11, v8, 4, 2
	v_ashrrev_i32_e32 v9, 6, v8
	v_and_b32_e32 v10, 63, v8
	v_xor_b32_e32 v0, v11, v8
	v_lshl_or_b32 v3, v9, 8, v10
	v_lshlrev_b32_e32 v0, 3, v0
	v_lshlrev_b32_e32 v2, 7, v3
	v_and_b32_e32 v12, 56, v0
	v_and_or_b32 v0, v2, s5, v12
	v_or_b32_e32 v2, 64, v3
	v_lshrrev_b32_e32 v4, 4, v2
	v_xor_b32_e32 v4, v4, v8
	v_or_b32_e32 v3, 0xc0, v3
	v_lshlrev_b32_e32 v13, 7, v2
	v_lshlrev_b32_e32 v2, 3, v4
	v_lshrrev_b32_e32 v4, 4, v3
	v_xor_b32_e32 v4, v4, v8
	v_lshlrev_b32_e32 v98, 12, v9
	v_lshlrev_b32_e32 v15, 7, v3
	v_lshlrev_b32_e32 v3, 3, v4
	v_lshlrev_b64 v[4:5], 1, v[0:1]
	v_readfirstlane_b32 s4, v98
	v_add_u32_e32 v99, 0x4000, v98
	v_lshl_add_u64 v[6:7], s[28:29], 0, v[4:5]
	s_mov_b32 m0, s4
	v_readfirstlane_b32 s4, v99
	v_and_b32_e32 v14, 56, v2
	s_waitcnt vmcnt(63) expcnt(7) lgkmcnt(15)
	s_barrier
	global_load_lds_dwordx4 v[6:7], off
	s_mov_b32 m0, s4
	s_movk_i32 s4, 0xbc00
	v_or_b32_e32 v2, 0x4000, v0
	v_lshl_add_u64 v[4:5], s[48:49], 0, v[4:5]
	v_and_or_b32 v0, v13, s4, v14
	global_load_lds_dwordx4 v[4:5], off
	v_lshlrev_b64 v[4:5], 1, v[0:1]
	v_or_b32_e32 v0, 0x400, v98
	v_add_u32_e32 v100, 0x4400, v98
	v_readfirstlane_b32 s4, v0
	v_and_b32_e32 v16, 56, v3
	v_lshl_add_u64 v[6:7], s[28:29], 0, v[4:5]
	s_mov_b32 m0, s4
	v_readfirstlane_b32 s4, v100
	v_mov_b32_e32 v3, v1
	v_or_b32_e32 v0, 0x800, v98
	global_load_lds_dwordx4 v[6:7], off
	v_lshl_add_u64 v[6:7], s[48:49], 0, v[4:5]
	s_mov_b32 m0, s4
	v_lshlrev_b64 v[2:3], 1, v[2:3]
	v_readfirstlane_b32 s4, v0
	v_add_u32_e32 v101, 0x4800, v98
	global_load_lds_dwordx4 v[6:7], off
	v_lshl_add_u64 v[6:7], s[28:29], 0, v[2:3]
	s_mov_b32 m0, s4
	v_readfirstlane_b32 s4, v101
	global_load_lds_dwordx4 v[6:7], off
	s_mov_b32 m0, s4
	s_movk_i32 s4, 0xfc00
	v_lshl_add_u64 v[2:3], s[48:49], 0, v[2:3]
	v_and_or_b32 v0, v15, s4, v16
	global_load_lds_dwordx4 v[2:3], off
	v_lshlrev_b64 v[2:3], 1, v[0:1]
	v_or_b32_e32 v0, 0xc00, v98
	v_add_u32_e32 v102, 0x4c00, v98
	v_readfirstlane_b32 s4, v0
	v_lshl_add_u64 v[6:7], s[28:29], 0, v[2:3]
	s_mov_b32 m0, s4
	v_readfirstlane_b32 s4, v102
	global_load_lds_dwordx4 v[6:7], off
	v_lshl_add_u64 v[6:7], s[48:49], 0, v[2:3]
	s_mov_b32 m0, s4
	v_lshrrev_b32_e32 v0, 1, v8
	global_load_lds_dwordx4 v[6:7], off
	v_bitop3_b32 v0, v11, v0, 7 bitop3:0x78
	v_lshlrev_b32_e32 v7, 6, v8
	v_lshlrev_b32_e32 v14, 13, v9
	v_bfe_u32 v6, v8, 1, 3
	v_lshlrev_b32_e32 v0, 4, v0
	v_and_b32_e32 v7, 0xffffe000, v7
	v_and_b32_e32 v14, 0x2000, v14
	v_or_b32_e32 v13, v0, v7
	v_or_b32_e32 v15, v0, v14
	v_bitop3_b32 v0, v11, v6, 4 bitop3:0x36
	v_lshlrev_b32_e32 v0, 4, v0
	v_or_b32_e32 v11, v0, v7
	v_or_b32_e32 v14, v0, v14
	v_lshlrev_b32_e32 v0, 7, v10
	v_lshl_or_b32 v0, v9, 15, v0
	v_and_or_b32 v0, v0, s5, v12
	s_add_u32 s4, s11, s38
	s_waitcnt vmcnt(0)
	v_lshlrev_b32_e32 v8, 7, v8
	v_lshlrev_b64 v[6:7], 1, v[0:1]
	s_addc_u32 s5, s10, s39
	v_or_b32_e32 v0, 0x4000, v0
	v_and_b32_e32 v8, 0x780, v8
	v_lshl_add_u64 v[70:71], s[46:47], 0, v[4:5]
	v_lshl_add_u64 v[72:73], s[4:5], 0, v[4:5]
	v_lshlrev_b64 v[4:5], 1, v[0:1]
	v_lshl_add_u64 v[78:79], s[46:47], 0, v[2:3]
	v_lshl_add_u64 v[80:81], s[4:5], 0, v[2:3]
	v_mov_b32_e32 v2, 0
	v_lshl_add_u64 v[66:67], s[46:47], 0, v[6:7]
	v_lshl_add_u64 v[68:69], s[4:5], 0, v[6:7]
	v_lshl_add_u64 v[74:75], s[46:47], 0, v[4:5]
	v_lshl_add_u64 v[76:77], s[4:5], 0, v[4:5]
	s_mov_b32 s4, 0
	v_add_u32_e32 v0, v13, v8
	v_add_u32_e32 v103, v15, v8
	v_add_u32_e32 v104, v11, v8
	v_add_u32_e32 v105, v14, v8
	v_mov_b32_e32 v3, v2
	v_mov_b32_e32 v4, v2
	v_mov_b32_e32 v5, v2
	v_mov_b32_e32 v6, v2
	v_mov_b32_e32 v7, v2
	v_mov_b32_e32 v8, v2
	v_mov_b32_e32 v9, v2
	v_mov_b32_e32 v10, v2
	v_mov_b32_e32 v11, v2
	v_mov_b32_e32 v12, v2
	v_mov_b32_e32 v13, v2
	v_mov_b32_e32 v14, v2
	v_mov_b32_e32 v15, v2
	v_mov_b32_e32 v16, v2
	v_mov_b32_e32 v17, v2
	s_waitcnt vmcnt(0)
	v_mov_b32_e32 v18, v2
	v_mov_b32_e32 v19, v2
	v_mov_b32_e32 v20, v2
	v_mov_b32_e32 v21, v2
	v_mov_b32_e32 v22, v2
	v_mov_b32_e32 v23, v2
	v_mov_b32_e32 v24, v2
	v_mov_b32_e32 v25, v2
	v_mov_b32_e32 v26, v2
	v_mov_b32_e32 v27, v2
	v_mov_b32_e32 v28, v2
	v_mov_b32_e32 v29, v2
	v_mov_b32_e32 v30, v2
	v_mov_b32_e32 v31, v2
	v_mov_b32_e32 v32, v2
	v_mov_b32_e32 v33, v2
	v_mov_b32_e32 v34, v2
	v_mov_b32_e32 v35, v2
	v_mov_b32_e32 v36, v2
	v_mov_b32_e32 v37, v2
	v_mov_b32_e32 v38, v2
	v_mov_b32_e32 v39, v2
	v_mov_b32_e32 v40, v2
	v_mov_b32_e32 v41, v2
	v_mov_b32_e32 v42, v2
	v_mov_b32_e32 v43, v2
	v_mov_b32_e32 v44, v2
	v_mov_b32_e32 v45, v2
	v_mov_b32_e32 v46, v2
	v_mov_b32_e32 v47, v2
	v_mov_b32_e32 v48, v2
	v_mov_b32_e32 v49, v2
	v_mov_b32_e32 v50, v2
	v_mov_b32_e32 v51, v2
	v_mov_b32_e32 v52, v2
	v_mov_b32_e32 v53, v2
	v_mov_b32_e32 v54, v2
	v_mov_b32_e32 v55, v2
	v_mov_b32_e32 v56, v2
	v_mov_b32_e32 v57, v2
	v_mov_b32_e32 v58, v2
	v_mov_b32_e32 v59, v2
	v_mov_b32_e32 v60, v2
	v_mov_b32_e32 v61, v2
	v_mov_b32_e32 v62, v2
	v_mov_b32_e32 v63, v2
	v_mov_b32_e32 v64, v2
	v_mov_b32_e32 v65, v2
	s_waitcnt lgkmcnt(0)
	s_barrier
	s_branch .LBB0_206

.LBB0_255:
	s_and_b64 vcc, exec, s[84:85]
	s_cbranch_vccz .LBB0_196
	s_bfe_u32 s4, s100, 0x20008
	s_cmp_eq_u32 s4, 0
	s_cbranch_scc1 .Lpk_tt_orig
	s_cmp_eq_u32 s4, 2
	s_cbranch_scc1 .Lpk_tt_unpark
	v_lshrrev_b32_e32 v0, 6, v151
	v_and_b32_e32 v218, 63, v151
	s_nop 0
	v_readfirstlane_b32 s5, v0
	v_lshrrev_b32_e32 v219, 4, v218
	v_and_b32_e32 v220, 7, v218
	v_xor_b32_e32 v220, v220, v219
	v_lshlrev_b32_e32 v220, 4, v220
	v_lshrrev_b32_e32 v219, 3, v218
	v_lshl_or_b32 v98, v219, 11, v220
	s_lshl_b32 s4, s5, 16
	v_add_u32_e32 v98, s4, v98
	v_xor_b32_e32 v99, 64, v98
	v_add_u32_e32 v99, 0x4000, v99
	v_add_u32_e32 v100, 0x8000, v98
	v_add_u32_e32 v101, 0x8000, v99
	v_and_b32_e32 v219, 15, v218
	v_lshrrev_b32_e32 v220, 4, v218
	v_bfe_u32 v218, v219, 1, 3
	v_xor_b32_e32 v220, v220, v218
	v_lshlrev_b32_e32 v220, 4, v220
	v_lshl_or_b32 v220, v219, 7, v220
	s_lshr_b32 s4, s5, 1
	s_lshl_b32 s4, s4, 13
	v_add_u32_e32 v102, s4, v220
	v_xor_b32_e32 v103, 64, v102
	s_and_b32 s4, s5, 1
	s_lshl_b32 s4, s4, 13
	v_add_u32_e32 v104, s4, v220
	v_xor_b32_e32 v105, 64, v104
	v_add_u32_e32 v250, 0x4000, v104
	v_add_u32_e32 v251, 0x4000, v105
	s_lshl_b32 s4, s5, 12
	s_add_u32 s6, s28, 0x40000
	s_addc_u32 s7, s29, 0
	v_mov_b32_e32 v0, 0x13ff0
	ds_read_b64 v[218:219], v0
	s_waitcnt lgkmcnt(0)
	v_readfirstlane_b32 s5, v218
	v_readfirstlane_b32 s101, v219
	s_barrier
	s_add_u32 m0, s4, 0x0
	s_nop 0
	global_load_lds_dwordx4 v98, s[28:29]
	s_add_u32 m0, s4, 0x400
	s_nop 0
	global_load_lds_dwordx4 v99, s[28:29]
	s_add_u32 m0, s4, 0x800
	s_nop 0
	global_load_lds_dwordx4 v100, s[28:29]
	s_add_u32 m0, s4, 0xc00
	s_nop 0
	global_load_lds_dwordx4 v101, s[28:29]
	s_add_u32 m0, s4, 0xc000
	s_nop 0
	global_load_lds_dwordx4 v98, s[48:49]
	s_add_u32 m0, s4, 0xc400
	s_nop 0
	global_load_lds_dwordx4 v99, s[48:49]
	s_add_u32 m0, s4, 0xc800
	s_nop 0
	global_load_lds_dwordx4 v100, s[48:49]
	s_add_u32 m0, s4, 0xcc00
	s_nop 0
	global_load_lds_dwordx4 v101, s[48:49]
	s_add_u32 m0, s4, 0x4000
	s_nop 0
	global_load_lds_dwordx4 v98, s[6:7]
	s_add_u32 m0, s4, 0x4400
	s_nop 0
	global_load_lds_dwordx4 v99, s[6:7]
	s_add_u32 m0, s4, 0x4800
	s_nop 0
	global_load_lds_dwordx4 v100, s[6:7]
	s_add_u32 m0, s4, 0x4c00
	s_nop 0
	global_load_lds_dwordx4 v101, s[6:7]
	v_add_u32_e32 v98, 0x80, v98
	v_add_u32_e32 v99, 0x80, v99
	v_add_u32_e32 v100, 0x80, v100
	v_add_u32_e32 v101, 0x80, v101
	v_mov_b32_e32 v62, 0
	v_mov_b32_e32 v106, 0
	v_mov_b32_e32 v63, 0
	v_mov_b32_e32 v107, 0
	v_mov_b32_e32 v64, 0
	v_mov_b32_e32 v108, 0
	v_mov_b32_e32 v65, 0
	v_mov_b32_e32 v109, 0
	v_mov_b32_e32 v58, 0
	v_mov_b32_e32 v110, 0
	v_mov_b32_e32 v59, 0
	v_mov_b32_e32 v111, 0
	v_mov_b32_e32 v60, 0
	v_mov_b32_e32 v112, 0
	v_mov_b32_e32 v61, 0
	v_mov_b32_e32 v113, 0
	v_mov_b32_e32 v54, 0
	v_mov_b32_e32 v114, 0
	v_mov_b32_e32 v55, 0
	v_mov_b32_e32 v115, 0
	v_mov_b32_e32 v56, 0
	v_mov_b32_e32 v116, 0
	v_mov_b32_e32 v57, 0
	v_mov_b32_e32 v117, 0
	v_mov_b32_e32 v50, 0
	v_mov_b32_e32 v118, 0
	v_mov_b32_e32 v51, 0
	v_mov_b32_e32 v119, 0
	v_mov_b32_e32 v52, 0
	v_mov_b32_e32 v120, 0
	v_mov_b32_e32 v53, 0
	v_mov_b32_e32 v121, 0
	v_mov_b32_e32 v46, 0
	v_mov_b32_e32 v122, 0
	v_mov_b32_e32 v47, 0
	v_mov_b32_e32 v123, 0
	v_mov_b32_e32 v48, 0
	v_mov_b32_e32 v124, 0
	v_mov_b32_e32 v49, 0
	v_mov_b32_e32 v125, 0
	v_mov_b32_e32 v42, 0
	v_mov_b32_e32 v126, 0
	v_mov_b32_e32 v43, 0
	v_mov_b32_e32 v127, 0
	v_mov_b32_e32 v44, 0
	v_mov_b32_e32 v128, 0
	v_mov_b32_e32 v45, 0
	v_mov_b32_e32 v129, 0
	v_mov_b32_e32 v38, 0
	v_mov_b32_e32 v130, 0
	v_mov_b32_e32 v39, 0
	v_mov_b32_e32 v131, 0
	v_mov_b32_e32 v40, 0
	v_mov_b32_e32 v132, 0
	v_mov_b32_e32 v41, 0
	v_mov_b32_e32 v133, 0
	v_mov_b32_e32 v34, 0
	v_mov_b32_e32 v134, 0
	v_mov_b32_e32 v35, 0
	v_mov_b32_e32 v135, 0
	v_mov_b32_e32 v36, 0
	v_mov_b32_e32 v136, 0
	v_mov_b32_e32 v37, 0
	v_mov_b32_e32 v137, 0
	v_mov_b32_e32 v30, 0
	v_mov_b32_e32 v138, 0
	v_mov_b32_e32 v31, 0
	v_mov_b32_e32 v139, 0
	v_mov_b32_e32 v32, 0
	v_mov_b32_e32 v140, 0
	v_mov_b32_e32 v33, 0
	v_mov_b32_e32 v141, 0
	v_mov_b32_e32 v26, 0
	v_mov_b32_e32 v142, 0
	v_mov_b32_e32 v27, 0
	v_mov_b32_e32 v143, 0
	v_mov_b32_e32 v28, 0
	v_mov_b32_e32 v144, 0
	v_mov_b32_e32 v29, 0
	v_mov_b32_e32 v145, 0
	v_mov_b32_e32 v22, 0
	v_mov_b32_e32 v154, 0
	v_mov_b32_e32 v23, 0
	v_mov_b32_e32 v155, 0
	v_mov_b32_e32 v24, 0
	v_mov_b32_e32 v156, 0
	v_mov_b32_e32 v25, 0
	v_mov_b32_e32 v157, 0
	v_mov_b32_e32 v18, 0
	v_mov_b32_e32 v158, 0
	v_mov_b32_e32 v19, 0
	v_mov_b32_e32 v159, 0
	v_mov_b32_e32 v20, 0
	v_mov_b32_e32 v160, 0
	v_mov_b32_e32 v21, 0
	v_mov_b32_e32 v161, 0
	v_mov_b32_e32 v14, 0
	v_mov_b32_e32 v162, 0
	v_mov_b32_e32 v15, 0
	v_mov_b32_e32 v163, 0
	v_mov_b32_e32 v16, 0
	v_mov_b32_e32 v164, 0
	v_mov_b32_e32 v17, 0
	v_mov_b32_e32 v165, 0
	v_mov_b32_e32 v10, 0
	v_mov_b32_e32 v166, 0
	v_mov_b32_e32 v11, 0
	v_mov_b32_e32 v167, 0
	v_mov_b32_e32 v12, 0
	v_mov_b32_e32 v168, 0
	v_mov_b32_e32 v13, 0
	v_mov_b32_e32 v169, 0
	v_mov_b32_e32 v6, 0
	v_mov_b32_e32 v170, 0
	v_mov_b32_e32 v7, 0
	v_mov_b32_e32 v171, 0
	v_mov_b32_e32 v8, 0
	v_mov_b32_e32 v172, 0
	v_mov_b32_e32 v9, 0
	v_mov_b32_e32 v173, 0
	v_mov_b32_e32 v2, 0
	v_mov_b32_e32 v174, 0
	v_mov_b32_e32 v3, 0
	v_mov_b32_e32 v175, 0
	v_mov_b32_e32 v4, 0
	v_mov_b32_e32 v176, 0
	v_mov_b32_e32 v5, 0
	v_mov_b32_e32 v177, 0
	s_waitcnt vmcnt(4)
	s_barrier
	ds_read_b128 v[218:221], v102 offset:0
	ds_read_b128 v[222:225], v102 offset:2048
	ds_read_b128 v[226:229], v102 offset:4096
	ds_read_b128 v[230:233], v102 offset:6144
	ds_read_b128 v[66:69], v104 offset:49152
	ds_read_b128 v[70:73], v104 offset:51200
	ds_read_b128 v[74:77], v104 offset:53248
	ds_read_b128 v[78:81], v104 offset:55296
	ds_read_b128 v[234:237], v103 offset:0
	ds_read_b128 v[238:241], v103 offset:2048
	ds_read_b128 v[242:245], v103 offset:4096
	ds_read_b128 v[246:249], v103 offset:6144
	ds_read_b128 v[82:85], v105 offset:49152
	ds_read_b128 v[86:89], v105 offset:51200
	ds_read_b128 v[90:93], v105 offset:53248
	ds_read_b128 v[94:97], v105 offset:55296
	s_add_u32 m0, s4, 0x8000
	s_nop 0
	global_load_lds_dwordx4 v98, s[28:29]
	s_add_u32 m0, s4, 0x8400
	s_nop 0
	global_load_lds_dwordx4 v99, s[28:29]
	s_add_u32 m0, s4, 0x8800
	s_nop 0
	global_load_lds_dwordx4 v100, s[28:29]
	s_add_u32 m0, s4, 0x8c00
	s_nop 0
	global_load_lds_dwordx4 v101, s[28:29]
	s_add_u32 m0, s4, 0x10000
	s_nop 0
	global_load_lds_dwordx4 v98, s[48:49]
	s_add_u32 m0, s4, 0x10400
	s_nop 0
	global_load_lds_dwordx4 v99, s[48:49]
	s_add_u32 m0, s4, 0x10800
	s_nop 0
	global_load_lds_dwordx4 v100, s[48:49]
	s_add_u32 m0, s4, 0x10c00
	s_nop 0
	global_load_lds_dwordx4 v101, s[48:49]
	s_waitcnt lgkmcnt(8)
	v_mfma_f32_16x16x32_bf16 v[62:65], v[218:221], v[66:69], v[62:65]
	v_mfma_f32_16x16x32_bf16 v[46:49], v[222:225], v[66:69], v[46:49]
	v_mfma_f32_16x16x32_bf16 v[30:33], v[226:229], v[66:69], v[30:33]
	v_mfma_f32_16x16x32_bf16 v[14:17], v[230:233], v[66:69], v[14:17]
	v_mfma_f32_16x16x32_bf16 v[58:61], v[218:221], v[70:73], v[58:61]
	v_mfma_f32_16x16x32_bf16 v[42:45], v[222:225], v[70:73], v[42:45]
	v_mfma_f32_16x16x32_bf16 v[26:29], v[226:229], v[70:73], v[26:29]
	v_mfma_f32_16x16x32_bf16 v[10:13], v[230:233], v[70:73], v[10:13]
	v_mfma_f32_16x16x32_bf16 v[54:57], v[218:221], v[74:77], v[54:57]
	v_mfma_f32_16x16x32_bf16 v[38:41], v[222:225], v[74:77], v[38:41]
	v_mfma_f32_16x16x32_bf16 v[22:25], v[226:229], v[74:77], v[22:25]
	v_mfma_f32_16x16x32_bf16 v[6:9], v[230:233], v[74:77], v[6:9]
	v_mfma_f32_16x16x32_bf16 v[50:53], v[218:221], v[78:81], v[50:53]
	v_mfma_f32_16x16x32_bf16 v[34:37], v[222:225], v[78:81], v[34:37]
	v_mfma_f32_16x16x32_bf16 v[18:21], v[226:229], v[78:81], v[18:21]
	v_mfma_f32_16x16x32_bf16 v[2:5], v[230:233], v[78:81], v[2:5]
	s_waitcnt lgkmcnt(0)
	v_mfma_f32_16x16x32_bf16 v[62:65], v[234:237], v[82:85], v[62:65]
	v_mfma_f32_16x16x32_bf16 v[46:49], v[238:241], v[82:85], v[46:49]
	v_mfma_f32_16x16x32_bf16 v[30:33], v[242:245], v[82:85], v[30:33]
	v_mfma_f32_16x16x32_bf16 v[14:17], v[246:249], v[82:85], v[14:17]
	v_mfma_f32_16x16x32_bf16 v[58:61], v[234:237], v[86:89], v[58:61]
	v_mfma_f32_16x16x32_bf16 v[42:45], v[238:241], v[86:89], v[42:45]
	v_mfma_f32_16x16x32_bf16 v[26:29], v[242:245], v[86:89], v[26:29]
	v_mfma_f32_16x16x32_bf16 v[10:13], v[246:249], v[86:89], v[10:13]
	v_mfma_f32_16x16x32_bf16 v[54:57], v[234:237], v[90:93], v[54:57]
	v_mfma_f32_16x16x32_bf16 v[38:41], v[238:241], v[90:93], v[38:41]
	v_mfma_f32_16x16x32_bf16 v[22:25], v[242:245], v[90:93], v[22:25]
	v_mfma_f32_16x16x32_bf16 v[6:9], v[246:249], v[90:93], v[6:9]
	v_mfma_f32_16x16x32_bf16 v[50:53], v[234:237], v[94:97], v[50:53]
	v_mfma_f32_16x16x32_bf16 v[34:37], v[238:241], v[94:97], v[34:37]
	v_mfma_f32_16x16x32_bf16 v[18:21], v[242:245], v[94:97], v[18:21]
	v_mfma_f32_16x16x32_bf16 v[2:5], v[246:249], v[94:97], v[2:5]
	s_waitcnt vmcnt(8)
	s_barrier
	ds_read_b128 v[218:221], v102 offset:16384
	ds_read_b128 v[222:225], v102 offset:18432
	ds_read_b128 v[226:229], v102 offset:20480
	ds_read_b128 v[230:233], v102 offset:22528
	ds_read_b128 v[234:237], v103 offset:16384
	ds_read_b128 v[238:241], v103 offset:18432
	ds_read_b128 v[242:245], v103 offset:20480
	ds_read_b128 v[246:249], v103 offset:22528
	s_add_u32 m0, s4, 0x0
	s_nop 0
	global_load_lds_dwordx4 v98, s[6:7]
	s_add_u32 m0, s4, 0x400
	s_nop 0
	global_load_lds_dwordx4 v99, s[6:7]
	s_add_u32 m0, s4, 0x800
	s_nop 0
	global_load_lds_dwordx4 v100, s[6:7]
	s_add_u32 m0, s4, 0xc00
	s_nop 0
	global_load_lds_dwordx4 v101, s[6:7]
	v_add_u32_e32 v98, 0x80, v98
	v_add_u32_e32 v99, 0x80, v99
	v_add_u32_e32 v100, 0x80, v100
	v_add_u32_e32 v101, 0x80, v101
	s_waitcnt lgkmcnt(4)
	v_mfma_f32_16x16x32_bf16 v[106:109], v[218:221], v[66:69], v[106:109]
	v_mfma_f32_16x16x32_bf16 v[122:125], v[222:225], v[66:69], v[122:125]
	v_mfma_f32_16x16x32_bf16 v[138:141], v[226:229], v[66:69], v[138:141]
	v_mfma_f32_16x16x32_bf16 v[162:165], v[230:233], v[66:69], v[162:165]
	v_mfma_f32_16x16x32_bf16 v[110:113], v[218:221], v[70:73], v[110:113]
	v_mfma_f32_16x16x32_bf16 v[126:129], v[222:225], v[70:73], v[126:129]
	v_mfma_f32_16x16x32_bf16 v[142:145], v[226:229], v[70:73], v[142:145]
	v_mfma_f32_16x16x32_bf16 v[166:169], v[230:233], v[70:73], v[166:169]
	v_mfma_f32_16x16x32_bf16 v[114:117], v[218:221], v[74:77], v[114:117]
	v_mfma_f32_16x16x32_bf16 v[130:133], v[222:225], v[74:77], v[130:133]
	v_mfma_f32_16x16x32_bf16 v[154:157], v[226:229], v[74:77], v[154:157]
	v_mfma_f32_16x16x32_bf16 v[170:173], v[230:233], v[74:77], v[170:173]
	v_mfma_f32_16x16x32_bf16 v[118:121], v[218:221], v[78:81], v[118:121]
	v_mfma_f32_16x16x32_bf16 v[134:137], v[222:225], v[78:81], v[134:137]
	v_mfma_f32_16x16x32_bf16 v[158:161], v[226:229], v[78:81], v[158:161]
	v_mfma_f32_16x16x32_bf16 v[174:177], v[230:233], v[78:81], v[174:177]
	s_waitcnt lgkmcnt(0)
	v_mfma_f32_16x16x32_bf16 v[106:109], v[234:237], v[82:85], v[106:109]
	v_mfma_f32_16x16x32_bf16 v[122:125], v[238:241], v[82:85], v[122:125]
	v_mfma_f32_16x16x32_bf16 v[138:141], v[242:245], v[82:85], v[138:141]
	v_mfma_f32_16x16x32_bf16 v[162:165], v[246:249], v[82:85], v[162:165]
	v_mfma_f32_16x16x32_bf16 v[110:113], v[234:237], v[86:89], v[110:113]
	v_mfma_f32_16x16x32_bf16 v[126:129], v[238:241], v[86:89], v[126:129]
	v_mfma_f32_16x16x32_bf16 v[142:145], v[242:245], v[86:89], v[142:145]
	v_mfma_f32_16x16x32_bf16 v[166:169], v[246:249], v[86:89], v[166:169]
	v_mfma_f32_16x16x32_bf16 v[114:117], v[234:237], v[90:93], v[114:117]
	v_mfma_f32_16x16x32_bf16 v[130:133], v[238:241], v[90:93], v[130:133]
	v_mfma_f32_16x16x32_bf16 v[154:157], v[242:245], v[90:93], v[154:157]
	v_mfma_f32_16x16x32_bf16 v[170:173], v[246:249], v[90:93], v[170:173]
	v_mfma_f32_16x16x32_bf16 v[118:121], v[234:237], v[94:97], v[118:121]
	v_mfma_f32_16x16x32_bf16 v[134:137], v[238:241], v[94:97], v[134:137]
	v_mfma_f32_16x16x32_bf16 v[158:161], v[242:245], v[94:97], v[158:161]
	v_mfma_f32_16x16x32_bf16 v[174:177], v[246:249], v[94:97], v[174:177]
	s_waitcnt vmcnt(4)
	s_barrier
	ds_read_b128 v[218:221], v102 offset:32768
	ds_read_b128 v[222:225], v102 offset:34816
	ds_read_b128 v[226:229], v102 offset:36864
	ds_read_b128 v[230:233], v102 offset:38912
	ds_read_b128 v[66:69], v250 offset:49152
	ds_read_b128 v[70:73], v250 offset:51200
	ds_read_b128 v[74:77], v250 offset:53248
	ds_read_b128 v[78:81], v250 offset:55296
	ds_read_b128 v[234:237], v103 offset:32768
	ds_read_b128 v[238:241], v103 offset:34816
	ds_read_b128 v[242:245], v103 offset:36864
	ds_read_b128 v[246:249], v103 offset:38912
	ds_read_b128 v[82:85], v251 offset:49152
	ds_read_b128 v[86:89], v251 offset:51200
	ds_read_b128 v[90:93], v251 offset:53248
	ds_read_b128 v[94:97], v251 offset:55296
	s_add_u32 m0, s4, 0x4000
	s_nop 0
	global_load_lds_dwordx4 v98, s[28:29]
	s_add_u32 m0, s4, 0x4400
	s_nop 0
	global_load_lds_dwordx4 v99, s[28:29]
	s_add_u32 m0, s4, 0x4800
	s_nop 0
	global_load_lds_dwordx4 v100, s[28:29]
	s_add_u32 m0, s4, 0x4c00
	s_nop 0
	global_load_lds_dwordx4 v101, s[28:29]
	s_add_u32 m0, s4, 0xc000
	s_nop 0
	global_load_lds_dwordx4 v98, s[48:49]
	s_add_u32 m0, s4, 0xc400
	s_nop 0
	global_load_lds_dwordx4 v99, s[48:49]
	s_add_u32 m0, s4, 0xc800
	s_nop 0
	global_load_lds_dwordx4 v100, s[48:49]
	s_add_u32 m0, s4, 0xcc00
	s_nop 0
	global_load_lds_dwordx4 v101, s[48:49]
	s_waitcnt lgkmcnt(8)
	v_mfma_f32_16x16x32_bf16 v[62:65], v[218:221], v[66:69], v[62:65]
	v_mfma_f32_16x16x32_bf16 v[46:49], v[222:225], v[66:69], v[46:49]
	v_mfma_f32_16x16x32_bf16 v[30:33], v[226:229], v[66:69], v[30:33]
	v_mfma_f32_16x16x32_bf16 v[14:17], v[230:233], v[66:69], v[14:17]
	v_mfma_f32_16x16x32_bf16 v[58:61], v[218:221], v[70:73], v[58:61]
	v_mfma_f32_16x16x32_bf16 v[42:45], v[222:225], v[70:73], v[42:45]
	v_mfma_f32_16x16x32_bf16 v[26:29], v[226:229], v[70:73], v[26:29]
	v_mfma_f32_16x16x32_bf16 v[10:13], v[230:233], v[70:73], v[10:13]
	v_mfma_f32_16x16x32_bf16 v[54:57], v[218:221], v[74:77], v[54:57]
	v_mfma_f32_16x16x32_bf16 v[38:41], v[222:225], v[74:77], v[38:41]
	v_mfma_f32_16x16x32_bf16 v[22:25], v[226:229], v[74:77], v[22:25]
	v_mfma_f32_16x16x32_bf16 v[6:9], v[230:233], v[74:77], v[6:9]
	v_mfma_f32_16x16x32_bf16 v[50:53], v[218:221], v[78:81], v[50:53]
	v_mfma_f32_16x16x32_bf16 v[34:37], v[222:225], v[78:81], v[34:37]
	v_mfma_f32_16x16x32_bf16 v[18:21], v[226:229], v[78:81], v[18:21]
	v_mfma_f32_16x16x32_bf16 v[2:5], v[230:233], v[78:81], v[2:5]
	s_waitcnt lgkmcnt(0)
	v_mfma_f32_16x16x32_bf16 v[62:65], v[234:237], v[82:85], v[62:65]
	v_mfma_f32_16x16x32_bf16 v[46:49], v[238:241], v[82:85], v[46:49]
	v_mfma_f32_16x16x32_bf16 v[30:33], v[242:245], v[82:85], v[30:33]
	v_mfma_f32_16x16x32_bf16 v[14:17], v[246:249], v[82:85], v[14:17]
	v_mfma_f32_16x16x32_bf16 v[58:61], v[234:237], v[86:89], v[58:61]
	v_mfma_f32_16x16x32_bf16 v[42:45], v[238:241], v[86:89], v[42:45]
	v_mfma_f32_16x16x32_bf16 v[26:29], v[242:245], v[86:89], v[26:29]
	v_mfma_f32_16x16x32_bf16 v[10:13], v[246:249], v[86:89], v[10:13]
	v_mfma_f32_16x16x32_bf16 v[54:57], v[234:237], v[90:93], v[54:57]
	v_mfma_f32_16x16x32_bf16 v[38:41], v[238:241], v[90:93], v[38:41]
	v_mfma_f32_16x16x32_bf16 v[22:25], v[242:245], v[90:93], v[22:25]
	v_mfma_f32_16x16x32_bf16 v[6:9], v[246:249], v[90:93], v[6:9]
	v_mfma_f32_16x16x32_bf16 v[50:53], v[234:237], v[94:97], v[50:53]
	v_mfma_f32_16x16x32_bf16 v[34:37], v[238:241], v[94:97], v[34:37]
	v_mfma_f32_16x16x32_bf16 v[18:21], v[242:245], v[94:97], v[18:21]
	v_mfma_f32_16x16x32_bf16 v[2:5], v[246:249], v[94:97], v[2:5]
	s_waitcnt vmcnt(8)
	s_barrier
	ds_read_b128 v[218:221], v102 offset:0
	ds_read_b128 v[222:225], v102 offset:2048
	ds_read_b128 v[226:229], v102 offset:4096
	ds_read_b128 v[230:233], v102 offset:6144
	ds_read_b128 v[234:237], v103 offset:0
	ds_read_b128 v[238:241], v103 offset:2048
	ds_read_b128 v[242:245], v103 offset:4096
	ds_read_b128 v[246:249], v103 offset:6144
	s_add_u32 m0, s4, 0x8000
	s_nop 0
	global_load_lds_dwordx4 v98, s[6:7]
	s_add_u32 m0, s4, 0x8400
	s_nop 0
	global_load_lds_dwordx4 v99, s[6:7]
	s_add_u32 m0, s4, 0x8800
	s_nop 0
	global_load_lds_dwordx4 v100, s[6:7]
	s_add_u32 m0, s4, 0x8c00
	s_nop 0
	global_load_lds_dwordx4 v101, s[6:7]
	v_add_u32_e32 v98, 0x80, v98
	v_add_u32_e32 v99, 0x80, v99
	v_add_u32_e32 v100, 0x80, v100
	v_add_u32_e32 v101, 0x80, v101
	s_waitcnt lgkmcnt(4)
	v_mfma_f32_16x16x32_bf16 v[106:109], v[218:221], v[66:69], v[106:109]
	v_mfma_f32_16x16x32_bf16 v[122:125], v[222:225], v[66:69], v[122:125]
	v_mfma_f32_16x16x32_bf16 v[138:141], v[226:229], v[66:69], v[138:141]
	v_mfma_f32_16x16x32_bf16 v[162:165], v[230:233], v[66:69], v[162:165]
	v_mfma_f32_16x16x32_bf16 v[110:113], v[218:221], v[70:73], v[110:113]
	v_mfma_f32_16x16x32_bf16 v[126:129], v[222:225], v[70:73], v[126:129]
	v_mfma_f32_16x16x32_bf16 v[142:145], v[226:229], v[70:73], v[142:145]
	v_mfma_f32_16x16x32_bf16 v[166:169], v[230:233], v[70:73], v[166:169]
	v_mfma_f32_16x16x32_bf16 v[114:117], v[218:221], v[74:77], v[114:117]
	v_mfma_f32_16x16x32_bf16 v[130:133], v[222:225], v[74:77], v[130:133]
	v_mfma_f32_16x16x32_bf16 v[154:157], v[226:229], v[74:77], v[154:157]
	v_mfma_f32_16x16x32_bf16 v[170:173], v[230:233], v[74:77], v[170:173]
	v_mfma_f32_16x16x32_bf16 v[118:121], v[218:221], v[78:81], v[118:121]
	v_mfma_f32_16x16x32_bf16 v[134:137], v[222:225], v[78:81], v[134:137]
	v_mfma_f32_16x16x32_bf16 v[158:161], v[226:229], v[78:81], v[158:161]
	v_mfma_f32_16x16x32_bf16 v[174:177], v[230:233], v[78:81], v[174:177]
	s_waitcnt lgkmcnt(0)
	v_mfma_f32_16x16x32_bf16 v[106:109], v[234:237], v[82:85], v[106:109]
	v_mfma_f32_16x16x32_bf16 v[122:125], v[238:241], v[82:85], v[122:125]
	v_mfma_f32_16x16x32_bf16 v[138:141], v[242:245], v[82:85], v[138:141]
	v_mfma_f32_16x16x32_bf16 v[162:165], v[246:249], v[82:85], v[162:165]
	v_mfma_f32_16x16x32_bf16 v[110:113], v[234:237], v[86:89], v[110:113]
	v_mfma_f32_16x16x32_bf16 v[126:129], v[238:241], v[86:89], v[126:129]
	v_mfma_f32_16x16x32_bf16 v[142:145], v[242:245], v[86:89], v[142:145]
	v_mfma_f32_16x16x32_bf16 v[166:169], v[246:249], v[86:89], v[166:169]
	v_mfma_f32_16x16x32_bf16 v[114:117], v[234:237], v[90:93], v[114:117]
	v_mfma_f32_16x16x32_bf16 v[130:133], v[238:241], v[90:93], v[130:133]
	v_mfma_f32_16x16x32_bf16 v[154:157], v[242:245], v[90:93], v[154:157]
	v_mfma_f32_16x16x32_bf16 v[170:173], v[246:249], v[90:93], v[170:173]
	v_mfma_f32_16x16x32_bf16 v[118:121], v[234:237], v[94:97], v[118:121]
	v_mfma_f32_16x16x32_bf16 v[134:137], v[238:241], v[94:97], v[134:137]
	v_mfma_f32_16x16x32_bf16 v[158:161], v[242:245], v[94:97], v[158:161]
	v_mfma_f32_16x16x32_bf16 v[174:177], v[246:249], v[94:97], v[174:177]
	s_waitcnt vmcnt(4)
	s_barrier
	ds_read_b128 v[218:221], v102 offset:16384
	ds_read_b128 v[222:225], v102 offset:18432
	ds_read_b128 v[226:229], v102 offset:20480
	ds_read_b128 v[230:233], v102 offset:22528
	ds_read_b128 v[66:69], v104 offset:49152
	ds_read_b128 v[70:73], v104 offset:51200
	ds_read_b128 v[74:77], v104 offset:53248
	ds_read_b128 v[78:81], v104 offset:55296
	ds_read_b128 v[234:237], v103 offset:16384
	ds_read_b128 v[238:241], v103 offset:18432
	ds_read_b128 v[242:245], v103 offset:20480
	ds_read_b128 v[246:249], v103 offset:22528
	ds_read_b128 v[82:85], v105 offset:49152
	ds_read_b128 v[86:89], v105 offset:51200
	ds_read_b128 v[90:93], v105 offset:53248
	ds_read_b128 v[94:97], v105 offset:55296
	s_add_u32 m0, s4, 0x0
	s_nop 0
	global_load_lds_dwordx4 v98, s[28:29]
	s_add_u32 m0, s4, 0x400
	s_nop 0
	global_load_lds_dwordx4 v99, s[28:29]
	s_add_u32 m0, s4, 0x800
	s_nop 0
	global_load_lds_dwordx4 v100, s[28:29]
	s_add_u32 m0, s4, 0xc00
	s_nop 0
	global_load_lds_dwordx4 v101, s[28:29]
	s_add_u32 m0, s4, 0x10000
	s_nop 0
	global_load_lds_dwordx4 v98, s[48:49]
	s_add_u32 m0, s4, 0x10400
	s_nop 0
	global_load_lds_dwordx4 v99, s[48:49]
	s_add_u32 m0, s4, 0x10800
	s_nop 0
	global_load_lds_dwordx4 v100, s[48:49]
	s_add_u32 m0, s4, 0x10c00
	s_nop 0
	global_load_lds_dwordx4 v101, s[48:49]
	s_waitcnt lgkmcnt(8)
	v_mfma_f32_16x16x32_bf16 v[62:65], v[218:221], v[66:69], v[62:65]
	v_mfma_f32_16x16x32_bf16 v[46:49], v[222:225], v[66:69], v[46:49]
	v_mfma_f32_16x16x32_bf16 v[30:33], v[226:229], v[66:69], v[30:33]
	v_mfma_f32_16x16x32_bf16 v[14:17], v[230:233], v[66:69], v[14:17]
	v_mfma_f32_16x16x32_bf16 v[58:61], v[218:221], v[70:73], v[58:61]
	v_mfma_f32_16x16x32_bf16 v[42:45], v[222:225], v[70:73], v[42:45]
	v_mfma_f32_16x16x32_bf16 v[26:29], v[226:229], v[70:73], v[26:29]
	v_mfma_f32_16x16x32_bf16 v[10:13], v[230:233], v[70:73], v[10:13]
	v_mfma_f32_16x16x32_bf16 v[54:57], v[218:221], v[74:77], v[54:57]
	v_mfma_f32_16x16x32_bf16 v[38:41], v[222:225], v[74:77], v[38:41]
	v_mfma_f32_16x16x32_bf16 v[22:25], v[226:229], v[74:77], v[22:25]
	v_mfma_f32_16x16x32_bf16 v[6:9], v[230:233], v[74:77], v[6:9]
	v_mfma_f32_16x16x32_bf16 v[50:53], v[218:221], v[78:81], v[50:53]
	v_mfma_f32_16x16x32_bf16 v[34:37], v[222:225], v[78:81], v[34:37]
	v_mfma_f32_16x16x32_bf16 v[18:21], v[226:229], v[78:81], v[18:21]
	v_mfma_f32_16x16x32_bf16 v[2:5], v[230:233], v[78:81], v[2:5]
	s_waitcnt lgkmcnt(0)
	v_mfma_f32_16x16x32_bf16 v[62:65], v[234:237], v[82:85], v[62:65]
	v_mfma_f32_16x16x32_bf16 v[46:49], v[238:241], v[82:85], v[46:49]
	v_mfma_f32_16x16x32_bf16 v[30:33], v[242:245], v[82:85], v[30:33]
	v_mfma_f32_16x16x32_bf16 v[14:17], v[246:249], v[82:85], v[14:17]
	v_mfma_f32_16x16x32_bf16 v[58:61], v[234:237], v[86:89], v[58:61]
	v_mfma_f32_16x16x32_bf16 v[42:45], v[238:241], v[86:89], v[42:45]
	v_mfma_f32_16x16x32_bf16 v[26:29], v[242:245], v[86:89], v[26:29]
	v_mfma_f32_16x16x32_bf16 v[10:13], v[246:249], v[86:89], v[10:13]
	v_mfma_f32_16x16x32_bf16 v[54:57], v[234:237], v[90:93], v[54:57]
	v_mfma_f32_16x16x32_bf16 v[38:41], v[238:241], v[90:93], v[38:41]
	v_mfma_f32_16x16x32_bf16 v[22:25], v[242:245], v[90:93], v[22:25]
	v_mfma_f32_16x16x32_bf16 v[6:9], v[246:249], v[90:93], v[6:9]
	v_mfma_f32_16x16x32_bf16 v[50:53], v[234:237], v[94:97], v[50:53]
	v_mfma_f32_16x16x32_bf16 v[34:37], v[238:241], v[94:97], v[34:37]
	v_mfma_f32_16x16x32_bf16 v[18:21], v[242:245], v[94:97], v[18:21]
	v_mfma_f32_16x16x32_bf16 v[2:5], v[246:249], v[94:97], v[2:5]
	s_waitcnt vmcnt(8)
	s_barrier
	ds_read_b128 v[218:221], v102 offset:32768
	ds_read_b128 v[222:225], v102 offset:34816
	ds_read_b128 v[226:229], v102 offset:36864
	ds_read_b128 v[230:233], v102 offset:38912
	ds_read_b128 v[234:237], v103 offset:32768
	ds_read_b128 v[238:241], v103 offset:34816
	ds_read_b128 v[242:245], v103 offset:36864
	ds_read_b128 v[246:249], v103 offset:38912
	s_add_u32 m0, s4, 0x4000
	s_nop 0
	global_load_lds_dwordx4 v98, s[6:7]
	s_add_u32 m0, s4, 0x4400
	s_nop 0
	global_load_lds_dwordx4 v99, s[6:7]
	s_add_u32 m0, s4, 0x4800
	s_nop 0
	global_load_lds_dwordx4 v100, s[6:7]
	s_add_u32 m0, s4, 0x4c00
	s_nop 0
	global_load_lds_dwordx4 v101, s[6:7]
	v_add_u32_e32 v98, 0x80, v98
	v_add_u32_e32 v99, 0x80, v99
	v_add_u32_e32 v100, 0x80, v100
	v_add_u32_e32 v101, 0x80, v101
	s_waitcnt lgkmcnt(4)
	v_mfma_f32_16x16x32_bf16 v[106:109], v[218:221], v[66:69], v[106:109]
	v_mfma_f32_16x16x32_bf16 v[122:125], v[222:225], v[66:69], v[122:125]
	v_mfma_f32_16x16x32_bf16 v[138:141], v[226:229], v[66:69], v[138:141]
	v_mfma_f32_16x16x32_bf16 v[162:165], v[230:233], v[66:69], v[162:165]
	v_mfma_f32_16x16x32_bf16 v[110:113], v[218:221], v[70:73], v[110:113]
	v_mfma_f32_16x16x32_bf16 v[126:129], v[222:225], v[70:73], v[126:129]
	v_mfma_f32_16x16x32_bf16 v[142:145], v[226:229], v[70:73], v[142:145]
	v_mfma_f32_16x16x32_bf16 v[166:169], v[230:233], v[70:73], v[166:169]
	v_mfma_f32_16x16x32_bf16 v[114:117], v[218:221], v[74:77], v[114:117]
	v_mfma_f32_16x16x32_bf16 v[130:133], v[222:225], v[74:77], v[130:133]
	v_mfma_f32_16x16x32_bf16 v[154:157], v[226:229], v[74:77], v[154:157]
	v_mfma_f32_16x16x32_bf16 v[170:173], v[230:233], v[74:77], v[170:173]
	v_mfma_f32_16x16x32_bf16 v[118:121], v[218:221], v[78:81], v[118:121]
	v_mfma_f32_16x16x32_bf16 v[134:137], v[222:225], v[78:81], v[134:137]
	v_mfma_f32_16x16x32_bf16 v[158:161], v[226:229], v[78:81], v[158:161]
	v_mfma_f32_16x16x32_bf16 v[174:177], v[230:233], v[78:81], v[174:177]
	s_waitcnt lgkmcnt(0)
	v_mfma_f32_16x16x32_bf16 v[106:109], v[234:237], v[82:85], v[106:109]
	v_mfma_f32_16x16x32_bf16 v[122:125], v[238:241], v[82:85], v[122:125]
	v_mfma_f32_16x16x32_bf16 v[138:141], v[242:245], v[82:85], v[138:141]
	v_mfma_f32_16x16x32_bf16 v[162:165], v[246:249], v[82:85], v[162:165]
	v_mfma_f32_16x16x32_bf16 v[110:113], v[234:237], v[86:89], v[110:113]
	v_mfma_f32_16x16x32_bf16 v[126:129], v[238:241], v[86:89], v[126:129]
	v_mfma_f32_16x16x32_bf16 v[142:145], v[242:245], v[86:89], v[142:145]
	v_mfma_f32_16x16x32_bf16 v[166:169], v[246:249], v[86:89], v[166:169]
	v_mfma_f32_16x16x32_bf16 v[114:117], v[234:237], v[90:93], v[114:117]
	v_mfma_f32_16x16x32_bf16 v[130:133], v[238:241], v[90:93], v[130:133]
	v_mfma_f32_16x16x32_bf16 v[154:157], v[242:245], v[90:93], v[154:157]
	v_mfma_f32_16x16x32_bf16 v[170:173], v[246:249], v[90:93], v[170:173]
	v_mfma_f32_16x16x32_bf16 v[118:121], v[234:237], v[94:97], v[118:121]
	v_mfma_f32_16x16x32_bf16 v[134:137], v[238:241], v[94:97], v[134:137]
	v_mfma_f32_16x16x32_bf16 v[158:161], v[242:245], v[94:97], v[158:161]
	v_mfma_f32_16x16x32_bf16 v[174:177], v[246:249], v[94:97], v[174:177]
	s_waitcnt vmcnt(4)
	s_barrier
	ds_read_b128 v[218:221], v102 offset:0
	ds_read_b128 v[222:225], v102 offset:2048
	ds_read_b128 v[226:229], v102 offset:4096
	ds_read_b128 v[230:233], v102 offset:6144
	ds_read_b128 v[66:69], v250 offset:49152
	ds_read_b128 v[70:73], v250 offset:51200
	ds_read_b128 v[74:77], v250 offset:53248
	ds_read_b128 v[78:81], v250 offset:55296
	ds_read_b128 v[234:237], v103 offset:0
	ds_read_b128 v[238:241], v103 offset:2048
	ds_read_b128 v[242:245], v103 offset:4096
	ds_read_b128 v[246:249], v103 offset:6144
	ds_read_b128 v[82:85], v251 offset:49152
	ds_read_b128 v[86:89], v251 offset:51200
	ds_read_b128 v[90:93], v251 offset:53248
	ds_read_b128 v[94:97], v251 offset:55296
	s_add_u32 m0, s4, 0x8000
	s_nop 0
	global_load_lds_dwordx4 v98, s[28:29]
	s_add_u32 m0, s4, 0x8400
	s_nop 0
	global_load_lds_dwordx4 v99, s[28:29]
	s_add_u32 m0, s4, 0x8800
	s_nop 0
	global_load_lds_dwordx4 v100, s[28:29]
	s_add_u32 m0, s4, 0x8c00
	s_nop 0
	global_load_lds_dwordx4 v101, s[28:29]
	s_add_u32 m0, s4, 0xc000
	s_nop 0
	global_load_lds_dwordx4 v98, s[48:49]
	s_add_u32 m0, s4, 0xc400
	s_nop 0
	global_load_lds_dwordx4 v99, s[48:49]
	s_add_u32 m0, s4, 0xc800
	s_nop 0
	global_load_lds_dwordx4 v100, s[48:49]
	s_add_u32 m0, s4, 0xcc00
	s_nop 0
	global_load_lds_dwordx4 v101, s[48:49]
	s_waitcnt lgkmcnt(8)
	v_mfma_f32_16x16x32_bf16 v[62:65], v[218:221], v[66:69], v[62:65]
	v_mfma_f32_16x16x32_bf16 v[46:49], v[222:225], v[66:69], v[46:49]
	v_mfma_f32_16x16x32_bf16 v[30:33], v[226:229], v[66:69], v[30:33]
	v_mfma_f32_16x16x32_bf16 v[14:17], v[230:233], v[66:69], v[14:17]
	v_mfma_f32_16x16x32_bf16 v[58:61], v[218:221], v[70:73], v[58:61]
	v_mfma_f32_16x16x32_bf16 v[42:45], v[222:225], v[70:73], v[42:45]
	v_mfma_f32_16x16x32_bf16 v[26:29], v[226:229], v[70:73], v[26:29]
	v_mfma_f32_16x16x32_bf16 v[10:13], v[230:233], v[70:73], v[10:13]
	v_mfma_f32_16x16x32_bf16 v[54:57], v[218:221], v[74:77], v[54:57]
	v_mfma_f32_16x16x32_bf16 v[38:41], v[222:225], v[74:77], v[38:41]
	v_mfma_f32_16x16x32_bf16 v[22:25], v[226:229], v[74:77], v[22:25]
	v_mfma_f32_16x16x32_bf16 v[6:9], v[230:233], v[74:77], v[6:9]
	v_mfma_f32_16x16x32_bf16 v[50:53], v[218:221], v[78:81], v[50:53]
	v_mfma_f32_16x16x32_bf16 v[34:37], v[222:225], v[78:81], v[34:37]
	v_mfma_f32_16x16x32_bf16 v[18:21], v[226:229], v[78:81], v[18:21]
	v_mfma_f32_16x16x32_bf16 v[2:5], v[230:233], v[78:81], v[2:5]
	s_waitcnt lgkmcnt(0)
	v_mfma_f32_16x16x32_bf16 v[62:65], v[234:237], v[82:85], v[62:65]
	v_mfma_f32_16x16x32_bf16 v[46:49], v[238:241], v[82:85], v[46:49]
	v_mfma_f32_16x16x32_bf16 v[30:33], v[242:245], v[82:85], v[30:33]
	v_mfma_f32_16x16x32_bf16 v[14:17], v[246:249], v[82:85], v[14:17]
	v_mfma_f32_16x16x32_bf16 v[58:61], v[234:237], v[86:89], v[58:61]
	v_mfma_f32_16x16x32_bf16 v[42:45], v[238:241], v[86:89], v[42:45]
	v_mfma_f32_16x16x32_bf16 v[26:29], v[242:245], v[86:89], v[26:29]
	v_mfma_f32_16x16x32_bf16 v[10:13], v[246:249], v[86:89], v[10:13]
	v_mfma_f32_16x16x32_bf16 v[54:57], v[234:237], v[90:93], v[54:57]
	v_mfma_f32_16x16x32_bf16 v[38:41], v[238:241], v[90:93], v[38:41]
	v_mfma_f32_16x16x32_bf16 v[22:25], v[242:245], v[90:93], v[22:25]
	v_mfma_f32_16x16x32_bf16 v[6:9], v[246:249], v[90:93], v[6:9]
	v_mfma_f32_16x16x32_bf16 v[50:53], v[234:237], v[94:97], v[50:53]
	v_mfma_f32_16x16x32_bf16 v[34:37], v[238:241], v[94:97], v[34:37]
	v_mfma_f32_16x16x32_bf16 v[18:21], v[242:245], v[94:97], v[18:21]
	v_mfma_f32_16x16x32_bf16 v[2:5], v[246:249], v[94:97], v[2:5]
	s_waitcnt vmcnt(8)
	s_barrier
	ds_read_b128 v[218:221], v102 offset:16384
	ds_read_b128 v[222:225], v102 offset:18432
	ds_read_b128 v[226:229], v102 offset:20480
	ds_read_b128 v[230:233], v102 offset:22528
	ds_read_b128 v[234:237], v103 offset:16384
	ds_read_b128 v[238:241], v103 offset:18432
	ds_read_b128 v[242:245], v103 offset:20480
	ds_read_b128 v[246:249], v103 offset:22528
	s_add_u32 m0, s4, 0x0
	s_nop 0
	global_load_lds_dwordx4 v98, s[6:7]
	s_add_u32 m0, s4, 0x400
	s_nop 0
	global_load_lds_dwordx4 v99, s[6:7]
	s_add_u32 m0, s4, 0x800
	s_nop 0
	global_load_lds_dwordx4 v100, s[6:7]
	s_add_u32 m0, s4, 0xc00
	s_nop 0
	global_load_lds_dwordx4 v101, s[6:7]
	v_add_u32_e32 v98, 0x80, v98
	v_add_u32_e32 v99, 0x80, v99
	v_add_u32_e32 v100, 0x80, v100
	v_add_u32_e32 v101, 0x80, v101
	s_waitcnt lgkmcnt(4)
	v_mfma_f32_16x16x32_bf16 v[106:109], v[218:221], v[66:69], v[106:109]
	v_mfma_f32_16x16x32_bf16 v[122:125], v[222:225], v[66:69], v[122:125]
	v_mfma_f32_16x16x32_bf16 v[138:141], v[226:229], v[66:69], v[138:141]
	v_mfma_f32_16x16x32_bf16 v[162:165], v[230:233], v[66:69], v[162:165]
	v_mfma_f32_16x16x32_bf16 v[110:113], v[218:221], v[70:73], v[110:113]
	v_mfma_f32_16x16x32_bf16 v[126:129], v[222:225], v[70:73], v[126:129]
	v_mfma_f32_16x16x32_bf16 v[142:145], v[226:229], v[70:73], v[142:145]
	v_mfma_f32_16x16x32_bf16 v[166:169], v[230:233], v[70:73], v[166:169]
	v_mfma_f32_16x16x32_bf16 v[114:117], v[218:221], v[74:77], v[114:117]
	v_mfma_f32_16x16x32_bf16 v[130:133], v[222:225], v[74:77], v[130:133]
	v_mfma_f32_16x16x32_bf16 v[154:157], v[226:229], v[74:77], v[154:157]
	v_mfma_f32_16x16x32_bf16 v[170:173], v[230:233], v[74:77], v[170:173]
	v_mfma_f32_16x16x32_bf16 v[118:121], v[218:221], v[78:81], v[118:121]
	v_mfma_f32_16x16x32_bf16 v[134:137], v[222:225], v[78:81], v[134:137]
	v_mfma_f32_16x16x32_bf16 v[158:161], v[226:229], v[78:81], v[158:161]
	v_mfma_f32_16x16x32_bf16 v[174:177], v[230:233], v[78:81], v[174:177]
	s_waitcnt lgkmcnt(0)
	v_mfma_f32_16x16x32_bf16 v[106:109], v[234:237], v[82:85], v[106:109]
	v_mfma_f32_16x16x32_bf16 v[122:125], v[238:241], v[82:85], v[122:125]
	v_mfma_f32_16x16x32_bf16 v[138:141], v[242:245], v[82:85], v[138:141]
	v_mfma_f32_16x16x32_bf16 v[162:165], v[246:249], v[82:85], v[162:165]
	v_mfma_f32_16x16x32_bf16 v[110:113], v[234:237], v[86:89], v[110:113]
	v_mfma_f32_16x16x32_bf16 v[126:129], v[238:241], v[86:89], v[126:129]
	v_mfma_f32_16x16x32_bf16 v[142:145], v[242:245], v[86:89], v[142:145]
	v_mfma_f32_16x16x32_bf16 v[166:169], v[246:249], v[86:89], v[166:169]
	v_mfma_f32_16x16x32_bf16 v[114:117], v[234:237], v[90:93], v[114:117]
	v_mfma_f32_16x16x32_bf16 v[130:133], v[238:241], v[90:93], v[130:133]
	v_mfma_f32_16x16x32_bf16 v[154:157], v[242:245], v[90:93], v[154:157]
	v_mfma_f32_16x16x32_bf16 v[170:173], v[246:249], v[90:93], v[170:173]
	v_mfma_f32_16x16x32_bf16 v[118:121], v[234:237], v[94:97], v[118:121]
	v_mfma_f32_16x16x32_bf16 v[134:137], v[238:241], v[94:97], v[134:137]
	v_mfma_f32_16x16x32_bf16 v[158:161], v[242:245], v[94:97], v[158:161]
	v_mfma_f32_16x16x32_bf16 v[174:177], v[246:249], v[94:97], v[174:177]
	s_waitcnt vmcnt(4)
	s_barrier
	ds_read_b128 v[218:221], v102 offset:32768
	ds_read_b128 v[222:225], v102 offset:34816
	ds_read_b128 v[226:229], v102 offset:36864
	ds_read_b128 v[230:233], v102 offset:38912
	ds_read_b128 v[66:69], v104 offset:49152
	ds_read_b128 v[70:73], v104 offset:51200
	ds_read_b128 v[74:77], v104 offset:53248
	ds_read_b128 v[78:81], v104 offset:55296
	ds_read_b128 v[234:237], v103 offset:32768
	ds_read_b128 v[238:241], v103 offset:34816
	ds_read_b128 v[242:245], v103 offset:36864
	ds_read_b128 v[246:249], v103 offset:38912
	ds_read_b128 v[82:85], v105 offset:49152
	ds_read_b128 v[86:89], v105 offset:51200
	ds_read_b128 v[90:93], v105 offset:53248
	ds_read_b128 v[94:97], v105 offset:55296
	s_add_u32 m0, s4, 0x4000
	s_nop 0
	global_load_lds_dwordx4 v98, s[28:29]
	s_add_u32 m0, s4, 0x4400
	s_nop 0
	global_load_lds_dwordx4 v99, s[28:29]
	s_add_u32 m0, s4, 0x4800
	s_nop 0
	global_load_lds_dwordx4 v100, s[28:29]
	s_add_u32 m0, s4, 0x4c00
	s_nop 0
	global_load_lds_dwordx4 v101, s[28:29]
	s_add_u32 m0, s4, 0x10000
	s_nop 0
	global_load_lds_dwordx4 v98, s[48:49]
	s_add_u32 m0, s4, 0x10400
	s_nop 0
	global_load_lds_dwordx4 v99, s[48:49]
	s_add_u32 m0, s4, 0x10800
	s_nop 0
	global_load_lds_dwordx4 v100, s[48:49]
	s_add_u32 m0, s4, 0x10c00
	s_nop 0
	global_load_lds_dwordx4 v101, s[48:49]
	s_waitcnt lgkmcnt(8)
	v_mfma_f32_16x16x32_bf16 v[62:65], v[218:221], v[66:69], v[62:65]
	v_mfma_f32_16x16x32_bf16 v[46:49], v[222:225], v[66:69], v[46:49]
	v_mfma_f32_16x16x32_bf16 v[30:33], v[226:229], v[66:69], v[30:33]
	v_mfma_f32_16x16x32_bf16 v[14:17], v[230:233], v[66:69], v[14:17]
	v_mfma_f32_16x16x32_bf16 v[58:61], v[218:221], v[70:73], v[58:61]
	v_mfma_f32_16x16x32_bf16 v[42:45], v[222:225], v[70:73], v[42:45]
	v_mfma_f32_16x16x32_bf16 v[26:29], v[226:229], v[70:73], v[26:29]
	v_mfma_f32_16x16x32_bf16 v[10:13], v[230:233], v[70:73], v[10:13]
	v_mfma_f32_16x16x32_bf16 v[54:57], v[218:221], v[74:77], v[54:57]
	v_mfma_f32_16x16x32_bf16 v[38:41], v[222:225], v[74:77], v[38:41]
	v_mfma_f32_16x16x32_bf16 v[22:25], v[226:229], v[74:77], v[22:25]
	v_mfma_f32_16x16x32_bf16 v[6:9], v[230:233], v[74:77], v[6:9]
	v_mfma_f32_16x16x32_bf16 v[50:53], v[218:221], v[78:81], v[50:53]
	v_mfma_f32_16x16x32_bf16 v[34:37], v[222:225], v[78:81], v[34:37]
	v_mfma_f32_16x16x32_bf16 v[18:21], v[226:229], v[78:81], v[18:21]
	v_mfma_f32_16x16x32_bf16 v[2:5], v[230:233], v[78:81], v[2:5]
	s_waitcnt lgkmcnt(0)
	v_mfma_f32_16x16x32_bf16 v[62:65], v[234:237], v[82:85], v[62:65]
	v_mfma_f32_16x16x32_bf16 v[46:49], v[238:241], v[82:85], v[46:49]
	v_mfma_f32_16x16x32_bf16 v[30:33], v[242:245], v[82:85], v[30:33]
	v_mfma_f32_16x16x32_bf16 v[14:17], v[246:249], v[82:85], v[14:17]
	v_mfma_f32_16x16x32_bf16 v[58:61], v[234:237], v[86:89], v[58:61]
	v_mfma_f32_16x16x32_bf16 v[42:45], v[238:241], v[86:89], v[42:45]
	v_mfma_f32_16x16x32_bf16 v[26:29], v[242:245], v[86:89], v[26:29]
	v_mfma_f32_16x16x32_bf16 v[10:13], v[246:249], v[86:89], v[10:13]
	v_mfma_f32_16x16x32_bf16 v[54:57], v[234:237], v[90:93], v[54:57]
	v_mfma_f32_16x16x32_bf16 v[38:41], v[238:241], v[90:93], v[38:41]
	v_mfma_f32_16x16x32_bf16 v[22:25], v[242:245], v[90:93], v[22:25]
	v_mfma_f32_16x16x32_bf16 v[6:9], v[246:249], v[90:93], v[6:9]
	v_mfma_f32_16x16x32_bf16 v[50:53], v[234:237], v[94:97], v[50:53]
	v_mfma_f32_16x16x32_bf16 v[34:37], v[238:241], v[94:97], v[34:37]
	v_mfma_f32_16x16x32_bf16 v[18:21], v[242:245], v[94:97], v[18:21]
	v_mfma_f32_16x16x32_bf16 v[2:5], v[246:249], v[94:97], v[2:5]
	s_waitcnt vmcnt(8)
	s_barrier
	ds_read_b128 v[218:221], v102 offset:0
	ds_read_b128 v[222:225], v102 offset:2048
	ds_read_b128 v[226:229], v102 offset:4096
	ds_read_b128 v[230:233], v102 offset:6144
	ds_read_b128 v[234:237], v103 offset:0
	ds_read_b128 v[238:241], v103 offset:2048
	ds_read_b128 v[242:245], v103 offset:4096
	ds_read_b128 v[246:249], v103 offset:6144
	s_add_u32 m0, s4, 0x8000
	s_nop 0
	global_load_lds_dwordx4 v98, s[6:7]
	s_add_u32 m0, s4, 0x8400
	s_nop 0
	global_load_lds_dwordx4 v99, s[6:7]
	s_add_u32 m0, s4, 0x8800
	s_nop 0
	global_load_lds_dwordx4 v100, s[6:7]
	s_add_u32 m0, s4, 0x8c00
	s_nop 0
	global_load_lds_dwordx4 v101, s[6:7]
	v_add_u32_e32 v98, 0x80, v98
	v_add_u32_e32 v99, 0x80, v99
	v_add_u32_e32 v100, 0x80, v100
	v_add_u32_e32 v101, 0x80, v101
	s_waitcnt lgkmcnt(4)
	v_mfma_f32_16x16x32_bf16 v[106:109], v[218:221], v[66:69], v[106:109]
	v_mfma_f32_16x16x32_bf16 v[122:125], v[222:225], v[66:69], v[122:125]
	v_mfma_f32_16x16x32_bf16 v[138:141], v[226:229], v[66:69], v[138:141]
	v_mfma_f32_16x16x32_bf16 v[162:165], v[230:233], v[66:69], v[162:165]
	v_mfma_f32_16x16x32_bf16 v[110:113], v[218:221], v[70:73], v[110:113]
	v_mfma_f32_16x16x32_bf16 v[126:129], v[222:225], v[70:73], v[126:129]
	v_mfma_f32_16x16x32_bf16 v[142:145], v[226:229], v[70:73], v[142:145]
	v_mfma_f32_16x16x32_bf16 v[166:169], v[230:233], v[70:73], v[166:169]
	v_mfma_f32_16x16x32_bf16 v[114:117], v[218:221], v[74:77], v[114:117]
	v_mfma_f32_16x16x32_bf16 v[130:133], v[222:225], v[74:77], v[130:133]
	v_mfma_f32_16x16x32_bf16 v[154:157], v[226:229], v[74:77], v[154:157]
	v_mfma_f32_16x16x32_bf16 v[170:173], v[230:233], v[74:77], v[170:173]
	v_mfma_f32_16x16x32_bf16 v[118:121], v[218:221], v[78:81], v[118:121]
	v_mfma_f32_16x16x32_bf16 v[134:137], v[222:225], v[78:81], v[134:137]
	v_mfma_f32_16x16x32_bf16 v[158:161], v[226:229], v[78:81], v[158:161]
	v_mfma_f32_16x16x32_bf16 v[174:177], v[230:233], v[78:81], v[174:177]
	s_waitcnt lgkmcnt(0)
	v_mfma_f32_16x16x32_bf16 v[106:109], v[234:237], v[82:85], v[106:109]
	v_mfma_f32_16x16x32_bf16 v[122:125], v[238:241], v[82:85], v[122:125]
	v_mfma_f32_16x16x32_bf16 v[138:141], v[242:245], v[82:85], v[138:141]
	v_mfma_f32_16x16x32_bf16 v[162:165], v[246:249], v[82:85], v[162:165]
	v_mfma_f32_16x16x32_bf16 v[110:113], v[234:237], v[86:89], v[110:113]
	v_mfma_f32_16x16x32_bf16 v[126:129], v[238:241], v[86:89], v[126:129]
	v_mfma_f32_16x16x32_bf16 v[142:145], v[242:245], v[86:89], v[142:145]
	v_mfma_f32_16x16x32_bf16 v[166:169], v[246:249], v[86:89], v[166:169]
	v_mfma_f32_16x16x32_bf16 v[114:117], v[234:237], v[90:93], v[114:117]
	v_mfma_f32_16x16x32_bf16 v[130:133], v[238:241], v[90:93], v[130:133]
	v_mfma_f32_16x16x32_bf16 v[154:157], v[242:245], v[90:93], v[154:157]
	v_mfma_f32_16x16x32_bf16 v[170:173], v[246:249], v[90:93], v[170:173]
	v_mfma_f32_16x16x32_bf16 v[118:121], v[234:237], v[94:97], v[118:121]
	v_mfma_f32_16x16x32_bf16 v[134:137], v[238:241], v[94:97], v[134:137]
	v_mfma_f32_16x16x32_bf16 v[158:161], v[242:245], v[94:97], v[158:161]
	v_mfma_f32_16x16x32_bf16 v[174:177], v[246:249], v[94:97], v[174:177]
	s_waitcnt vmcnt(4)
	s_barrier
	ds_read_b128 v[218:221], v102 offset:16384
	ds_read_b128 v[222:225], v102 offset:18432
	ds_read_b128 v[226:229], v102 offset:20480
	ds_read_b128 v[230:233], v102 offset:22528
	ds_read_b128 v[66:69], v250 offset:49152
	ds_read_b128 v[70:73], v250 offset:51200
	ds_read_b128 v[74:77], v250 offset:53248
	ds_read_b128 v[78:81], v250 offset:55296
	ds_read_b128 v[234:237], v103 offset:16384
	ds_read_b128 v[238:241], v103 offset:18432
	ds_read_b128 v[242:245], v103 offset:20480
	ds_read_b128 v[246:249], v103 offset:22528
	ds_read_b128 v[82:85], v251 offset:49152
	ds_read_b128 v[86:89], v251 offset:51200
	ds_read_b128 v[90:93], v251 offset:53248
	ds_read_b128 v[94:97], v251 offset:55296
	s_add_u32 m0, s4, 0x0
	s_nop 0
	global_load_lds_dwordx4 v98, s[28:29]
	s_add_u32 m0, s4, 0x400
	s_nop 0
	global_load_lds_dwordx4 v99, s[28:29]
	s_add_u32 m0, s4, 0x800
	s_nop 0
	global_load_lds_dwordx4 v100, s[28:29]
	s_add_u32 m0, s4, 0xc00
	s_nop 0
	global_load_lds_dwordx4 v101, s[28:29]
	s_add_u32 m0, s4, 0xc000
	s_nop 0
	global_load_lds_dwordx4 v98, s[48:49]
	s_add_u32 m0, s4, 0xc400
	s_nop 0
	global_load_lds_dwordx4 v99, s[48:49]
	s_add_u32 m0, s4, 0xc800
	s_nop 0
	global_load_lds_dwordx4 v100, s[48:49]
	s_add_u32 m0, s4, 0xcc00
	s_nop 0
	global_load_lds_dwordx4 v101, s[48:49]
	s_waitcnt lgkmcnt(8)
	v_mfma_f32_16x16x32_bf16 v[62:65], v[218:221], v[66:69], v[62:65]
	v_mfma_f32_16x16x32_bf16 v[46:49], v[222:225], v[66:69], v[46:49]
	v_mfma_f32_16x16x32_bf16 v[30:33], v[226:229], v[66:69], v[30:33]
	v_mfma_f32_16x16x32_bf16 v[14:17], v[230:233], v[66:69], v[14:17]
	v_mfma_f32_16x16x32_bf16 v[58:61], v[218:221], v[70:73], v[58:61]
	v_mfma_f32_16x16x32_bf16 v[42:45], v[222:225], v[70:73], v[42:45]
	v_mfma_f32_16x16x32_bf16 v[26:29], v[226:229], v[70:73], v[26:29]
	v_mfma_f32_16x16x32_bf16 v[10:13], v[230:233], v[70:73], v[10:13]
	v_mfma_f32_16x16x32_bf16 v[54:57], v[218:221], v[74:77], v[54:57]
	v_mfma_f32_16x16x32_bf16 v[38:41], v[222:225], v[74:77], v[38:41]
	v_mfma_f32_16x16x32_bf16 v[22:25], v[226:229], v[74:77], v[22:25]
	v_mfma_f32_16x16x32_bf16 v[6:9], v[230:233], v[74:77], v[6:9]
	v_mfma_f32_16x16x32_bf16 v[50:53], v[218:221], v[78:81], v[50:53]
	v_mfma_f32_16x16x32_bf16 v[34:37], v[222:225], v[78:81], v[34:37]
	v_mfma_f32_16x16x32_bf16 v[18:21], v[226:229], v[78:81], v[18:21]
	v_mfma_f32_16x16x32_bf16 v[2:5], v[230:233], v[78:81], v[2:5]
	s_waitcnt lgkmcnt(0)
	v_mfma_f32_16x16x32_bf16 v[62:65], v[234:237], v[82:85], v[62:65]
	v_mfma_f32_16x16x32_bf16 v[46:49], v[238:241], v[82:85], v[46:49]
	v_mfma_f32_16x16x32_bf16 v[30:33], v[242:245], v[82:85], v[30:33]
	v_mfma_f32_16x16x32_bf16 v[14:17], v[246:249], v[82:85], v[14:17]
	v_mfma_f32_16x16x32_bf16 v[58:61], v[234:237], v[86:89], v[58:61]
	v_mfma_f32_16x16x32_bf16 v[42:45], v[238:241], v[86:89], v[42:45]
	v_mfma_f32_16x16x32_bf16 v[26:29], v[242:245], v[86:89], v[26:29]
	v_mfma_f32_16x16x32_bf16 v[10:13], v[246:249], v[86:89], v[10:13]
	v_mfma_f32_16x16x32_bf16 v[54:57], v[234:237], v[90:93], v[54:57]
	v_mfma_f32_16x16x32_bf16 v[38:41], v[238:241], v[90:93], v[38:41]
	v_mfma_f32_16x16x32_bf16 v[22:25], v[242:245], v[90:93], v[22:25]
	v_mfma_f32_16x16x32_bf16 v[6:9], v[246:249], v[90:93], v[6:9]
	v_mfma_f32_16x16x32_bf16 v[50:53], v[234:237], v[94:97], v[50:53]
	v_mfma_f32_16x16x32_bf16 v[34:37], v[238:241], v[94:97], v[34:37]
	v_mfma_f32_16x16x32_bf16 v[18:21], v[242:245], v[94:97], v[18:21]
	v_mfma_f32_16x16x32_bf16 v[2:5], v[246:249], v[94:97], v[2:5]
	s_waitcnt vmcnt(8)
	s_barrier
	ds_read_b128 v[218:221], v102 offset:32768
	ds_read_b128 v[222:225], v102 offset:34816
	ds_read_b128 v[226:229], v102 offset:36864
	ds_read_b128 v[230:233], v102 offset:38912
	ds_read_b128 v[234:237], v103 offset:32768
	ds_read_b128 v[238:241], v103 offset:34816
	ds_read_b128 v[242:245], v103 offset:36864
	ds_read_b128 v[246:249], v103 offset:38912
	s_add_u32 m0, s4, 0x4000
	s_nop 0
	global_load_lds_dwordx4 v98, s[6:7]
	s_add_u32 m0, s4, 0x4400
	s_nop 0
	global_load_lds_dwordx4 v99, s[6:7]
	s_add_u32 m0, s4, 0x4800
	s_nop 0
	global_load_lds_dwordx4 v100, s[6:7]
	s_add_u32 m0, s4, 0x4c00
	s_nop 0
	global_load_lds_dwordx4 v101, s[6:7]
	v_add_u32_e32 v98, 0x80, v98
	v_add_u32_e32 v99, 0x80, v99
	v_add_u32_e32 v100, 0x80, v100
	v_add_u32_e32 v101, 0x80, v101
	s_waitcnt lgkmcnt(4)
	v_mfma_f32_16x16x32_bf16 v[106:109], v[218:221], v[66:69], v[106:109]
	v_mfma_f32_16x16x32_bf16 v[122:125], v[222:225], v[66:69], v[122:125]
	v_mfma_f32_16x16x32_bf16 v[138:141], v[226:229], v[66:69], v[138:141]
	v_mfma_f32_16x16x32_bf16 v[162:165], v[230:233], v[66:69], v[162:165]
	v_mfma_f32_16x16x32_bf16 v[110:113], v[218:221], v[70:73], v[110:113]
	v_mfma_f32_16x16x32_bf16 v[126:129], v[222:225], v[70:73], v[126:129]
	v_mfma_f32_16x16x32_bf16 v[142:145], v[226:229], v[70:73], v[142:145]
	v_mfma_f32_16x16x32_bf16 v[166:169], v[230:233], v[70:73], v[166:169]
	v_mfma_f32_16x16x32_bf16 v[114:117], v[218:221], v[74:77], v[114:117]
	v_mfma_f32_16x16x32_bf16 v[130:133], v[222:225], v[74:77], v[130:133]
	v_mfma_f32_16x16x32_bf16 v[154:157], v[226:229], v[74:77], v[154:157]
	v_mfma_f32_16x16x32_bf16 v[170:173], v[230:233], v[74:77], v[170:173]
	v_mfma_f32_16x16x32_bf16 v[118:121], v[218:221], v[78:81], v[118:121]
	v_mfma_f32_16x16x32_bf16 v[134:137], v[222:225], v[78:81], v[134:137]
	v_mfma_f32_16x16x32_bf16 v[158:161], v[226:229], v[78:81], v[158:161]
	v_mfma_f32_16x16x32_bf16 v[174:177], v[230:233], v[78:81], v[174:177]
	s_waitcnt lgkmcnt(0)
	v_mfma_f32_16x16x32_bf16 v[106:109], v[234:237], v[82:85], v[106:109]
	v_mfma_f32_16x16x32_bf16 v[122:125], v[238:241], v[82:85], v[122:125]
	v_mfma_f32_16x16x32_bf16 v[138:141], v[242:245], v[82:85], v[138:141]
	v_mfma_f32_16x16x32_bf16 v[162:165], v[246:249], v[82:85], v[162:165]
	v_mfma_f32_16x16x32_bf16 v[110:113], v[234:237], v[86:89], v[110:113]
	v_mfma_f32_16x16x32_bf16 v[126:129], v[238:241], v[86:89], v[126:129]
	v_mfma_f32_16x16x32_bf16 v[142:145], v[242:245], v[86:89], v[142:145]
	v_mfma_f32_16x16x32_bf16 v[166:169], v[246:249], v[86:89], v[166:169]
	v_mfma_f32_16x16x32_bf16 v[114:117], v[234:237], v[90:93], v[114:117]
	v_mfma_f32_16x16x32_bf16 v[130:133], v[238:241], v[90:93], v[130:133]
	v_mfma_f32_16x16x32_bf16 v[154:157], v[242:245], v[90:93], v[154:157]
	v_mfma_f32_16x16x32_bf16 v[170:173], v[246:249], v[90:93], v[170:173]
	v_mfma_f32_16x16x32_bf16 v[118:121], v[234:237], v[94:97], v[118:121]
	v_mfma_f32_16x16x32_bf16 v[134:137], v[238:241], v[94:97], v[134:137]
	v_mfma_f32_16x16x32_bf16 v[158:161], v[242:245], v[94:97], v[158:161]
	v_mfma_f32_16x16x32_bf16 v[174:177], v[246:249], v[94:97], v[174:177]
	s_waitcnt vmcnt(4)
	s_barrier
	ds_read_b128 v[218:221], v102 offset:0
	ds_read_b128 v[222:225], v102 offset:2048
	ds_read_b128 v[226:229], v102 offset:4096
	ds_read_b128 v[230:233], v102 offset:6144
	ds_read_b128 v[66:69], v104 offset:49152
	ds_read_b128 v[70:73], v104 offset:51200
	ds_read_b128 v[74:77], v104 offset:53248
	ds_read_b128 v[78:81], v104 offset:55296
	ds_read_b128 v[234:237], v103 offset:0
	ds_read_b128 v[238:241], v103 offset:2048
	ds_read_b128 v[242:245], v103 offset:4096
	ds_read_b128 v[246:249], v103 offset:6144
	ds_read_b128 v[82:85], v105 offset:49152
	ds_read_b128 v[86:89], v105 offset:51200
	ds_read_b128 v[90:93], v105 offset:53248
	ds_read_b128 v[94:97], v105 offset:55296
	s_add_u32 m0, s4, 0x8000
	s_nop 0
	global_load_lds_dwordx4 v98, s[28:29]
	s_add_u32 m0, s4, 0x8400
	s_nop 0
	global_load_lds_dwordx4 v99, s[28:29]
	s_add_u32 m0, s4, 0x8800
	s_nop 0
	global_load_lds_dwordx4 v100, s[28:29]
	s_add_u32 m0, s4, 0x8c00
	s_nop 0
	global_load_lds_dwordx4 v101, s[28:29]
	s_add_u32 m0, s4, 0x10000
	s_nop 0
	global_load_lds_dwordx4 v98, s[48:49]
	s_add_u32 m0, s4, 0x10400
	s_nop 0
	global_load_lds_dwordx4 v99, s[48:49]
	s_add_u32 m0, s4, 0x10800
	s_nop 0
	global_load_lds_dwordx4 v100, s[48:49]
	s_add_u32 m0, s4, 0x10c00
	s_nop 0
	global_load_lds_dwordx4 v101, s[48:49]
	s_waitcnt lgkmcnt(8)
	v_mfma_f32_16x16x32_bf16 v[62:65], v[218:221], v[66:69], v[62:65]
	v_mfma_f32_16x16x32_bf16 v[46:49], v[222:225], v[66:69], v[46:49]
	v_mfma_f32_16x16x32_bf16 v[30:33], v[226:229], v[66:69], v[30:33]
	v_mfma_f32_16x16x32_bf16 v[14:17], v[230:233], v[66:69], v[14:17]
	v_mfma_f32_16x16x32_bf16 v[58:61], v[218:221], v[70:73], v[58:61]
	v_mfma_f32_16x16x32_bf16 v[42:45], v[222:225], v[70:73], v[42:45]
	v_mfma_f32_16x16x32_bf16 v[26:29], v[226:229], v[70:73], v[26:29]
	v_mfma_f32_16x16x32_bf16 v[10:13], v[230:233], v[70:73], v[10:13]
	v_mfma_f32_16x16x32_bf16 v[54:57], v[218:221], v[74:77], v[54:57]
	v_mfma_f32_16x16x32_bf16 v[38:41], v[222:225], v[74:77], v[38:41]
	v_mfma_f32_16x16x32_bf16 v[22:25], v[226:229], v[74:77], v[22:25]
	v_mfma_f32_16x16x32_bf16 v[6:9], v[230:233], v[74:77], v[6:9]
	v_mfma_f32_16x16x32_bf16 v[50:53], v[218:221], v[78:81], v[50:53]
	v_mfma_f32_16x16x32_bf16 v[34:37], v[222:225], v[78:81], v[34:37]
	v_mfma_f32_16x16x32_bf16 v[18:21], v[226:229], v[78:81], v[18:21]
	v_mfma_f32_16x16x32_bf16 v[2:5], v[230:233], v[78:81], v[2:5]
	s_waitcnt lgkmcnt(0)
	v_mfma_f32_16x16x32_bf16 v[62:65], v[234:237], v[82:85], v[62:65]
	v_mfma_f32_16x16x32_bf16 v[46:49], v[238:241], v[82:85], v[46:49]
	v_mfma_f32_16x16x32_bf16 v[30:33], v[242:245], v[82:85], v[30:33]
	v_mfma_f32_16x16x32_bf16 v[14:17], v[246:249], v[82:85], v[14:17]
	v_mfma_f32_16x16x32_bf16 v[58:61], v[234:237], v[86:89], v[58:61]
	v_mfma_f32_16x16x32_bf16 v[42:45], v[238:241], v[86:89], v[42:45]
	v_mfma_f32_16x16x32_bf16 v[26:29], v[242:245], v[86:89], v[26:29]
	v_mfma_f32_16x16x32_bf16 v[10:13], v[246:249], v[86:89], v[10:13]
	v_mfma_f32_16x16x32_bf16 v[54:57], v[234:237], v[90:93], v[54:57]
	v_mfma_f32_16x16x32_bf16 v[38:41], v[238:241], v[90:93], v[38:41]
	v_mfma_f32_16x16x32_bf16 v[22:25], v[242:245], v[90:93], v[22:25]
	v_mfma_f32_16x16x32_bf16 v[6:9], v[246:249], v[90:93], v[6:9]
	v_mfma_f32_16x16x32_bf16 v[50:53], v[234:237], v[94:97], v[50:53]
	v_mfma_f32_16x16x32_bf16 v[34:37], v[238:241], v[94:97], v[34:37]
	v_mfma_f32_16x16x32_bf16 v[18:21], v[242:245], v[94:97], v[18:21]
	v_mfma_f32_16x16x32_bf16 v[2:5], v[246:249], v[94:97], v[2:5]
	s_waitcnt vmcnt(8)
	s_barrier
	ds_read_b128 v[218:221], v102 offset:16384
	ds_read_b128 v[222:225], v102 offset:18432
	ds_read_b128 v[226:229], v102 offset:20480
	ds_read_b128 v[230:233], v102 offset:22528
	ds_read_b128 v[234:237], v103 offset:16384
	ds_read_b128 v[238:241], v103 offset:18432
	ds_read_b128 v[242:245], v103 offset:20480
	ds_read_b128 v[246:249], v103 offset:22528
	s_add_u32 m0, s4, 0x0
	s_nop 0
	global_load_lds_dwordx4 v98, s[6:7]
	s_add_u32 m0, s4, 0x400
	s_nop 0
	global_load_lds_dwordx4 v99, s[6:7]
	s_add_u32 m0, s4, 0x800
	s_nop 0
	global_load_lds_dwordx4 v100, s[6:7]
	s_add_u32 m0, s4, 0xc00
	s_nop 0
	global_load_lds_dwordx4 v101, s[6:7]
	v_add_u32_e32 v98, 0x80, v98
	v_add_u32_e32 v99, 0x80, v99
	v_add_u32_e32 v100, 0x80, v100
	v_add_u32_e32 v101, 0x80, v101
	s_waitcnt lgkmcnt(4)
	v_mfma_f32_16x16x32_bf16 v[106:109], v[218:221], v[66:69], v[106:109]
	v_mfma_f32_16x16x32_bf16 v[122:125], v[222:225], v[66:69], v[122:125]
	v_mfma_f32_16x16x32_bf16 v[138:141], v[226:229], v[66:69], v[138:141]
	v_mfma_f32_16x16x32_bf16 v[162:165], v[230:233], v[66:69], v[162:165]
	v_mfma_f32_16x16x32_bf16 v[110:113], v[218:221], v[70:73], v[110:113]
	v_mfma_f32_16x16x32_bf16 v[126:129], v[222:225], v[70:73], v[126:129]
	v_mfma_f32_16x16x32_bf16 v[142:145], v[226:229], v[70:73], v[142:145]
	v_mfma_f32_16x16x32_bf16 v[166:169], v[230:233], v[70:73], v[166:169]
	v_mfma_f32_16x16x32_bf16 v[114:117], v[218:221], v[74:77], v[114:117]
	v_mfma_f32_16x16x32_bf16 v[130:133], v[222:225], v[74:77], v[130:133]
	v_mfma_f32_16x16x32_bf16 v[154:157], v[226:229], v[74:77], v[154:157]
	v_mfma_f32_16x16x32_bf16 v[170:173], v[230:233], v[74:77], v[170:173]
	v_mfma_f32_16x16x32_bf16 v[118:121], v[218:221], v[78:81], v[118:121]
	v_mfma_f32_16x16x32_bf16 v[134:137], v[222:225], v[78:81], v[134:137]
	v_mfma_f32_16x16x32_bf16 v[158:161], v[226:229], v[78:81], v[158:161]
	v_mfma_f32_16x16x32_bf16 v[174:177], v[230:233], v[78:81], v[174:177]
	s_waitcnt lgkmcnt(0)
	v_mfma_f32_16x16x32_bf16 v[106:109], v[234:237], v[82:85], v[106:109]
	v_mfma_f32_16x16x32_bf16 v[122:125], v[238:241], v[82:85], v[122:125]
	v_mfma_f32_16x16x32_bf16 v[138:141], v[242:245], v[82:85], v[138:141]
	v_mfma_f32_16x16x32_bf16 v[162:165], v[246:249], v[82:85], v[162:165]
	v_mfma_f32_16x16x32_bf16 v[110:113], v[234:237], v[86:89], v[110:113]
	v_mfma_f32_16x16x32_bf16 v[126:129], v[238:241], v[86:89], v[126:129]
	v_mfma_f32_16x16x32_bf16 v[142:145], v[242:245], v[86:89], v[142:145]
	v_mfma_f32_16x16x32_bf16 v[166:169], v[246:249], v[86:89], v[166:169]
	v_mfma_f32_16x16x32_bf16 v[114:117], v[234:237], v[90:93], v[114:117]
	v_mfma_f32_16x16x32_bf16 v[130:133], v[238:241], v[90:93], v[130:133]
	v_mfma_f32_16x16x32_bf16 v[154:157], v[242:245], v[90:93], v[154:157]
	v_mfma_f32_16x16x32_bf16 v[170:173], v[246:249], v[90:93], v[170:173]
	v_mfma_f32_16x16x32_bf16 v[118:121], v[234:237], v[94:97], v[118:121]
	v_mfma_f32_16x16x32_bf16 v[134:137], v[238:241], v[94:97], v[134:137]
	v_mfma_f32_16x16x32_bf16 v[158:161], v[242:245], v[94:97], v[158:161]
	v_mfma_f32_16x16x32_bf16 v[174:177], v[246:249], v[94:97], v[174:177]
	s_waitcnt vmcnt(4)
	s_barrier
	ds_read_b128 v[218:221], v102 offset:32768
	ds_read_b128 v[222:225], v102 offset:34816
	ds_read_b128 v[226:229], v102 offset:36864
	ds_read_b128 v[230:233], v102 offset:38912
	ds_read_b128 v[66:69], v250 offset:49152
	ds_read_b128 v[70:73], v250 offset:51200
	ds_read_b128 v[74:77], v250 offset:53248
	ds_read_b128 v[78:81], v250 offset:55296
	ds_read_b128 v[234:237], v103 offset:32768
	ds_read_b128 v[238:241], v103 offset:34816
	ds_read_b128 v[242:245], v103 offset:36864
	ds_read_b128 v[246:249], v103 offset:38912
	ds_read_b128 v[82:85], v251 offset:49152
	ds_read_b128 v[86:89], v251 offset:51200
	ds_read_b128 v[90:93], v251 offset:53248
	ds_read_b128 v[94:97], v251 offset:55296
	s_add_u32 m0, s4, 0x4000
	s_nop 0
	global_load_lds_dwordx4 v98, s[28:29]
	s_add_u32 m0, s4, 0x4400
	s_nop 0
	global_load_lds_dwordx4 v99, s[28:29]
	s_add_u32 m0, s4, 0x4800
	s_nop 0
	global_load_lds_dwordx4 v100, s[28:29]
	s_add_u32 m0, s4, 0x4c00
	s_nop 0
	global_load_lds_dwordx4 v101, s[28:29]
	s_add_u32 m0, s4, 0xc000
	s_nop 0
	global_load_lds_dwordx4 v98, s[48:49]
	s_add_u32 m0, s4, 0xc400
	s_nop 0
	global_load_lds_dwordx4 v99, s[48:49]
	s_add_u32 m0, s4, 0xc800
	s_nop 0
	global_load_lds_dwordx4 v100, s[48:49]
	s_add_u32 m0, s4, 0xcc00
	s_nop 0
	global_load_lds_dwordx4 v101, s[48:49]
	s_waitcnt lgkmcnt(8)
	v_mfma_f32_16x16x32_bf16 v[62:65], v[218:221], v[66:69], v[62:65]
	v_mfma_f32_16x16x32_bf16 v[46:49], v[222:225], v[66:69], v[46:49]
	v_mfma_f32_16x16x32_bf16 v[30:33], v[226:229], v[66:69], v[30:33]
	v_mfma_f32_16x16x32_bf16 v[14:17], v[230:233], v[66:69], v[14:17]
	v_mfma_f32_16x16x32_bf16 v[58:61], v[218:221], v[70:73], v[58:61]
	v_mfma_f32_16x16x32_bf16 v[42:45], v[222:225], v[70:73], v[42:45]
	v_mfma_f32_16x16x32_bf16 v[26:29], v[226:229], v[70:73], v[26:29]
	v_mfma_f32_16x16x32_bf16 v[10:13], v[230:233], v[70:73], v[10:13]
	v_mfma_f32_16x16x32_bf16 v[54:57], v[218:221], v[74:77], v[54:57]
	v_mfma_f32_16x16x32_bf16 v[38:41], v[222:225], v[74:77], v[38:41]
	v_mfma_f32_16x16x32_bf16 v[22:25], v[226:229], v[74:77], v[22:25]
	v_mfma_f32_16x16x32_bf16 v[6:9], v[230:233], v[74:77], v[6:9]
	v_mfma_f32_16x16x32_bf16 v[50:53], v[218:221], v[78:81], v[50:53]
	v_mfma_f32_16x16x32_bf16 v[34:37], v[222:225], v[78:81], v[34:37]
	v_mfma_f32_16x16x32_bf16 v[18:21], v[226:229], v[78:81], v[18:21]
	v_mfma_f32_16x16x32_bf16 v[2:5], v[230:233], v[78:81], v[2:5]
	s_waitcnt lgkmcnt(0)
	v_mfma_f32_16x16x32_bf16 v[62:65], v[234:237], v[82:85], v[62:65]
	v_mfma_f32_16x16x32_bf16 v[46:49], v[238:241], v[82:85], v[46:49]
	v_mfma_f32_16x16x32_bf16 v[30:33], v[242:245], v[82:85], v[30:33]
	v_mfma_f32_16x16x32_bf16 v[14:17], v[246:249], v[82:85], v[14:17]
	v_mfma_f32_16x16x32_bf16 v[58:61], v[234:237], v[86:89], v[58:61]
	v_mfma_f32_16x16x32_bf16 v[42:45], v[238:241], v[86:89], v[42:45]
	v_mfma_f32_16x16x32_bf16 v[26:29], v[242:245], v[86:89], v[26:29]
	v_mfma_f32_16x16x32_bf16 v[10:13], v[246:249], v[86:89], v[10:13]
	v_mfma_f32_16x16x32_bf16 v[54:57], v[234:237], v[90:93], v[54:57]
	v_mfma_f32_16x16x32_bf16 v[38:41], v[238:241], v[90:93], v[38:41]
	v_mfma_f32_16x16x32_bf16 v[22:25], v[242:245], v[90:93], v[22:25]
	v_mfma_f32_16x16x32_bf16 v[6:9], v[246:249], v[90:93], v[6:9]
	v_mfma_f32_16x16x32_bf16 v[50:53], v[234:237], v[94:97], v[50:53]
	v_mfma_f32_16x16x32_bf16 v[34:37], v[238:241], v[94:97], v[34:37]
	v_mfma_f32_16x16x32_bf16 v[18:21], v[242:245], v[94:97], v[18:21]
	v_mfma_f32_16x16x32_bf16 v[2:5], v[246:249], v[94:97], v[2:5]
	s_waitcnt vmcnt(8)
	s_barrier
	ds_read_b128 v[218:221], v102 offset:0
	ds_read_b128 v[222:225], v102 offset:2048
	ds_read_b128 v[226:229], v102 offset:4096
	ds_read_b128 v[230:233], v102 offset:6144
	ds_read_b128 v[234:237], v103 offset:0
	ds_read_b128 v[238:241], v103 offset:2048
	ds_read_b128 v[242:245], v103 offset:4096
	ds_read_b128 v[246:249], v103 offset:6144
	s_add_u32 m0, s4, 0x8000
	s_nop 0
	global_load_lds_dwordx4 v98, s[6:7]
	s_add_u32 m0, s4, 0x8400
	s_nop 0
	global_load_lds_dwordx4 v99, s[6:7]
	s_add_u32 m0, s4, 0x8800
	s_nop 0
	global_load_lds_dwordx4 v100, s[6:7]
	s_add_u32 m0, s4, 0x8c00
	s_nop 0
	global_load_lds_dwordx4 v101, s[6:7]
	v_add_u32_e32 v98, 0x80, v98
	v_add_u32_e32 v99, 0x80, v99
	v_add_u32_e32 v100, 0x80, v100
	v_add_u32_e32 v101, 0x80, v101
	s_waitcnt lgkmcnt(4)
	v_mfma_f32_16x16x32_bf16 v[106:109], v[218:221], v[66:69], v[106:109]
	v_mfma_f32_16x16x32_bf16 v[122:125], v[222:225], v[66:69], v[122:125]
	v_mfma_f32_16x16x32_bf16 v[138:141], v[226:229], v[66:69], v[138:141]
	v_mfma_f32_16x16x32_bf16 v[162:165], v[230:233], v[66:69], v[162:165]
	v_mfma_f32_16x16x32_bf16 v[110:113], v[218:221], v[70:73], v[110:113]
	v_mfma_f32_16x16x32_bf16 v[126:129], v[222:225], v[70:73], v[126:129]
	v_mfma_f32_16x16x32_bf16 v[142:145], v[226:229], v[70:73], v[142:145]
	v_mfma_f32_16x16x32_bf16 v[166:169], v[230:233], v[70:73], v[166:169]
	v_mfma_f32_16x16x32_bf16 v[114:117], v[218:221], v[74:77], v[114:117]
	v_mfma_f32_16x16x32_bf16 v[130:133], v[222:225], v[74:77], v[130:133]
	v_mfma_f32_16x16x32_bf16 v[154:157], v[226:229], v[74:77], v[154:157]
	v_mfma_f32_16x16x32_bf16 v[170:173], v[230:233], v[74:77], v[170:173]
	v_mfma_f32_16x16x32_bf16 v[118:121], v[218:221], v[78:81], v[118:121]
	v_mfma_f32_16x16x32_bf16 v[134:137], v[222:225], v[78:81], v[134:137]
	v_mfma_f32_16x16x32_bf16 v[158:161], v[226:229], v[78:81], v[158:161]
	v_mfma_f32_16x16x32_bf16 v[174:177], v[230:233], v[78:81], v[174:177]
	s_waitcnt lgkmcnt(0)
	v_mfma_f32_16x16x32_bf16 v[106:109], v[234:237], v[82:85], v[106:109]
	v_mfma_f32_16x16x32_bf16 v[122:125], v[238:241], v[82:85], v[122:125]
	v_mfma_f32_16x16x32_bf16 v[138:141], v[242:245], v[82:85], v[138:141]
	v_mfma_f32_16x16x32_bf16 v[162:165], v[246:249], v[82:85], v[162:165]
	v_mfma_f32_16x16x32_bf16 v[110:113], v[234:237], v[86:89], v[110:113]
	v_mfma_f32_16x16x32_bf16 v[126:129], v[238:241], v[86:89], v[126:129]
	v_mfma_f32_16x16x32_bf16 v[142:145], v[242:245], v[86:89], v[142:145]
	v_mfma_f32_16x16x32_bf16 v[166:169], v[246:249], v[86:89], v[166:169]
	v_mfma_f32_16x16x32_bf16 v[114:117], v[234:237], v[90:93], v[114:117]
	v_mfma_f32_16x16x32_bf16 v[130:133], v[238:241], v[90:93], v[130:133]
	v_mfma_f32_16x16x32_bf16 v[154:157], v[242:245], v[90:93], v[154:157]
	v_mfma_f32_16x16x32_bf16 v[170:173], v[246:249], v[90:93], v[170:173]
	v_mfma_f32_16x16x32_bf16 v[118:121], v[234:237], v[94:97], v[118:121]
	v_mfma_f32_16x16x32_bf16 v[134:137], v[238:241], v[94:97], v[134:137]
	v_mfma_f32_16x16x32_bf16 v[158:161], v[242:245], v[94:97], v[158:161]
	v_mfma_f32_16x16x32_bf16 v[174:177], v[246:249], v[94:97], v[174:177]
	s_waitcnt vmcnt(4)
	s_barrier
	ds_read_b128 v[218:221], v102 offset:16384
	ds_read_b128 v[222:225], v102 offset:18432
	ds_read_b128 v[226:229], v102 offset:20480
	ds_read_b128 v[230:233], v102 offset:22528
	ds_read_b128 v[66:69], v104 offset:49152
	ds_read_b128 v[70:73], v104 offset:51200
	ds_read_b128 v[74:77], v104 offset:53248
	ds_read_b128 v[78:81], v104 offset:55296
	ds_read_b128 v[234:237], v103 offset:16384
	ds_read_b128 v[238:241], v103 offset:18432
	ds_read_b128 v[242:245], v103 offset:20480
	ds_read_b128 v[246:249], v103 offset:22528
	ds_read_b128 v[82:85], v105 offset:49152
	ds_read_b128 v[86:89], v105 offset:51200
	ds_read_b128 v[90:93], v105 offset:53248
	ds_read_b128 v[94:97], v105 offset:55296
	s_add_u32 m0, s4, 0x0
	s_nop 0
	global_load_lds_dwordx4 v98, s[28:29]
	s_add_u32 m0, s4, 0x400
	s_nop 0
	global_load_lds_dwordx4 v99, s[28:29]
	s_add_u32 m0, s4, 0x800
	s_nop 0
	global_load_lds_dwordx4 v100, s[28:29]
	s_add_u32 m0, s4, 0xc00
	s_nop 0
	global_load_lds_dwordx4 v101, s[28:29]
	s_add_u32 m0, s4, 0x10000
	s_nop 0
	global_load_lds_dwordx4 v98, s[48:49]
	s_add_u32 m0, s4, 0x10400
	s_nop 0
	global_load_lds_dwordx4 v99, s[48:49]
	s_add_u32 m0, s4, 0x10800
	s_nop 0
	global_load_lds_dwordx4 v100, s[48:49]
	s_add_u32 m0, s4, 0x10c00
	s_nop 0
	global_load_lds_dwordx4 v101, s[48:49]
	s_waitcnt lgkmcnt(8)
	v_mfma_f32_16x16x32_bf16 v[62:65], v[218:221], v[66:69], v[62:65]
	v_mfma_f32_16x16x32_bf16 v[46:49], v[222:225], v[66:69], v[46:49]
	v_mfma_f32_16x16x32_bf16 v[30:33], v[226:229], v[66:69], v[30:33]
	v_mfma_f32_16x16x32_bf16 v[14:17], v[230:233], v[66:69], v[14:17]
	v_mfma_f32_16x16x32_bf16 v[58:61], v[218:221], v[70:73], v[58:61]
	v_mfma_f32_16x16x32_bf16 v[42:45], v[222:225], v[70:73], v[42:45]
	v_mfma_f32_16x16x32_bf16 v[26:29], v[226:229], v[70:73], v[26:29]
	v_mfma_f32_16x16x32_bf16 v[10:13], v[230:233], v[70:73], v[10:13]
	v_mfma_f32_16x16x32_bf16 v[54:57], v[218:221], v[74:77], v[54:57]
	v_mfma_f32_16x16x32_bf16 v[38:41], v[222:225], v[74:77], v[38:41]
	v_mfma_f32_16x16x32_bf16 v[22:25], v[226:229], v[74:77], v[22:25]
	v_mfma_f32_16x16x32_bf16 v[6:9], v[230:233], v[74:77], v[6:9]
	v_mfma_f32_16x16x32_bf16 v[50:53], v[218:221], v[78:81], v[50:53]
	v_mfma_f32_16x16x32_bf16 v[34:37], v[222:225], v[78:81], v[34:37]
	v_mfma_f32_16x16x32_bf16 v[18:21], v[226:229], v[78:81], v[18:21]
	v_mfma_f32_16x16x32_bf16 v[2:5], v[230:233], v[78:81], v[2:5]
	s_waitcnt lgkmcnt(0)
	v_mfma_f32_16x16x32_bf16 v[62:65], v[234:237], v[82:85], v[62:65]
	v_mfma_f32_16x16x32_bf16 v[46:49], v[238:241], v[82:85], v[46:49]
	v_mfma_f32_16x16x32_bf16 v[30:33], v[242:245], v[82:85], v[30:33]
	v_mfma_f32_16x16x32_bf16 v[14:17], v[246:249], v[82:85], v[14:17]
	v_mfma_f32_16x16x32_bf16 v[58:61], v[234:237], v[86:89], v[58:61]
	v_mfma_f32_16x16x32_bf16 v[42:45], v[238:241], v[86:89], v[42:45]
	v_mfma_f32_16x16x32_bf16 v[26:29], v[242:245], v[86:89], v[26:29]
	v_mfma_f32_16x16x32_bf16 v[10:13], v[246:249], v[86:89], v[10:13]
	v_mfma_f32_16x16x32_bf16 v[54:57], v[234:237], v[90:93], v[54:57]
	v_mfma_f32_16x16x32_bf16 v[38:41], v[238:241], v[90:93], v[38:41]
	v_mfma_f32_16x16x32_bf16 v[22:25], v[242:245], v[90:93], v[22:25]
	v_mfma_f32_16x16x32_bf16 v[6:9], v[246:249], v[90:93], v[6:9]
	v_mfma_f32_16x16x32_bf16 v[50:53], v[234:237], v[94:97], v[50:53]
	v_mfma_f32_16x16x32_bf16 v[34:37], v[238:241], v[94:97], v[34:37]
	v_mfma_f32_16x16x32_bf16 v[18:21], v[242:245], v[94:97], v[18:21]
	v_mfma_f32_16x16x32_bf16 v[2:5], v[246:249], v[94:97], v[2:5]
	s_waitcnt vmcnt(8)
	s_barrier
	ds_read_b128 v[218:221], v102 offset:32768
	ds_read_b128 v[222:225], v102 offset:34816
	ds_read_b128 v[226:229], v102 offset:36864
	ds_read_b128 v[230:233], v102 offset:38912
	ds_read_b128 v[234:237], v103 offset:32768
	ds_read_b128 v[238:241], v103 offset:34816
	ds_read_b128 v[242:245], v103 offset:36864
	ds_read_b128 v[246:249], v103 offset:38912
	s_add_u32 m0, s4, 0x4000
	s_nop 0
	global_load_lds_dwordx4 v98, s[6:7]
	s_add_u32 m0, s4, 0x4400
	s_nop 0
	global_load_lds_dwordx4 v99, s[6:7]
	s_add_u32 m0, s4, 0x4800
	s_nop 0
	global_load_lds_dwordx4 v100, s[6:7]
	s_add_u32 m0, s4, 0x4c00
	s_nop 0
	global_load_lds_dwordx4 v101, s[6:7]
	v_add_u32_e32 v98, 0x80, v98
	v_add_u32_e32 v99, 0x80, v99
	v_add_u32_e32 v100, 0x80, v100
	v_add_u32_e32 v101, 0x80, v101
	s_waitcnt lgkmcnt(4)
	v_mfma_f32_16x16x32_bf16 v[106:109], v[218:221], v[66:69], v[106:109]
	v_mfma_f32_16x16x32_bf16 v[122:125], v[222:225], v[66:69], v[122:125]
	v_mfma_f32_16x16x32_bf16 v[138:141], v[226:229], v[66:69], v[138:141]
	v_mfma_f32_16x16x32_bf16 v[162:165], v[230:233], v[66:69], v[162:165]
	v_mfma_f32_16x16x32_bf16 v[110:113], v[218:221], v[70:73], v[110:113]
	v_mfma_f32_16x16x32_bf16 v[126:129], v[222:225], v[70:73], v[126:129]
	v_mfma_f32_16x16x32_bf16 v[142:145], v[226:229], v[70:73], v[142:145]
	v_mfma_f32_16x16x32_bf16 v[166:169], v[230:233], v[70:73], v[166:169]
	v_mfma_f32_16x16x32_bf16 v[114:117], v[218:221], v[74:77], v[114:117]
	v_mfma_f32_16x16x32_bf16 v[130:133], v[222:225], v[74:77], v[130:133]
	v_mfma_f32_16x16x32_bf16 v[154:157], v[226:229], v[74:77], v[154:157]
	v_mfma_f32_16x16x32_bf16 v[170:173], v[230:233], v[74:77], v[170:173]
	v_mfma_f32_16x16x32_bf16 v[118:121], v[218:221], v[78:81], v[118:121]
	v_mfma_f32_16x16x32_bf16 v[134:137], v[222:225], v[78:81], v[134:137]
	v_mfma_f32_16x16x32_bf16 v[158:161], v[226:229], v[78:81], v[158:161]
	v_mfma_f32_16x16x32_bf16 v[174:177], v[230:233], v[78:81], v[174:177]
	s_waitcnt lgkmcnt(0)
	v_mfma_f32_16x16x32_bf16 v[106:109], v[234:237], v[82:85], v[106:109]
	v_mfma_f32_16x16x32_bf16 v[122:125], v[238:241], v[82:85], v[122:125]
	v_mfma_f32_16x16x32_bf16 v[138:141], v[242:245], v[82:85], v[138:141]
	v_mfma_f32_16x16x32_bf16 v[162:165], v[246:249], v[82:85], v[162:165]
	v_mfma_f32_16x16x32_bf16 v[110:113], v[234:237], v[86:89], v[110:113]
	v_mfma_f32_16x16x32_bf16 v[126:129], v[238:241], v[86:89], v[126:129]
	v_mfma_f32_16x16x32_bf16 v[142:145], v[242:245], v[86:89], v[142:145]
	v_mfma_f32_16x16x32_bf16 v[166:169], v[246:249], v[86:89], v[166:169]
	v_mfma_f32_16x16x32_bf16 v[114:117], v[234:237], v[90:93], v[114:117]
	v_mfma_f32_16x16x32_bf16 v[130:133], v[238:241], v[90:93], v[130:133]
	v_mfma_f32_16x16x32_bf16 v[154:157], v[242:245], v[90:93], v[154:157]
	v_mfma_f32_16x16x32_bf16 v[170:173], v[246:249], v[90:93], v[170:173]
	v_mfma_f32_16x16x32_bf16 v[118:121], v[234:237], v[94:97], v[118:121]
	v_mfma_f32_16x16x32_bf16 v[134:137], v[238:241], v[94:97], v[134:137]
	v_mfma_f32_16x16x32_bf16 v[158:161], v[242:245], v[94:97], v[158:161]
	v_mfma_f32_16x16x32_bf16 v[174:177], v[246:249], v[94:97], v[174:177]
	s_waitcnt vmcnt(4)
	s_barrier
	ds_read_b128 v[218:221], v102 offset:0
	ds_read_b128 v[222:225], v102 offset:2048
	ds_read_b128 v[226:229], v102 offset:4096
	ds_read_b128 v[230:233], v102 offset:6144
	ds_read_b128 v[66:69], v250 offset:49152
	ds_read_b128 v[70:73], v250 offset:51200
	ds_read_b128 v[74:77], v250 offset:53248
	ds_read_b128 v[78:81], v250 offset:55296
	ds_read_b128 v[234:237], v103 offset:0
	ds_read_b128 v[238:241], v103 offset:2048
	ds_read_b128 v[242:245], v103 offset:4096
	ds_read_b128 v[246:249], v103 offset:6144
	ds_read_b128 v[82:85], v251 offset:49152
	ds_read_b128 v[86:89], v251 offset:51200
	ds_read_b128 v[90:93], v251 offset:53248
	ds_read_b128 v[94:97], v251 offset:55296
	s_add_u32 m0, s4, 0x8000
	s_nop 0
	global_load_lds_dwordx4 v98, s[28:29]
	s_add_u32 m0, s4, 0x8400
	s_nop 0
	global_load_lds_dwordx4 v99, s[28:29]
	s_add_u32 m0, s4, 0x8800
	s_nop 0
	global_load_lds_dwordx4 v100, s[28:29]
	s_add_u32 m0, s4, 0x8c00
	s_nop 0
	global_load_lds_dwordx4 v101, s[28:29]
	s_add_u32 m0, s4, 0xc000
	s_nop 0
	global_load_lds_dwordx4 v98, s[48:49]
	s_add_u32 m0, s4, 0xc400
	s_nop 0
	global_load_lds_dwordx4 v99, s[48:49]
	s_add_u32 m0, s4, 0xc800
	s_nop 0
	global_load_lds_dwordx4 v100, s[48:49]
	s_add_u32 m0, s4, 0xcc00
	s_nop 0
	global_load_lds_dwordx4 v101, s[48:49]
	s_waitcnt lgkmcnt(8)
	v_mfma_f32_16x16x32_bf16 v[62:65], v[218:221], v[66:69], v[62:65]
	v_mfma_f32_16x16x32_bf16 v[46:49], v[222:225], v[66:69], v[46:49]
	v_mfma_f32_16x16x32_bf16 v[30:33], v[226:229], v[66:69], v[30:33]
	v_mfma_f32_16x16x32_bf16 v[14:17], v[230:233], v[66:69], v[14:17]
	v_mfma_f32_16x16x32_bf16 v[58:61], v[218:221], v[70:73], v[58:61]
	v_mfma_f32_16x16x32_bf16 v[42:45], v[222:225], v[70:73], v[42:45]
	v_mfma_f32_16x16x32_bf16 v[26:29], v[226:229], v[70:73], v[26:29]
	v_mfma_f32_16x16x32_bf16 v[10:13], v[230:233], v[70:73], v[10:13]
	v_mfma_f32_16x16x32_bf16 v[54:57], v[218:221], v[74:77], v[54:57]
	v_mfma_f32_16x16x32_bf16 v[38:41], v[222:225], v[74:77], v[38:41]
	v_mfma_f32_16x16x32_bf16 v[22:25], v[226:229], v[74:77], v[22:25]
	v_mfma_f32_16x16x32_bf16 v[6:9], v[230:233], v[74:77], v[6:9]
	v_mfma_f32_16x16x32_bf16 v[50:53], v[218:221], v[78:81], v[50:53]
	v_mfma_f32_16x16x32_bf16 v[34:37], v[222:225], v[78:81], v[34:37]
	v_mfma_f32_16x16x32_bf16 v[18:21], v[226:229], v[78:81], v[18:21]
	v_mfma_f32_16x16x32_bf16 v[2:5], v[230:233], v[78:81], v[2:5]
	s_waitcnt lgkmcnt(0)
	v_mfma_f32_16x16x32_bf16 v[62:65], v[234:237], v[82:85], v[62:65]
	v_mfma_f32_16x16x32_bf16 v[46:49], v[238:241], v[82:85], v[46:49]
	v_mfma_f32_16x16x32_bf16 v[30:33], v[242:245], v[82:85], v[30:33]
	v_mfma_f32_16x16x32_bf16 v[14:17], v[246:249], v[82:85], v[14:17]
	v_mfma_f32_16x16x32_bf16 v[58:61], v[234:237], v[86:89], v[58:61]
	v_mfma_f32_16x16x32_bf16 v[42:45], v[238:241], v[86:89], v[42:45]
	v_mfma_f32_16x16x32_bf16 v[26:29], v[242:245], v[86:89], v[26:29]
	v_mfma_f32_16x16x32_bf16 v[10:13], v[246:249], v[86:89], v[10:13]
	v_mfma_f32_16x16x32_bf16 v[54:57], v[234:237], v[90:93], v[54:57]
	v_mfma_f32_16x16x32_bf16 v[38:41], v[238:241], v[90:93], v[38:41]
	v_mfma_f32_16x16x32_bf16 v[22:25], v[242:245], v[90:93], v[22:25]
	v_mfma_f32_16x16x32_bf16 v[6:9], v[246:249], v[90:93], v[6:9]
	v_mfma_f32_16x16x32_bf16 v[50:53], v[234:237], v[94:97], v[50:53]
	v_mfma_f32_16x16x32_bf16 v[34:37], v[238:241], v[94:97], v[34:37]
	v_mfma_f32_16x16x32_bf16 v[18:21], v[242:245], v[94:97], v[18:21]
	v_mfma_f32_16x16x32_bf16 v[2:5], v[246:249], v[94:97], v[2:5]
	s_waitcnt vmcnt(8)
	s_barrier
	ds_read_b128 v[218:221], v102 offset:16384
	ds_read_b128 v[222:225], v102 offset:18432
	ds_read_b128 v[226:229], v102 offset:20480
	ds_read_b128 v[230:233], v102 offset:22528
	ds_read_b128 v[234:237], v103 offset:16384
	ds_read_b128 v[238:241], v103 offset:18432
	ds_read_b128 v[242:245], v103 offset:20480
	ds_read_b128 v[246:249], v103 offset:22528
	s_add_u32 m0, s4, 0x0
	s_nop 0
	global_load_lds_dwordx4 v98, s[6:7]
	s_add_u32 m0, s4, 0x400
	s_nop 0
	global_load_lds_dwordx4 v99, s[6:7]
	s_add_u32 m0, s4, 0x800
	s_nop 0
	global_load_lds_dwordx4 v100, s[6:7]
	s_add_u32 m0, s4, 0xc00
	s_nop 0
	global_load_lds_dwordx4 v101, s[6:7]
	v_add_u32_e32 v98, 0x80, v98
	v_add_u32_e32 v99, 0x80, v99
	v_add_u32_e32 v100, 0x80, v100
	v_add_u32_e32 v101, 0x80, v101
	s_waitcnt lgkmcnt(4)
	v_mfma_f32_16x16x32_bf16 v[106:109], v[218:221], v[66:69], v[106:109]
	v_mfma_f32_16x16x32_bf16 v[122:125], v[222:225], v[66:69], v[122:125]
	v_mfma_f32_16x16x32_bf16 v[138:141], v[226:229], v[66:69], v[138:141]
	v_mfma_f32_16x16x32_bf16 v[162:165], v[230:233], v[66:69], v[162:165]
	v_mfma_f32_16x16x32_bf16 v[110:113], v[218:221], v[70:73], v[110:113]
	v_mfma_f32_16x16x32_bf16 v[126:129], v[222:225], v[70:73], v[126:129]
	v_mfma_f32_16x16x32_bf16 v[142:145], v[226:229], v[70:73], v[142:145]
	v_mfma_f32_16x16x32_bf16 v[166:169], v[230:233], v[70:73], v[166:169]
	v_mfma_f32_16x16x32_bf16 v[114:117], v[218:221], v[74:77], v[114:117]
	v_mfma_f32_16x16x32_bf16 v[130:133], v[222:225], v[74:77], v[130:133]
	v_mfma_f32_16x16x32_bf16 v[154:157], v[226:229], v[74:77], v[154:157]
	v_mfma_f32_16x16x32_bf16 v[170:173], v[230:233], v[74:77], v[170:173]
	v_mfma_f32_16x16x32_bf16 v[118:121], v[218:221], v[78:81], v[118:121]
	v_mfma_f32_16x16x32_bf16 v[134:137], v[222:225], v[78:81], v[134:137]
	v_mfma_f32_16x16x32_bf16 v[158:161], v[226:229], v[78:81], v[158:161]
	v_mfma_f32_16x16x32_bf16 v[174:177], v[230:233], v[78:81], v[174:177]
	s_waitcnt lgkmcnt(0)
	v_mfma_f32_16x16x32_bf16 v[106:109], v[234:237], v[82:85], v[106:109]
	v_mfma_f32_16x16x32_bf16 v[122:125], v[238:241], v[82:85], v[122:125]
	v_mfma_f32_16x16x32_bf16 v[138:141], v[242:245], v[82:85], v[138:141]
	v_mfma_f32_16x16x32_bf16 v[162:165], v[246:249], v[82:85], v[162:165]
	v_mfma_f32_16x16x32_bf16 v[110:113], v[234:237], v[86:89], v[110:113]
	v_mfma_f32_16x16x32_bf16 v[126:129], v[238:241], v[86:89], v[126:129]
	v_mfma_f32_16x16x32_bf16 v[142:145], v[242:245], v[86:89], v[142:145]
	v_mfma_f32_16x16x32_bf16 v[166:169], v[246:249], v[86:89], v[166:169]
	v_mfma_f32_16x16x32_bf16 v[114:117], v[234:237], v[90:93], v[114:117]
	v_mfma_f32_16x16x32_bf16 v[130:133], v[238:241], v[90:93], v[130:133]
	v_mfma_f32_16x16x32_bf16 v[154:157], v[242:245], v[90:93], v[154:157]
	v_mfma_f32_16x16x32_bf16 v[170:173], v[246:249], v[90:93], v[170:173]
	v_mfma_f32_16x16x32_bf16 v[118:121], v[234:237], v[94:97], v[118:121]
	v_mfma_f32_16x16x32_bf16 v[134:137], v[238:241], v[94:97], v[134:137]
	v_mfma_f32_16x16x32_bf16 v[158:161], v[242:245], v[94:97], v[158:161]
	v_mfma_f32_16x16x32_bf16 v[174:177], v[246:249], v[94:97], v[174:177]
	s_waitcnt vmcnt(4)
	s_barrier
	ds_read_b128 v[218:221], v102 offset:32768
	ds_read_b128 v[222:225], v102 offset:34816
	ds_read_b128 v[226:229], v102 offset:36864
	ds_read_b128 v[230:233], v102 offset:38912
	ds_read_b128 v[66:69], v104 offset:49152
	ds_read_b128 v[70:73], v104 offset:51200
	ds_read_b128 v[74:77], v104 offset:53248
	ds_read_b128 v[78:81], v104 offset:55296
	ds_read_b128 v[234:237], v103 offset:32768
	ds_read_b128 v[238:241], v103 offset:34816
	ds_read_b128 v[242:245], v103 offset:36864
	ds_read_b128 v[246:249], v103 offset:38912
	ds_read_b128 v[82:85], v105 offset:49152
	ds_read_b128 v[86:89], v105 offset:51200
	ds_read_b128 v[90:93], v105 offset:53248
	ds_read_b128 v[94:97], v105 offset:55296
	s_add_u32 m0, s4, 0x4000
	s_nop 0
	global_load_lds_dwordx4 v98, s[28:29]
	s_add_u32 m0, s4, 0x4400
	s_nop 0
	global_load_lds_dwordx4 v99, s[28:29]
	s_add_u32 m0, s4, 0x4800
	s_nop 0
	global_load_lds_dwordx4 v100, s[28:29]
	s_add_u32 m0, s4, 0x4c00
	s_nop 0
	global_load_lds_dwordx4 v101, s[28:29]
	s_add_u32 m0, s4, 0x10000
	s_nop 0
	global_load_lds_dwordx4 v98, s[48:49]
	s_add_u32 m0, s4, 0x10400
	s_nop 0
	global_load_lds_dwordx4 v99, s[48:49]
	s_add_u32 m0, s4, 0x10800
	s_nop 0
	global_load_lds_dwordx4 v100, s[48:49]
	s_add_u32 m0, s4, 0x10c00
	s_nop 0
	global_load_lds_dwordx4 v101, s[48:49]
	s_waitcnt lgkmcnt(8)
	v_mfma_f32_16x16x32_bf16 v[62:65], v[218:221], v[66:69], v[62:65]
	v_mfma_f32_16x16x32_bf16 v[46:49], v[222:225], v[66:69], v[46:49]
	v_mfma_f32_16x16x32_bf16 v[30:33], v[226:229], v[66:69], v[30:33]
	v_mfma_f32_16x16x32_bf16 v[14:17], v[230:233], v[66:69], v[14:17]
	v_mfma_f32_16x16x32_bf16 v[58:61], v[218:221], v[70:73], v[58:61]
	v_mfma_f32_16x16x32_bf16 v[42:45], v[222:225], v[70:73], v[42:45]
	v_mfma_f32_16x16x32_bf16 v[26:29], v[226:229], v[70:73], v[26:29]
	v_mfma_f32_16x16x32_bf16 v[10:13], v[230:233], v[70:73], v[10:13]
	v_mfma_f32_16x16x32_bf16 v[54:57], v[218:221], v[74:77], v[54:57]
	v_mfma_f32_16x16x32_bf16 v[38:41], v[222:225], v[74:77], v[38:41]
	v_mfma_f32_16x16x32_bf16 v[22:25], v[226:229], v[74:77], v[22:25]
	v_mfma_f32_16x16x32_bf16 v[6:9], v[230:233], v[74:77], v[6:9]
	v_mfma_f32_16x16x32_bf16 v[50:53], v[218:221], v[78:81], v[50:53]
	v_mfma_f32_16x16x32_bf16 v[34:37], v[222:225], v[78:81], v[34:37]
	v_mfma_f32_16x16x32_bf16 v[18:21], v[226:229], v[78:81], v[18:21]
	v_mfma_f32_16x16x32_bf16 v[2:5], v[230:233], v[78:81], v[2:5]
	s_waitcnt lgkmcnt(0)
	v_mfma_f32_16x16x32_bf16 v[62:65], v[234:237], v[82:85], v[62:65]
	v_mfma_f32_16x16x32_bf16 v[46:49], v[238:241], v[82:85], v[46:49]
	v_mfma_f32_16x16x32_bf16 v[30:33], v[242:245], v[82:85], v[30:33]
	v_mfma_f32_16x16x32_bf16 v[14:17], v[246:249], v[82:85], v[14:17]
	v_mfma_f32_16x16x32_bf16 v[58:61], v[234:237], v[86:89], v[58:61]
	v_mfma_f32_16x16x32_bf16 v[42:45], v[238:241], v[86:89], v[42:45]
	v_mfma_f32_16x16x32_bf16 v[26:29], v[242:245], v[86:89], v[26:29]
	v_mfma_f32_16x16x32_bf16 v[10:13], v[246:249], v[86:89], v[10:13]
	v_mfma_f32_16x16x32_bf16 v[54:57], v[234:237], v[90:93], v[54:57]
	v_mfma_f32_16x16x32_bf16 v[38:41], v[238:241], v[90:93], v[38:41]
	v_mfma_f32_16x16x32_bf16 v[22:25], v[242:245], v[90:93], v[22:25]
	v_mfma_f32_16x16x32_bf16 v[6:9], v[246:249], v[90:93], v[6:9]
	v_mfma_f32_16x16x32_bf16 v[50:53], v[234:237], v[94:97], v[50:53]
	v_mfma_f32_16x16x32_bf16 v[34:37], v[238:241], v[94:97], v[34:37]
	v_mfma_f32_16x16x32_bf16 v[18:21], v[242:245], v[94:97], v[18:21]
	v_mfma_f32_16x16x32_bf16 v[2:5], v[246:249], v[94:97], v[2:5]
	s_waitcnt vmcnt(8)
	s_barrier
	ds_read_b128 v[218:221], v102 offset:0
	ds_read_b128 v[222:225], v102 offset:2048
	ds_read_b128 v[226:229], v102 offset:4096
	ds_read_b128 v[230:233], v102 offset:6144
	ds_read_b128 v[234:237], v103 offset:0
	ds_read_b128 v[238:241], v103 offset:2048
	ds_read_b128 v[242:245], v103 offset:4096
	ds_read_b128 v[246:249], v103 offset:6144
	s_add_u32 m0, s4, 0x8000
	s_nop 0
	global_load_lds_dwordx4 v98, s[6:7]
	s_add_u32 m0, s4, 0x8400
	s_nop 0
	global_load_lds_dwordx4 v99, s[6:7]
	s_add_u32 m0, s4, 0x8800
	s_nop 0
	global_load_lds_dwordx4 v100, s[6:7]
	s_add_u32 m0, s4, 0x8c00
	s_nop 0
	global_load_lds_dwordx4 v101, s[6:7]
	v_add_u32_e32 v98, 0x80, v98
	v_add_u32_e32 v99, 0x80, v99
	v_add_u32_e32 v100, 0x80, v100
	v_add_u32_e32 v101, 0x80, v101
	s_waitcnt lgkmcnt(4)
	v_mfma_f32_16x16x32_bf16 v[106:109], v[218:221], v[66:69], v[106:109]
	v_mfma_f32_16x16x32_bf16 v[122:125], v[222:225], v[66:69], v[122:125]
	v_mfma_f32_16x16x32_bf16 v[138:141], v[226:229], v[66:69], v[138:141]
	v_mfma_f32_16x16x32_bf16 v[162:165], v[230:233], v[66:69], v[162:165]
	v_mfma_f32_16x16x32_bf16 v[110:113], v[218:221], v[70:73], v[110:113]
	v_mfma_f32_16x16x32_bf16 v[126:129], v[222:225], v[70:73], v[126:129]
	v_mfma_f32_16x16x32_bf16 v[142:145], v[226:229], v[70:73], v[142:145]
	v_mfma_f32_16x16x32_bf16 v[166:169], v[230:233], v[70:73], v[166:169]
	v_mfma_f32_16x16x32_bf16 v[114:117], v[218:221], v[74:77], v[114:117]
	v_mfma_f32_16x16x32_bf16 v[130:133], v[222:225], v[74:77], v[130:133]
	v_mfma_f32_16x16x32_bf16 v[154:157], v[226:229], v[74:77], v[154:157]
	v_mfma_f32_16x16x32_bf16 v[170:173], v[230:233], v[74:77], v[170:173]
	v_mfma_f32_16x16x32_bf16 v[118:121], v[218:221], v[78:81], v[118:121]
	v_mfma_f32_16x16x32_bf16 v[134:137], v[222:225], v[78:81], v[134:137]
	v_mfma_f32_16x16x32_bf16 v[158:161], v[226:229], v[78:81], v[158:161]
	v_mfma_f32_16x16x32_bf16 v[174:177], v[230:233], v[78:81], v[174:177]
	s_waitcnt lgkmcnt(0)
	v_mfma_f32_16x16x32_bf16 v[106:109], v[234:237], v[82:85], v[106:109]
	v_mfma_f32_16x16x32_bf16 v[122:125], v[238:241], v[82:85], v[122:125]
	v_mfma_f32_16x16x32_bf16 v[138:141], v[242:245], v[82:85], v[138:141]
	v_mfma_f32_16x16x32_bf16 v[162:165], v[246:249], v[82:85], v[162:165]
	v_mfma_f32_16x16x32_bf16 v[110:113], v[234:237], v[86:89], v[110:113]
	v_mfma_f32_16x16x32_bf16 v[126:129], v[238:241], v[86:89], v[126:129]
	v_mfma_f32_16x16x32_bf16 v[142:145], v[242:245], v[86:89], v[142:145]
	v_mfma_f32_16x16x32_bf16 v[166:169], v[246:249], v[86:89], v[166:169]
	v_mfma_f32_16x16x32_bf16 v[114:117], v[234:237], v[90:93], v[114:117]
	v_mfma_f32_16x16x32_bf16 v[130:133], v[238:241], v[90:93], v[130:133]
	v_mfma_f32_16x16x32_bf16 v[154:157], v[242:245], v[90:93], v[154:157]
	v_mfma_f32_16x16x32_bf16 v[170:173], v[246:249], v[90:93], v[170:173]
	v_mfma_f32_16x16x32_bf16 v[118:121], v[234:237], v[94:97], v[118:121]
	v_mfma_f32_16x16x32_bf16 v[134:137], v[238:241], v[94:97], v[134:137]
	v_mfma_f32_16x16x32_bf16 v[158:161], v[242:245], v[94:97], v[158:161]
	v_mfma_f32_16x16x32_bf16 v[174:177], v[246:249], v[94:97], v[174:177]
	s_waitcnt vmcnt(4)
	s_barrier
	ds_read_b128 v[218:221], v102 offset:16384
	ds_read_b128 v[222:225], v102 offset:18432
	ds_read_b128 v[226:229], v102 offset:20480
	ds_read_b128 v[230:233], v102 offset:22528
	ds_read_b128 v[66:69], v250 offset:49152
	ds_read_b128 v[70:73], v250 offset:51200
	ds_read_b128 v[74:77], v250 offset:53248
	ds_read_b128 v[78:81], v250 offset:55296
	ds_read_b128 v[234:237], v103 offset:16384
	ds_read_b128 v[238:241], v103 offset:18432
	ds_read_b128 v[242:245], v103 offset:20480
	ds_read_b128 v[246:249], v103 offset:22528
	ds_read_b128 v[82:85], v251 offset:49152
	ds_read_b128 v[86:89], v251 offset:51200
	ds_read_b128 v[90:93], v251 offset:53248
	ds_read_b128 v[94:97], v251 offset:55296
	s_add_u32 m0, s4, 0x0
	s_nop 0
	global_load_lds_dwordx4 v98, s[28:29]
	s_add_u32 m0, s4, 0x400
	s_nop 0
	global_load_lds_dwordx4 v99, s[28:29]
	s_add_u32 m0, s4, 0x800
	s_nop 0
	global_load_lds_dwordx4 v100, s[28:29]
	s_add_u32 m0, s4, 0xc00
	s_nop 0
	global_load_lds_dwordx4 v101, s[28:29]
	s_add_u32 m0, s4, 0xc000
	s_nop 0
	global_load_lds_dwordx4 v98, s[48:49]
	s_add_u32 m0, s4, 0xc400
	s_nop 0
	global_load_lds_dwordx4 v99, s[48:49]
	s_add_u32 m0, s4, 0xc800
	s_nop 0
	global_load_lds_dwordx4 v100, s[48:49]
	s_add_u32 m0, s4, 0xcc00
	s_nop 0
	global_load_lds_dwordx4 v101, s[48:49]
	s_waitcnt lgkmcnt(8)
	v_mfma_f32_16x16x32_bf16 v[62:65], v[218:221], v[66:69], v[62:65]
	v_mfma_f32_16x16x32_bf16 v[46:49], v[222:225], v[66:69], v[46:49]
	v_mfma_f32_16x16x32_bf16 v[30:33], v[226:229], v[66:69], v[30:33]
	v_mfma_f32_16x16x32_bf16 v[14:17], v[230:233], v[66:69], v[14:17]
	v_mfma_f32_16x16x32_bf16 v[58:61], v[218:221], v[70:73], v[58:61]
	v_mfma_f32_16x16x32_bf16 v[42:45], v[222:225], v[70:73], v[42:45]
	v_mfma_f32_16x16x32_bf16 v[26:29], v[226:229], v[70:73], v[26:29]
	v_mfma_f32_16x16x32_bf16 v[10:13], v[230:233], v[70:73], v[10:13]
	v_mfma_f32_16x16x32_bf16 v[54:57], v[218:221], v[74:77], v[54:57]
	v_mfma_f32_16x16x32_bf16 v[38:41], v[222:225], v[74:77], v[38:41]
	v_mfma_f32_16x16x32_bf16 v[22:25], v[226:229], v[74:77], v[22:25]
	v_mfma_f32_16x16x32_bf16 v[6:9], v[230:233], v[74:77], v[6:9]
	v_mfma_f32_16x16x32_bf16 v[50:53], v[218:221], v[78:81], v[50:53]
	v_mfma_f32_16x16x32_bf16 v[34:37], v[222:225], v[78:81], v[34:37]
	v_mfma_f32_16x16x32_bf16 v[18:21], v[226:229], v[78:81], v[18:21]
	v_mfma_f32_16x16x32_bf16 v[2:5], v[230:233], v[78:81], v[2:5]
	s_waitcnt lgkmcnt(0)
	v_mfma_f32_16x16x32_bf16 v[62:65], v[234:237], v[82:85], v[62:65]
	v_mfma_f32_16x16x32_bf16 v[46:49], v[238:241], v[82:85], v[46:49]
	v_mfma_f32_16x16x32_bf16 v[30:33], v[242:245], v[82:85], v[30:33]
	v_mfma_f32_16x16x32_bf16 v[14:17], v[246:249], v[82:85], v[14:17]
	v_mfma_f32_16x16x32_bf16 v[58:61], v[234:237], v[86:89], v[58:61]
	v_mfma_f32_16x16x32_bf16 v[42:45], v[238:241], v[86:89], v[42:45]
	v_mfma_f32_16x16x32_bf16 v[26:29], v[242:245], v[86:89], v[26:29]
	v_mfma_f32_16x16x32_bf16 v[10:13], v[246:249], v[86:89], v[10:13]
	v_mfma_f32_16x16x32_bf16 v[54:57], v[234:237], v[90:93], v[54:57]
	v_mfma_f32_16x16x32_bf16 v[38:41], v[238:241], v[90:93], v[38:41]
	v_mfma_f32_16x16x32_bf16 v[22:25], v[242:245], v[90:93], v[22:25]
	v_mfma_f32_16x16x32_bf16 v[6:9], v[246:249], v[90:93], v[6:9]
	v_mfma_f32_16x16x32_bf16 v[50:53], v[234:237], v[94:97], v[50:53]
	v_mfma_f32_16x16x32_bf16 v[34:37], v[238:241], v[94:97], v[34:37]
	v_mfma_f32_16x16x32_bf16 v[18:21], v[242:245], v[94:97], v[18:21]
	v_mfma_f32_16x16x32_bf16 v[2:5], v[246:249], v[94:97], v[2:5]
	s_waitcnt vmcnt(8)
	s_barrier
	ds_read_b128 v[218:221], v102 offset:32768
	ds_read_b128 v[222:225], v102 offset:34816
	ds_read_b128 v[226:229], v102 offset:36864
	ds_read_b128 v[230:233], v102 offset:38912
	ds_read_b128 v[234:237], v103 offset:32768
	ds_read_b128 v[238:241], v103 offset:34816
	ds_read_b128 v[242:245], v103 offset:36864
	ds_read_b128 v[246:249], v103 offset:38912
	s_add_u32 m0, s4, 0x4000
	s_nop 0
	global_load_lds_dwordx4 v98, s[6:7]
	s_add_u32 m0, s4, 0x4400
	s_nop 0
	global_load_lds_dwordx4 v99, s[6:7]
	s_add_u32 m0, s4, 0x4800
	s_nop 0
	global_load_lds_dwordx4 v100, s[6:7]
	s_add_u32 m0, s4, 0x4c00
	s_nop 0
	global_load_lds_dwordx4 v101, s[6:7]
	v_add_u32_e32 v98, 0x80, v98
	v_add_u32_e32 v99, 0x80, v99
	v_add_u32_e32 v100, 0x80, v100
	v_add_u32_e32 v101, 0x80, v101
	s_waitcnt lgkmcnt(4)
	v_mfma_f32_16x16x32_bf16 v[106:109], v[218:221], v[66:69], v[106:109]
	v_mfma_f32_16x16x32_bf16 v[122:125], v[222:225], v[66:69], v[122:125]
	v_mfma_f32_16x16x32_bf16 v[138:141], v[226:229], v[66:69], v[138:141]
	v_mfma_f32_16x16x32_bf16 v[162:165], v[230:233], v[66:69], v[162:165]
	v_mfma_f32_16x16x32_bf16 v[110:113], v[218:221], v[70:73], v[110:113]
	v_mfma_f32_16x16x32_bf16 v[126:129], v[222:225], v[70:73], v[126:129]
	v_mfma_f32_16x16x32_bf16 v[142:145], v[226:229], v[70:73], v[142:145]
	v_mfma_f32_16x16x32_bf16 v[166:169], v[230:233], v[70:73], v[166:169]
	v_mfma_f32_16x16x32_bf16 v[114:117], v[218:221], v[74:77], v[114:117]
	v_mfma_f32_16x16x32_bf16 v[130:133], v[222:225], v[74:77], v[130:133]
	v_mfma_f32_16x16x32_bf16 v[154:157], v[226:229], v[74:77], v[154:157]
	v_mfma_f32_16x16x32_bf16 v[170:173], v[230:233], v[74:77], v[170:173]
	v_mfma_f32_16x16x32_bf16 v[118:121], v[218:221], v[78:81], v[118:121]
	v_mfma_f32_16x16x32_bf16 v[134:137], v[222:225], v[78:81], v[134:137]
	v_mfma_f32_16x16x32_bf16 v[158:161], v[226:229], v[78:81], v[158:161]
	v_mfma_f32_16x16x32_bf16 v[174:177], v[230:233], v[78:81], v[174:177]
	s_waitcnt lgkmcnt(0)
	v_mfma_f32_16x16x32_bf16 v[106:109], v[234:237], v[82:85], v[106:109]
	v_mfma_f32_16x16x32_bf16 v[122:125], v[238:241], v[82:85], v[122:125]
	v_mfma_f32_16x16x32_bf16 v[138:141], v[242:245], v[82:85], v[138:141]
	v_mfma_f32_16x16x32_bf16 v[162:165], v[246:249], v[82:85], v[162:165]
	v_mfma_f32_16x16x32_bf16 v[110:113], v[234:237], v[86:89], v[110:113]
	v_mfma_f32_16x16x32_bf16 v[126:129], v[238:241], v[86:89], v[126:129]
	v_mfma_f32_16x16x32_bf16 v[142:145], v[242:245], v[86:89], v[142:145]
	v_mfma_f32_16x16x32_bf16 v[166:169], v[246:249], v[86:89], v[166:169]
	v_mfma_f32_16x16x32_bf16 v[114:117], v[234:237], v[90:93], v[114:117]
	v_mfma_f32_16x16x32_bf16 v[130:133], v[238:241], v[90:93], v[130:133]
	v_mfma_f32_16x16x32_bf16 v[154:157], v[242:245], v[90:93], v[154:157]
	v_mfma_f32_16x16x32_bf16 v[170:173], v[246:249], v[90:93], v[170:173]
	v_mfma_f32_16x16x32_bf16 v[118:121], v[234:237], v[94:97], v[118:121]
	v_mfma_f32_16x16x32_bf16 v[134:137], v[238:241], v[94:97], v[134:137]
	v_mfma_f32_16x16x32_bf16 v[158:161], v[242:245], v[94:97], v[158:161]
	v_mfma_f32_16x16x32_bf16 v[174:177], v[246:249], v[94:97], v[174:177]
	s_waitcnt vmcnt(4)
	s_barrier
	ds_read_b128 v[218:221], v102 offset:0
	ds_read_b128 v[222:225], v102 offset:2048
	ds_read_b128 v[226:229], v102 offset:4096
	ds_read_b128 v[230:233], v102 offset:6144
	ds_read_b128 v[66:69], v104 offset:49152
	ds_read_b128 v[70:73], v104 offset:51200
	ds_read_b128 v[74:77], v104 offset:53248
	ds_read_b128 v[78:81], v104 offset:55296
	ds_read_b128 v[234:237], v103 offset:0
	ds_read_b128 v[238:241], v103 offset:2048
	ds_read_b128 v[242:245], v103 offset:4096
	ds_read_b128 v[246:249], v103 offset:6144
	ds_read_b128 v[82:85], v105 offset:49152
	ds_read_b128 v[86:89], v105 offset:51200
	ds_read_b128 v[90:93], v105 offset:53248
	ds_read_b128 v[94:97], v105 offset:55296
	s_add_u32 m0, s4, 0x8000
	s_nop 0
	global_load_lds_dwordx4 v98, s[28:29]
	s_add_u32 m0, s4, 0x8400
	s_nop 0
	global_load_lds_dwordx4 v99, s[28:29]
	s_add_u32 m0, s4, 0x8800
	s_nop 0
	global_load_lds_dwordx4 v100, s[28:29]
	s_add_u32 m0, s4, 0x8c00
	s_nop 0
	global_load_lds_dwordx4 v101, s[28:29]
	s_add_u32 m0, s4, 0x10000
	s_nop 0
	global_load_lds_dwordx4 v98, s[48:49]
	s_add_u32 m0, s4, 0x10400
	s_nop 0
	global_load_lds_dwordx4 v99, s[48:49]
	s_add_u32 m0, s4, 0x10800
	s_nop 0
	global_load_lds_dwordx4 v100, s[48:49]
	s_add_u32 m0, s4, 0x10c00
	s_nop 0
	global_load_lds_dwordx4 v101, s[48:49]
	s_waitcnt lgkmcnt(8)
	v_mfma_f32_16x16x32_bf16 v[62:65], v[218:221], v[66:69], v[62:65]
	v_mfma_f32_16x16x32_bf16 v[46:49], v[222:225], v[66:69], v[46:49]
	v_mfma_f32_16x16x32_bf16 v[30:33], v[226:229], v[66:69], v[30:33]
	v_mfma_f32_16x16x32_bf16 v[14:17], v[230:233], v[66:69], v[14:17]
	v_mfma_f32_16x16x32_bf16 v[58:61], v[218:221], v[70:73], v[58:61]
	v_mfma_f32_16x16x32_bf16 v[42:45], v[222:225], v[70:73], v[42:45]
	v_mfma_f32_16x16x32_bf16 v[26:29], v[226:229], v[70:73], v[26:29]
	v_mfma_f32_16x16x32_bf16 v[10:13], v[230:233], v[70:73], v[10:13]
	v_mfma_f32_16x16x32_bf16 v[54:57], v[218:221], v[74:77], v[54:57]
	v_mfma_f32_16x16x32_bf16 v[38:41], v[222:225], v[74:77], v[38:41]
	v_mfma_f32_16x16x32_bf16 v[22:25], v[226:229], v[74:77], v[22:25]
	v_mfma_f32_16x16x32_bf16 v[6:9], v[230:233], v[74:77], v[6:9]
	v_mfma_f32_16x16x32_bf16 v[50:53], v[218:221], v[78:81], v[50:53]
	v_mfma_f32_16x16x32_bf16 v[34:37], v[222:225], v[78:81], v[34:37]
	v_mfma_f32_16x16x32_bf16 v[18:21], v[226:229], v[78:81], v[18:21]
	v_mfma_f32_16x16x32_bf16 v[2:5], v[230:233], v[78:81], v[2:5]
	s_waitcnt lgkmcnt(0)
	v_mfma_f32_16x16x32_bf16 v[62:65], v[234:237], v[82:85], v[62:65]
	v_mfma_f32_16x16x32_bf16 v[46:49], v[238:241], v[82:85], v[46:49]
	v_mfma_f32_16x16x32_bf16 v[30:33], v[242:245], v[82:85], v[30:33]
	v_mfma_f32_16x16x32_bf16 v[14:17], v[246:249], v[82:85], v[14:17]
	v_mfma_f32_16x16x32_bf16 v[58:61], v[234:237], v[86:89], v[58:61]
	v_mfma_f32_16x16x32_bf16 v[42:45], v[238:241], v[86:89], v[42:45]
	v_mfma_f32_16x16x32_bf16 v[26:29], v[242:245], v[86:89], v[26:29]
	v_mfma_f32_16x16x32_bf16 v[10:13], v[246:249], v[86:89], v[10:13]
	v_mfma_f32_16x16x32_bf16 v[54:57], v[234:237], v[90:93], v[54:57]
	v_mfma_f32_16x16x32_bf16 v[38:41], v[238:241], v[90:93], v[38:41]
	v_mfma_f32_16x16x32_bf16 v[22:25], v[242:245], v[90:93], v[22:25]
	v_mfma_f32_16x16x32_bf16 v[6:9], v[246:249], v[90:93], v[6:9]
	v_mfma_f32_16x16x32_bf16 v[50:53], v[234:237], v[94:97], v[50:53]
	v_mfma_f32_16x16x32_bf16 v[34:37], v[238:241], v[94:97], v[34:37]
	v_mfma_f32_16x16x32_bf16 v[18:21], v[242:245], v[94:97], v[18:21]
	v_mfma_f32_16x16x32_bf16 v[2:5], v[246:249], v[94:97], v[2:5]
	s_waitcnt vmcnt(8)
	s_barrier
	ds_read_b128 v[218:221], v102 offset:16384
	ds_read_b128 v[222:225], v102 offset:18432
	ds_read_b128 v[226:229], v102 offset:20480
	ds_read_b128 v[230:233], v102 offset:22528
	ds_read_b128 v[234:237], v103 offset:16384
	ds_read_b128 v[238:241], v103 offset:18432
	ds_read_b128 v[242:245], v103 offset:20480
	ds_read_b128 v[246:249], v103 offset:22528
	s_add_u32 m0, s4, 0x0
	s_nop 0
	global_load_lds_dwordx4 v98, s[6:7]
	s_add_u32 m0, s4, 0x400
	s_nop 0
	global_load_lds_dwordx4 v99, s[6:7]
	s_add_u32 m0, s4, 0x800
	s_nop 0
	global_load_lds_dwordx4 v100, s[6:7]
	s_add_u32 m0, s4, 0xc00
	s_nop 0
	global_load_lds_dwordx4 v101, s[6:7]
	v_add_u32_e32 v98, 0x80, v98
	v_add_u32_e32 v99, 0x80, v99
	v_add_u32_e32 v100, 0x80, v100
	v_add_u32_e32 v101, 0x80, v101
	s_waitcnt lgkmcnt(4)
	v_mfma_f32_16x16x32_bf16 v[106:109], v[218:221], v[66:69], v[106:109]
	v_mfma_f32_16x16x32_bf16 v[122:125], v[222:225], v[66:69], v[122:125]
	v_mfma_f32_16x16x32_bf16 v[138:141], v[226:229], v[66:69], v[138:141]
	v_mfma_f32_16x16x32_bf16 v[162:165], v[230:233], v[66:69], v[162:165]
	v_mfma_f32_16x16x32_bf16 v[110:113], v[218:221], v[70:73], v[110:113]
	v_mfma_f32_16x16x32_bf16 v[126:129], v[222:225], v[70:73], v[126:129]
	v_mfma_f32_16x16x32_bf16 v[142:145], v[226:229], v[70:73], v[142:145]
	v_mfma_f32_16x16x32_bf16 v[166:169], v[230:233], v[70:73], v[166:169]
	v_mfma_f32_16x16x32_bf16 v[114:117], v[218:221], v[74:77], v[114:117]
	v_mfma_f32_16x16x32_bf16 v[130:133], v[222:225], v[74:77], v[130:133]
	v_mfma_f32_16x16x32_bf16 v[154:157], v[226:229], v[74:77], v[154:157]
	v_mfma_f32_16x16x32_bf16 v[170:173], v[230:233], v[74:77], v[170:173]
	v_mfma_f32_16x16x32_bf16 v[118:121], v[218:221], v[78:81], v[118:121]
	v_mfma_f32_16x16x32_bf16 v[134:137], v[222:225], v[78:81], v[134:137]
	v_mfma_f32_16x16x32_bf16 v[158:161], v[226:229], v[78:81], v[158:161]
	v_mfma_f32_16x16x32_bf16 v[174:177], v[230:233], v[78:81], v[174:177]
	s_waitcnt lgkmcnt(0)
	v_mfma_f32_16x16x32_bf16 v[106:109], v[234:237], v[82:85], v[106:109]
	v_mfma_f32_16x16x32_bf16 v[122:125], v[238:241], v[82:85], v[122:125]
	v_mfma_f32_16x16x32_bf16 v[138:141], v[242:245], v[82:85], v[138:141]
	v_mfma_f32_16x16x32_bf16 v[162:165], v[246:249], v[82:85], v[162:165]
	v_mfma_f32_16x16x32_bf16 v[110:113], v[234:237], v[86:89], v[110:113]
	v_mfma_f32_16x16x32_bf16 v[126:129], v[238:241], v[86:89], v[126:129]
	v_mfma_f32_16x16x32_bf16 v[142:145], v[242:245], v[86:89], v[142:145]
	v_mfma_f32_16x16x32_bf16 v[166:169], v[246:249], v[86:89], v[166:169]
	v_mfma_f32_16x16x32_bf16 v[114:117], v[234:237], v[90:93], v[114:117]
	v_mfma_f32_16x16x32_bf16 v[130:133], v[238:241], v[90:93], v[130:133]
	v_mfma_f32_16x16x32_bf16 v[154:157], v[242:245], v[90:93], v[154:157]
	v_mfma_f32_16x16x32_bf16 v[170:173], v[246:249], v[90:93], v[170:173]
	v_mfma_f32_16x16x32_bf16 v[118:121], v[234:237], v[94:97], v[118:121]
	v_mfma_f32_16x16x32_bf16 v[134:137], v[238:241], v[94:97], v[134:137]
	v_mfma_f32_16x16x32_bf16 v[158:161], v[242:245], v[94:97], v[158:161]
	v_mfma_f32_16x16x32_bf16 v[174:177], v[246:249], v[94:97], v[174:177]
	s_waitcnt vmcnt(4)
	s_barrier
	ds_read_b128 v[218:221], v102 offset:32768
	ds_read_b128 v[222:225], v102 offset:34816
	ds_read_b128 v[226:229], v102 offset:36864
	ds_read_b128 v[230:233], v102 offset:38912
	ds_read_b128 v[66:69], v250 offset:49152
	ds_read_b128 v[70:73], v250 offset:51200
	ds_read_b128 v[74:77], v250 offset:53248
	ds_read_b128 v[78:81], v250 offset:55296
	ds_read_b128 v[234:237], v103 offset:32768
	ds_read_b128 v[238:241], v103 offset:34816
	ds_read_b128 v[242:245], v103 offset:36864
	ds_read_b128 v[246:249], v103 offset:38912
	ds_read_b128 v[82:85], v251 offset:49152
	ds_read_b128 v[86:89], v251 offset:51200
	ds_read_b128 v[90:93], v251 offset:53248
	ds_read_b128 v[94:97], v251 offset:55296
	s_add_u32 m0, s4, 0x4000
	s_nop 0
	global_load_lds_dwordx4 v98, s[28:29]
	s_add_u32 m0, s4, 0x4400
	s_nop 0
	global_load_lds_dwordx4 v99, s[28:29]
	s_add_u32 m0, s4, 0x4800
	s_nop 0
	global_load_lds_dwordx4 v100, s[28:29]
	s_add_u32 m0, s4, 0x4c00
	s_nop 0
	global_load_lds_dwordx4 v101, s[28:29]
	s_add_u32 m0, s4, 0xc000
	s_nop 0
	global_load_lds_dwordx4 v98, s[48:49]
	s_add_u32 m0, s4, 0xc400
	s_nop 0
	global_load_lds_dwordx4 v99, s[48:49]
	s_add_u32 m0, s4, 0xc800
	s_nop 0
	global_load_lds_dwordx4 v100, s[48:49]
	s_add_u32 m0, s4, 0xcc00
	s_nop 0
	global_load_lds_dwordx4 v101, s[48:49]
	s_waitcnt lgkmcnt(8)
	v_mfma_f32_16x16x32_bf16 v[62:65], v[218:221], v[66:69], v[62:65]
	v_mfma_f32_16x16x32_bf16 v[46:49], v[222:225], v[66:69], v[46:49]
	v_mfma_f32_16x16x32_bf16 v[30:33], v[226:229], v[66:69], v[30:33]
	v_mfma_f32_16x16x32_bf16 v[14:17], v[230:233], v[66:69], v[14:17]
	v_mfma_f32_16x16x32_bf16 v[58:61], v[218:221], v[70:73], v[58:61]
	v_mfma_f32_16x16x32_bf16 v[42:45], v[222:225], v[70:73], v[42:45]
	v_mfma_f32_16x16x32_bf16 v[26:29], v[226:229], v[70:73], v[26:29]
	v_mfma_f32_16x16x32_bf16 v[10:13], v[230:233], v[70:73], v[10:13]
	v_mfma_f32_16x16x32_bf16 v[54:57], v[218:221], v[74:77], v[54:57]
	v_mfma_f32_16x16x32_bf16 v[38:41], v[222:225], v[74:77], v[38:41]
	v_mfma_f32_16x16x32_bf16 v[22:25], v[226:229], v[74:77], v[22:25]
	v_mfma_f32_16x16x32_bf16 v[6:9], v[230:233], v[74:77], v[6:9]
	v_mfma_f32_16x16x32_bf16 v[50:53], v[218:221], v[78:81], v[50:53]
	v_mfma_f32_16x16x32_bf16 v[34:37], v[222:225], v[78:81], v[34:37]
	v_mfma_f32_16x16x32_bf16 v[18:21], v[226:229], v[78:81], v[18:21]
	v_mfma_f32_16x16x32_bf16 v[2:5], v[230:233], v[78:81], v[2:5]
	s_waitcnt lgkmcnt(0)
	v_mfma_f32_16x16x32_bf16 v[62:65], v[234:237], v[82:85], v[62:65]
	v_mfma_f32_16x16x32_bf16 v[46:49], v[238:241], v[82:85], v[46:49]
	v_mfma_f32_16x16x32_bf16 v[30:33], v[242:245], v[82:85], v[30:33]
	v_mfma_f32_16x16x32_bf16 v[14:17], v[246:249], v[82:85], v[14:17]
	v_mfma_f32_16x16x32_bf16 v[58:61], v[234:237], v[86:89], v[58:61]
	v_mfma_f32_16x16x32_bf16 v[42:45], v[238:241], v[86:89], v[42:45]
	v_mfma_f32_16x16x32_bf16 v[26:29], v[242:245], v[86:89], v[26:29]
	v_mfma_f32_16x16x32_bf16 v[10:13], v[246:249], v[86:89], v[10:13]
	v_mfma_f32_16x16x32_bf16 v[54:57], v[234:237], v[90:93], v[54:57]
	v_mfma_f32_16x16x32_bf16 v[38:41], v[238:241], v[90:93], v[38:41]
	v_mfma_f32_16x16x32_bf16 v[22:25], v[242:245], v[90:93], v[22:25]
	v_mfma_f32_16x16x32_bf16 v[6:9], v[246:249], v[90:93], v[6:9]
	v_mfma_f32_16x16x32_bf16 v[50:53], v[234:237], v[94:97], v[50:53]
	v_mfma_f32_16x16x32_bf16 v[34:37], v[238:241], v[94:97], v[34:37]
	v_mfma_f32_16x16x32_bf16 v[18:21], v[242:245], v[94:97], v[18:21]
	v_mfma_f32_16x16x32_bf16 v[2:5], v[246:249], v[94:97], v[2:5]
	s_waitcnt vmcnt(8)
	s_barrier
	ds_read_b128 v[218:221], v102 offset:0
	ds_read_b128 v[222:225], v102 offset:2048
	ds_read_b128 v[226:229], v102 offset:4096
	ds_read_b128 v[230:233], v102 offset:6144
	ds_read_b128 v[234:237], v103 offset:0
	ds_read_b128 v[238:241], v103 offset:2048
	ds_read_b128 v[242:245], v103 offset:4096
	ds_read_b128 v[246:249], v103 offset:6144
	s_add_u32 m0, s4, 0x8000
	s_nop 0
	global_load_lds_dwordx4 v98, s[6:7]
	s_add_u32 m0, s4, 0x8400
	s_nop 0
	global_load_lds_dwordx4 v99, s[6:7]
	s_add_u32 m0, s4, 0x8800
	s_nop 0
	global_load_lds_dwordx4 v100, s[6:7]
	s_add_u32 m0, s4, 0x8c00
	s_nop 0
	global_load_lds_dwordx4 v101, s[6:7]
	v_add_u32_e32 v98, 0x80, v98
	v_add_u32_e32 v99, 0x80, v99
	v_add_u32_e32 v100, 0x80, v100
	v_add_u32_e32 v101, 0x80, v101
	s_waitcnt lgkmcnt(4)
	v_mfma_f32_16x16x32_bf16 v[106:109], v[218:221], v[66:69], v[106:109]
	v_mfma_f32_16x16x32_bf16 v[122:125], v[222:225], v[66:69], v[122:125]
	v_mfma_f32_16x16x32_bf16 v[138:141], v[226:229], v[66:69], v[138:141]
	v_mfma_f32_16x16x32_bf16 v[162:165], v[230:233], v[66:69], v[162:165]
	v_mfma_f32_16x16x32_bf16 v[110:113], v[218:221], v[70:73], v[110:113]
	v_mfma_f32_16x16x32_bf16 v[126:129], v[222:225], v[70:73], v[126:129]
	v_mfma_f32_16x16x32_bf16 v[142:145], v[226:229], v[70:73], v[142:145]
	v_mfma_f32_16x16x32_bf16 v[166:169], v[230:233], v[70:73], v[166:169]
	v_mfma_f32_16x16x32_bf16 v[114:117], v[218:221], v[74:77], v[114:117]
	v_mfma_f32_16x16x32_bf16 v[130:133], v[222:225], v[74:77], v[130:133]
	v_mfma_f32_16x16x32_bf16 v[154:157], v[226:229], v[74:77], v[154:157]
	v_mfma_f32_16x16x32_bf16 v[170:173], v[230:233], v[74:77], v[170:173]
	v_mfma_f32_16x16x32_bf16 v[118:121], v[218:221], v[78:81], v[118:121]
	v_mfma_f32_16x16x32_bf16 v[134:137], v[222:225], v[78:81], v[134:137]
	v_mfma_f32_16x16x32_bf16 v[158:161], v[226:229], v[78:81], v[158:161]
	v_mfma_f32_16x16x32_bf16 v[174:177], v[230:233], v[78:81], v[174:177]
	s_waitcnt lgkmcnt(0)
	v_mfma_f32_16x16x32_bf16 v[106:109], v[234:237], v[82:85], v[106:109]
	v_mfma_f32_16x16x32_bf16 v[122:125], v[238:241], v[82:85], v[122:125]
	v_mfma_f32_16x16x32_bf16 v[138:141], v[242:245], v[82:85], v[138:141]
	v_mfma_f32_16x16x32_bf16 v[162:165], v[246:249], v[82:85], v[162:165]
	v_mfma_f32_16x16x32_bf16 v[110:113], v[234:237], v[86:89], v[110:113]
	v_mfma_f32_16x16x32_bf16 v[126:129], v[238:241], v[86:89], v[126:129]
	v_mfma_f32_16x16x32_bf16 v[142:145], v[242:245], v[86:89], v[142:145]
	v_mfma_f32_16x16x32_bf16 v[166:169], v[246:249], v[86:89], v[166:169]
	v_mfma_f32_16x16x32_bf16 v[114:117], v[234:237], v[90:93], v[114:117]
	v_mfma_f32_16x16x32_bf16 v[130:133], v[238:241], v[90:93], v[130:133]
	v_mfma_f32_16x16x32_bf16 v[154:157], v[242:245], v[90:93], v[154:157]
	v_mfma_f32_16x16x32_bf16 v[170:173], v[246:249], v[90:93], v[170:173]
	v_mfma_f32_16x16x32_bf16 v[118:121], v[234:237], v[94:97], v[118:121]
	v_mfma_f32_16x16x32_bf16 v[134:137], v[238:241], v[94:97], v[134:137]
	v_mfma_f32_16x16x32_bf16 v[158:161], v[242:245], v[94:97], v[158:161]
	v_mfma_f32_16x16x32_bf16 v[174:177], v[246:249], v[94:97], v[174:177]
	s_waitcnt vmcnt(4)
	s_barrier
	ds_read_b128 v[218:221], v102 offset:16384
	ds_read_b128 v[222:225], v102 offset:18432
	ds_read_b128 v[226:229], v102 offset:20480
	ds_read_b128 v[230:233], v102 offset:22528
	ds_read_b128 v[66:69], v104 offset:49152
	ds_read_b128 v[70:73], v104 offset:51200
	ds_read_b128 v[74:77], v104 offset:53248
	ds_read_b128 v[78:81], v104 offset:55296
	ds_read_b128 v[234:237], v103 offset:16384
	ds_read_b128 v[238:241], v103 offset:18432
	ds_read_b128 v[242:245], v103 offset:20480
	ds_read_b128 v[246:249], v103 offset:22528
	ds_read_b128 v[82:85], v105 offset:49152
	ds_read_b128 v[86:89], v105 offset:51200
	ds_read_b128 v[90:93], v105 offset:53248
	ds_read_b128 v[94:97], v105 offset:55296
	s_add_u32 m0, s4, 0x0
	s_nop 0
	global_load_lds_dwordx4 v98, s[28:29]
	s_add_u32 m0, s4, 0x400
	s_nop 0
	global_load_lds_dwordx4 v99, s[28:29]
	s_add_u32 m0, s4, 0x800
	s_nop 0
	global_load_lds_dwordx4 v100, s[28:29]
	s_add_u32 m0, s4, 0xc00
	s_nop 0
	global_load_lds_dwordx4 v101, s[28:29]
	s_add_u32 m0, s4, 0x10000
	s_nop 0
	global_load_lds_dwordx4 v98, s[48:49]
	s_add_u32 m0, s4, 0x10400
	s_nop 0
	global_load_lds_dwordx4 v99, s[48:49]
	s_add_u32 m0, s4, 0x10800
	s_nop 0
	global_load_lds_dwordx4 v100, s[48:49]
	s_add_u32 m0, s4, 0x10c00
	s_nop 0
	global_load_lds_dwordx4 v101, s[48:49]
	s_waitcnt lgkmcnt(8)
	v_mfma_f32_16x16x32_bf16 v[62:65], v[218:221], v[66:69], v[62:65]
	v_mfma_f32_16x16x32_bf16 v[46:49], v[222:225], v[66:69], v[46:49]
	v_mfma_f32_16x16x32_bf16 v[30:33], v[226:229], v[66:69], v[30:33]
	v_mfma_f32_16x16x32_bf16 v[14:17], v[230:233], v[66:69], v[14:17]
	v_mfma_f32_16x16x32_bf16 v[58:61], v[218:221], v[70:73], v[58:61]
	v_mfma_f32_16x16x32_bf16 v[42:45], v[222:225], v[70:73], v[42:45]
	v_mfma_f32_16x16x32_bf16 v[26:29], v[226:229], v[70:73], v[26:29]
	v_mfma_f32_16x16x32_bf16 v[10:13], v[230:233], v[70:73], v[10:13]
	v_mfma_f32_16x16x32_bf16 v[54:57], v[218:221], v[74:77], v[54:57]
	v_mfma_f32_16x16x32_bf16 v[38:41], v[222:225], v[74:77], v[38:41]
	v_mfma_f32_16x16x32_bf16 v[22:25], v[226:229], v[74:77], v[22:25]
	v_mfma_f32_16x16x32_bf16 v[6:9], v[230:233], v[74:77], v[6:9]
	v_mfma_f32_16x16x32_bf16 v[50:53], v[218:221], v[78:81], v[50:53]
	v_mfma_f32_16x16x32_bf16 v[34:37], v[222:225], v[78:81], v[34:37]
	v_mfma_f32_16x16x32_bf16 v[18:21], v[226:229], v[78:81], v[18:21]
	v_mfma_f32_16x16x32_bf16 v[2:5], v[230:233], v[78:81], v[2:5]
	s_waitcnt lgkmcnt(0)
	v_mfma_f32_16x16x32_bf16 v[62:65], v[234:237], v[82:85], v[62:65]
	v_mfma_f32_16x16x32_bf16 v[46:49], v[238:241], v[82:85], v[46:49]
	v_mfma_f32_16x16x32_bf16 v[30:33], v[242:245], v[82:85], v[30:33]
	v_mfma_f32_16x16x32_bf16 v[14:17], v[246:249], v[82:85], v[14:17]
	v_mfma_f32_16x16x32_bf16 v[58:61], v[234:237], v[86:89], v[58:61]
	v_mfma_f32_16x16x32_bf16 v[42:45], v[238:241], v[86:89], v[42:45]
	v_mfma_f32_16x16x32_bf16 v[26:29], v[242:245], v[86:89], v[26:29]
	v_mfma_f32_16x16x32_bf16 v[10:13], v[246:249], v[86:89], v[10:13]
	v_mfma_f32_16x16x32_bf16 v[54:57], v[234:237], v[90:93], v[54:57]
	v_mfma_f32_16x16x32_bf16 v[38:41], v[238:241], v[90:93], v[38:41]
	v_mfma_f32_16x16x32_bf16 v[22:25], v[242:245], v[90:93], v[22:25]
	v_mfma_f32_16x16x32_bf16 v[6:9], v[246:249], v[90:93], v[6:9]
	v_mfma_f32_16x16x32_bf16 v[50:53], v[234:237], v[94:97], v[50:53]
	v_mfma_f32_16x16x32_bf16 v[34:37], v[238:241], v[94:97], v[34:37]
	v_mfma_f32_16x16x32_bf16 v[18:21], v[242:245], v[94:97], v[18:21]
	v_mfma_f32_16x16x32_bf16 v[2:5], v[246:249], v[94:97], v[2:5]
	s_waitcnt vmcnt(8)
	s_barrier
	ds_read_b128 v[218:221], v102 offset:32768
	ds_read_b128 v[222:225], v102 offset:34816
	ds_read_b128 v[226:229], v102 offset:36864
	ds_read_b128 v[230:233], v102 offset:38912
	ds_read_b128 v[234:237], v103 offset:32768
	ds_read_b128 v[238:241], v103 offset:34816
	ds_read_b128 v[242:245], v103 offset:36864
	ds_read_b128 v[246:249], v103 offset:38912
	s_add_u32 m0, s4, 0x4000
	s_nop 0
	global_load_lds_dwordx4 v98, s[6:7]
	s_add_u32 m0, s4, 0x4400
	s_nop 0
	global_load_lds_dwordx4 v99, s[6:7]
	s_add_u32 m0, s4, 0x4800
	s_nop 0
	global_load_lds_dwordx4 v100, s[6:7]
	s_add_u32 m0, s4, 0x4c00
	s_nop 0
	global_load_lds_dwordx4 v101, s[6:7]
	v_add_u32_e32 v98, 0x80, v98
	v_add_u32_e32 v99, 0x80, v99
	v_add_u32_e32 v100, 0x80, v100
	v_add_u32_e32 v101, 0x80, v101
	s_waitcnt lgkmcnt(4)
	v_mfma_f32_16x16x32_bf16 v[106:109], v[218:221], v[66:69], v[106:109]
	v_mfma_f32_16x16x32_bf16 v[122:125], v[222:225], v[66:69], v[122:125]
	v_mfma_f32_16x16x32_bf16 v[138:141], v[226:229], v[66:69], v[138:141]
	v_mfma_f32_16x16x32_bf16 v[162:165], v[230:233], v[66:69], v[162:165]
	v_mfma_f32_16x16x32_bf16 v[110:113], v[218:221], v[70:73], v[110:113]
	v_mfma_f32_16x16x32_bf16 v[126:129], v[222:225], v[70:73], v[126:129]
	v_mfma_f32_16x16x32_bf16 v[142:145], v[226:229], v[70:73], v[142:145]
	v_mfma_f32_16x16x32_bf16 v[166:169], v[230:233], v[70:73], v[166:169]
	v_mfma_f32_16x16x32_bf16 v[114:117], v[218:221], v[74:77], v[114:117]
	v_mfma_f32_16x16x32_bf16 v[130:133], v[222:225], v[74:77], v[130:133]
	v_mfma_f32_16x16x32_bf16 v[154:157], v[226:229], v[74:77], v[154:157]
	v_mfma_f32_16x16x32_bf16 v[170:173], v[230:233], v[74:77], v[170:173]
	v_mfma_f32_16x16x32_bf16 v[118:121], v[218:221], v[78:81], v[118:121]
	v_mfma_f32_16x16x32_bf16 v[134:137], v[222:225], v[78:81], v[134:137]
	v_mfma_f32_16x16x32_bf16 v[158:161], v[226:229], v[78:81], v[158:161]
	v_mfma_f32_16x16x32_bf16 v[174:177], v[230:233], v[78:81], v[174:177]
	s_waitcnt lgkmcnt(0)
	v_mfma_f32_16x16x32_bf16 v[106:109], v[234:237], v[82:85], v[106:109]
	v_mfma_f32_16x16x32_bf16 v[122:125], v[238:241], v[82:85], v[122:125]
	v_mfma_f32_16x16x32_bf16 v[138:141], v[242:245], v[82:85], v[138:141]
	v_mfma_f32_16x16x32_bf16 v[162:165], v[246:249], v[82:85], v[162:165]
	v_mfma_f32_16x16x32_bf16 v[110:113], v[234:237], v[86:89], v[110:113]
	v_mfma_f32_16x16x32_bf16 v[126:129], v[238:241], v[86:89], v[126:129]
	v_mfma_f32_16x16x32_bf16 v[142:145], v[242:245], v[86:89], v[142:145]
	v_mfma_f32_16x16x32_bf16 v[166:169], v[246:249], v[86:89], v[166:169]
	v_mfma_f32_16x16x32_bf16 v[114:117], v[234:237], v[90:93], v[114:117]
	v_mfma_f32_16x16x32_bf16 v[130:133], v[238:241], v[90:93], v[130:133]
	v_mfma_f32_16x16x32_bf16 v[154:157], v[242:245], v[90:93], v[154:157]
	v_mfma_f32_16x16x32_bf16 v[170:173], v[246:249], v[90:93], v[170:173]
	v_mfma_f32_16x16x32_bf16 v[118:121], v[234:237], v[94:97], v[118:121]
	v_mfma_f32_16x16x32_bf16 v[134:137], v[238:241], v[94:97], v[134:137]
	v_mfma_f32_16x16x32_bf16 v[158:161], v[242:245], v[94:97], v[158:161]
	v_mfma_f32_16x16x32_bf16 v[174:177], v[246:249], v[94:97], v[174:177]
	s_waitcnt vmcnt(4)
	s_barrier
	ds_read_b128 v[218:221], v102 offset:0
	ds_read_b128 v[222:225], v102 offset:2048
	ds_read_b128 v[226:229], v102 offset:4096
	ds_read_b128 v[230:233], v102 offset:6144
	ds_read_b128 v[66:69], v250 offset:49152
	ds_read_b128 v[70:73], v250 offset:51200
	ds_read_b128 v[74:77], v250 offset:53248
	ds_read_b128 v[78:81], v250 offset:55296
	ds_read_b128 v[234:237], v103 offset:0
	ds_read_b128 v[238:241], v103 offset:2048
	ds_read_b128 v[242:245], v103 offset:4096
	ds_read_b128 v[246:249], v103 offset:6144
	ds_read_b128 v[82:85], v251 offset:49152
	ds_read_b128 v[86:89], v251 offset:51200
	ds_read_b128 v[90:93], v251 offset:53248
	ds_read_b128 v[94:97], v251 offset:55296
	s_waitcnt lgkmcnt(8)
	v_mfma_f32_16x16x32_bf16 v[62:65], v[218:221], v[66:69], v[62:65]
	v_mfma_f32_16x16x32_bf16 v[46:49], v[222:225], v[66:69], v[46:49]
	v_mfma_f32_16x16x32_bf16 v[30:33], v[226:229], v[66:69], v[30:33]
	v_mfma_f32_16x16x32_bf16 v[14:17], v[230:233], v[66:69], v[14:17]
	v_mfma_f32_16x16x32_bf16 v[58:61], v[218:221], v[70:73], v[58:61]
	v_mfma_f32_16x16x32_bf16 v[42:45], v[222:225], v[70:73], v[42:45]
	v_mfma_f32_16x16x32_bf16 v[26:29], v[226:229], v[70:73], v[26:29]
	v_mfma_f32_16x16x32_bf16 v[10:13], v[230:233], v[70:73], v[10:13]
	v_mfma_f32_16x16x32_bf16 v[54:57], v[218:221], v[74:77], v[54:57]
	v_mfma_f32_16x16x32_bf16 v[38:41], v[222:225], v[74:77], v[38:41]
	v_mfma_f32_16x16x32_bf16 v[22:25], v[226:229], v[74:77], v[22:25]
	v_mfma_f32_16x16x32_bf16 v[6:9], v[230:233], v[74:77], v[6:9]
	v_mfma_f32_16x16x32_bf16 v[50:53], v[218:221], v[78:81], v[50:53]
	v_mfma_f32_16x16x32_bf16 v[34:37], v[222:225], v[78:81], v[34:37]
	v_mfma_f32_16x16x32_bf16 v[18:21], v[226:229], v[78:81], v[18:21]
	v_mfma_f32_16x16x32_bf16 v[2:5], v[230:233], v[78:81], v[2:5]
	s_waitcnt lgkmcnt(0)
	v_mfma_f32_16x16x32_bf16 v[62:65], v[234:237], v[82:85], v[62:65]
	v_mfma_f32_16x16x32_bf16 v[46:49], v[238:241], v[82:85], v[46:49]
	v_mfma_f32_16x16x32_bf16 v[30:33], v[242:245], v[82:85], v[30:33]
	v_mfma_f32_16x16x32_bf16 v[14:17], v[246:249], v[82:85], v[14:17]
	v_mfma_f32_16x16x32_bf16 v[58:61], v[234:237], v[86:89], v[58:61]
	v_mfma_f32_16x16x32_bf16 v[42:45], v[238:241], v[86:89], v[42:45]
	v_mfma_f32_16x16x32_bf16 v[26:29], v[242:245], v[86:89], v[26:29]
	v_mfma_f32_16x16x32_bf16 v[10:13], v[246:249], v[86:89], v[10:13]
	v_mfma_f32_16x16x32_bf16 v[54:57], v[234:237], v[90:93], v[54:57]
	v_mfma_f32_16x16x32_bf16 v[38:41], v[238:241], v[90:93], v[38:41]
	v_mfma_f32_16x16x32_bf16 v[22:25], v[242:245], v[90:93], v[22:25]
	v_mfma_f32_16x16x32_bf16 v[6:9], v[246:249], v[90:93], v[6:9]
	v_mfma_f32_16x16x32_bf16 v[50:53], v[234:237], v[94:97], v[50:53]
	v_mfma_f32_16x16x32_bf16 v[34:37], v[238:241], v[94:97], v[34:37]
	v_mfma_f32_16x16x32_bf16 v[18:21], v[242:245], v[94:97], v[18:21]
	v_mfma_f32_16x16x32_bf16 v[2:5], v[246:249], v[94:97], v[2:5]
	s_waitcnt vmcnt(0)
	s_barrier
	ds_read_b128 v[218:221], v102 offset:16384
	ds_read_b128 v[222:225], v102 offset:18432
	ds_read_b128 v[226:229], v102 offset:20480
	ds_read_b128 v[230:233], v102 offset:22528
	ds_read_b128 v[234:237], v103 offset:16384
	ds_read_b128 v[238:241], v103 offset:18432
	ds_read_b128 v[242:245], v103 offset:20480
	ds_read_b128 v[246:249], v103 offset:22528
	s_waitcnt lgkmcnt(4)
	v_mfma_f32_16x16x32_bf16 v[106:109], v[218:221], v[66:69], v[106:109]
	v_mfma_f32_16x16x32_bf16 v[122:125], v[222:225], v[66:69], v[122:125]
	v_mfma_f32_16x16x32_bf16 v[138:141], v[226:229], v[66:69], v[138:141]
	v_mfma_f32_16x16x32_bf16 v[162:165], v[230:233], v[66:69], v[162:165]
	v_mfma_f32_16x16x32_bf16 v[110:113], v[218:221], v[70:73], v[110:113]
	v_mfma_f32_16x16x32_bf16 v[126:129], v[222:225], v[70:73], v[126:129]
	v_mfma_f32_16x16x32_bf16 v[142:145], v[226:229], v[70:73], v[142:145]
	v_mfma_f32_16x16x32_bf16 v[166:169], v[230:233], v[70:73], v[166:169]
	v_mfma_f32_16x16x32_bf16 v[114:117], v[218:221], v[74:77], v[114:117]
	v_mfma_f32_16x16x32_bf16 v[130:133], v[222:225], v[74:77], v[130:133]
	v_mfma_f32_16x16x32_bf16 v[154:157], v[226:229], v[74:77], v[154:157]
	v_mfma_f32_16x16x32_bf16 v[170:173], v[230:233], v[74:77], v[170:173]
	v_mfma_f32_16x16x32_bf16 v[118:121], v[218:221], v[78:81], v[118:121]
	v_mfma_f32_16x16x32_bf16 v[134:137], v[222:225], v[78:81], v[134:137]
	v_mfma_f32_16x16x32_bf16 v[158:161], v[226:229], v[78:81], v[158:161]
	v_mfma_f32_16x16x32_bf16 v[174:177], v[230:233], v[78:81], v[174:177]
	s_waitcnt lgkmcnt(0)
	v_mfma_f32_16x16x32_bf16 v[106:109], v[234:237], v[82:85], v[106:109]
	v_mfma_f32_16x16x32_bf16 v[122:125], v[238:241], v[82:85], v[122:125]
	v_mfma_f32_16x16x32_bf16 v[138:141], v[242:245], v[82:85], v[138:141]
	v_mfma_f32_16x16x32_bf16 v[162:165], v[246:249], v[82:85], v[162:165]
	v_mfma_f32_16x16x32_bf16 v[110:113], v[234:237], v[86:89], v[110:113]
	v_mfma_f32_16x16x32_bf16 v[126:129], v[238:241], v[86:89], v[126:129]
	v_mfma_f32_16x16x32_bf16 v[142:145], v[242:245], v[86:89], v[142:145]
	v_mfma_f32_16x16x32_bf16 v[166:169], v[246:249], v[86:89], v[166:169]
	v_mfma_f32_16x16x32_bf16 v[114:117], v[234:237], v[90:93], v[114:117]
	v_mfma_f32_16x16x32_bf16 v[130:133], v[238:241], v[90:93], v[130:133]
	v_mfma_f32_16x16x32_bf16 v[154:157], v[242:245], v[90:93], v[154:157]
	v_mfma_f32_16x16x32_bf16 v[170:173], v[246:249], v[90:93], v[170:173]
	v_mfma_f32_16x16x32_bf16 v[118:121], v[234:237], v[94:97], v[118:121]
	v_mfma_f32_16x16x32_bf16 v[134:137], v[238:241], v[94:97], v[134:137]
	v_mfma_f32_16x16x32_bf16 v[158:161], v[242:245], v[94:97], v[158:161]
	v_mfma_f32_16x16x32_bf16 v[174:177], v[246:249], v[94:97], v[174:177]
	s_nop 7
	s_barrier
	v_mov_b32_e32 v0, 0x13ff0
	v_mov_b32_e32 v218, s5
	v_mov_b32_e32 v219, s101
	ds_write_b64 v0, v[218:219]
	s_branch .LBB0_260
.Lpk_tt_unpark:
	s_barrier
	v_mov_b32_e32 v62, v106
	v_mov_b32_e32 v63, v107
	v_mov_b32_e32 v64, v108
	v_mov_b32_e32 v65, v109
	v_mov_b32_e32 v58, v110
	v_mov_b32_e32 v59, v111
	v_mov_b32_e32 v60, v112
	v_mov_b32_e32 v61, v113
	v_mov_b32_e32 v54, v114
	v_mov_b32_e32 v55, v115
	v_mov_b32_e32 v56, v116
	v_mov_b32_e32 v57, v117
	v_mov_b32_e32 v50, v118
	v_mov_b32_e32 v51, v119
	v_mov_b32_e32 v52, v120
	v_mov_b32_e32 v53, v121
	v_mov_b32_e32 v46, v122
	v_mov_b32_e32 v47, v123
	v_mov_b32_e32 v48, v124
	v_mov_b32_e32 v49, v125
	v_mov_b32_e32 v42, v126
	v_mov_b32_e32 v43, v127
	v_mov_b32_e32 v44, v128
	v_mov_b32_e32 v45, v129
	v_mov_b32_e32 v38, v130
	v_mov_b32_e32 v39, v131
	v_mov_b32_e32 v40, v132
	v_mov_b32_e32 v41, v133
	v_mov_b32_e32 v34, v134
	v_mov_b32_e32 v35, v135
	v_mov_b32_e32 v36, v136
	v_mov_b32_e32 v37, v137
	v_mov_b32_e32 v30, v138
	v_mov_b32_e32 v31, v139
	v_mov_b32_e32 v32, v140
	v_mov_b32_e32 v33, v141
	v_mov_b32_e32 v26, v142
	v_mov_b32_e32 v27, v143
	v_mov_b32_e32 v28, v144
	v_mov_b32_e32 v29, v145
	v_mov_b32_e32 v22, v154
	v_mov_b32_e32 v23, v155
	v_mov_b32_e32 v24, v156
	v_mov_b32_e32 v25, v157
	v_mov_b32_e32 v18, v158
	v_mov_b32_e32 v19, v159
	v_mov_b32_e32 v20, v160
	v_mov_b32_e32 v21, v161
	v_mov_b32_e32 v14, v162
	v_mov_b32_e32 v15, v163
	v_mov_b32_e32 v16, v164
	v_mov_b32_e32 v17, v165
	v_mov_b32_e32 v10, v166
	v_mov_b32_e32 v11, v167
	v_mov_b32_e32 v12, v168
	v_mov_b32_e32 v13, v169
	v_mov_b32_e32 v6, v170
	v_mov_b32_e32 v7, v171
	v_mov_b32_e32 v8, v172
	v_mov_b32_e32 v9, v173
	v_mov_b32_e32 v2, v174
	v_mov_b32_e32 v3, v175
	v_mov_b32_e32 v4, v176
	v_mov_b32_e32 v5, v177
	s_branch .LBB0_260

	.amdhsa_kernel _Z4mega6Paramsii
		.amdhsa_group_segment_fixed_size 81920
		.amdhsa_private_segment_fixed_size 0
		.amdhsa_kernarg_size 504
		.amdhsa_user_sgpr_count 2
		.amdhsa_user_sgpr_dispatch_ptr 0
		.amdhsa_user_sgpr_queue_ptr 0
		.amdhsa_user_sgpr_kernarg_segment_ptr 1
		.amdhsa_user_sgpr_dispatch_id 0
		.amdhsa_user_sgpr_kernarg_preload_length 0
		.amdhsa_user_sgpr_kernarg_preload_offset 0
		.amdhsa_user_sgpr_private_segment_size 0
		.amdhsa_uses_dynamic_stack 0
		.amdhsa_enable_private_segment 0
		.amdhsa_system_sgpr_workgroup_id_x 1
		.amdhsa_system_sgpr_workgroup_id_y 0
		.amdhsa_system_sgpr_workgroup_id_z 0
		.amdhsa_system_sgpr_workgroup_info 0
		.amdhsa_system_vgpr_workitem_id 2
		.amdhsa_next_free_vgpr 256
		.amdhsa_next_free_sgpr 102
		.amdhsa_accum_offset 256
		.amdhsa_reserve_vcc 1
		.amdhsa_float_round_mode_32 0
		.amdhsa_float_round_mode_16_64 0
		.amdhsa_float_denorm_mode_32 3
		.amdhsa_float_denorm_mode_16_64 3
		.amdhsa_dx10_clamp 1
		.amdhsa_ieee_mode 1
		.amdhsa_fp16_overflow 0
		.amdhsa_tg_split 0
		.amdhsa_exception_fp_ieee_invalid_op 0
		.amdhsa_exception_fp_denorm_src 0
		.amdhsa_exception_fp_ieee_div_zero 0
		.amdhsa_exception_fp_ieee_overflow 0
		.amdhsa_exception_fp_ieee_underflow 0
		.amdhsa_exception_fp_ieee_inexact 0
		.amdhsa_exception_int_div_zero 0
	.end_amdhsa_kernel

amdhsa.kernels:
  - .agpr_count:     0
    .args:
      - .offset:         0
        .size:           240
        .value_kind:     by_value
      - .offset:         240
        .size:           4
        .value_kind:     by_value
      - .offset:         244
        .size:           4
        .value_kind:     by_value
      - .offset:         248
        .size:           4
        .value_kind:     hidden_block_count_x
      - .offset:         252
        .size:           4
        .value_kind:     hidden_block_count_y
      - .offset:         256
        .size:           4
        .value_kind:     hidden_block_count_z
      - .offset:         260
        .size:           2
        .value_kind:     hidden_group_size_x
      - .offset:         262
        .size:           2
        .value_kind:     hidden_group_size_y
      - .offset:         264
        .size:           2
        .value_kind:     hidden_group_size_z
      - .offset:         266
        .size:           2
        .value_kind:     hidden_remainder_x
      - .offset:         268
        .size:           2
        .value_kind:     hidden_remainder_y
      - .offset:         270
        .size:           2
        .value_kind:     hidden_remainder_z
      - .offset:         288
        .size:           8
        .value_kind:     hidden_global_offset_x
      - .offset:         296
        .size:           8
        .value_kind:     hidden_global_offset_y
      - .offset:         304
        .size:           8
        .value_kind:     hidden_global_offset_z
      - .offset:         312
        .size:           2
        .value_kind:     hidden_grid_dims
      - .offset:         336
        .size:           8
        .value_kind:     hidden_multigrid_sync_arg
    .group_segment_fixed_size: 81920
    .kernarg_segment_align: 8
    .kernarg_segment_size: 504
    .language:       OpenCL C
    .language_version:
      - 2
      - 0
    .max_flat_workgroup_size: 256
    .name:           _Z4mega6Paramsii
    .private_segment_fixed_size: 0
    .sgpr_count:     108
    .sgpr_spill_count: 235
    .symbol:         _Z4mega6Paramsii.kd
    .uniform_work_group_size: 1
    .uses_dynamic_stack: false
    .vgpr_count:     256
    .vgpr_spill_count: 0
    .wavefront_size: 64
